# stack on v3: GEMM2 residual wait behind staging, retention-loop vmcnt(0) removed, GEMM2 epilogue DPP row sums, flat to global loads
# speedup vs baseline: 1.0056x; 1.0041x over previous
.LBB0_18:
	s_and_saveexec_b64 s[8:9], s[38:39]
	s_cbranch_execz .LBB0_31
	s_and_b32 s0, s37, 31
	s_lshl_b32 s0, s0, 4
	s_add_u32 s12, s2, s0
	s_addc_u32 s13, s3, 0
	v_mov_b64_e32 v[6:7], s[12:13]
	global_load_dword v6, v[6:7], off sc1
	s_waitcnt vmcnt(0) lgkmcnt(0)
	v_cmp_gt_u32_e64 s[40:41], 8, v6
	s_and_saveexec_b64 s[10:11], s[40:41]
	s_cbranch_execz .LBB0_30
	s_mov_b32 s0, 1
	s_mov_b64 s[14:15], 0
	s_branch .LBB0_22

.LBB0_22:
	s_and_b32 s28, s0, 0xff
	s_mov_b64 s[26:27], -1
	s_cmp_lg_u32 s28, 0
	s_mov_b64 s[28:29], -1
	s_sleep 1
	s_cbranch_scc1 .LBB0_26
	v_mov_b64_e32 v[6:7], s[6:7]
	global_load_dword v6, v[6:7], off sc1
	s_mov_b64 s[28:29], 0
	s_mov_b64 s[34:35], -1
	s_waitcnt vmcnt(0) lgkmcnt(0)
	v_cmp_eq_u32_e64 s[40:41], 0, v6
	s_and_saveexec_b64 s[42:43], s[40:41]
	s_cmp_lt_u32 s0, 0x100001
	s_cselect_b64 s[28:29], -1, 0
	s_xor_b64 s[34:35], exec, -1
	s_and_b64 s[28:29], s[28:29], exec
	s_or_b64 exec, exec, s[42:43]
.LBB0_26:
	s_andn2_b64 s[18:19], s[18:19], exec
	s_and_b64 s[34:35], s[34:35], exec
	s_or_b64 s[18:19], s[18:19], s[34:35]
	s_and_saveexec_b64 s[34:35], s[28:29]
	s_cbranch_execz .LBB0_21
	v_mov_b64_e32 v[6:7], s[12:13]
	global_load_dword v6, v[6:7], off sc1
	s_add_i32 s0, s0, 1
	s_or_b64 s[18:19], s[18:19], exec
	s_waitcnt vmcnt(0) lgkmcnt(0)
	v_cmp_lt_u32_e64 s[40:41], 7, v6
	s_orn2_b64 s[26:27], s[40:41], exec
	s_branch .LBB0_21
.LBB0_28:
	s_or_b64 exec, exec, s[14:15]
	s_xor_b64 s[12:13], s[16:17], -1
	s_and_saveexec_b64 s[14:15], s[12:13]
	s_xor_b64 s[14:15], exec, s[14:15]
	s_cbranch_execz .LBB0_30
	v_mov_b64_e32 v[6:7], s[6:7]
	global_atomic_add v[6:7], v181, off

.LBB0_32:
	s_or_b64 exec, exec, s[10:11]
	s_waitcnt vmcnt(0) lgkmcnt(0)
	ds_bpermute_b32 v13, v219, v12
	s_mov_b32 s0, 0x9200000
	s_add_u32 s10, s12, s8
	s_addc_u32 s11, s13, s9
	s_add_u32 s8, s8, 0x1000
	s_waitcnt lgkmcnt(0)
	v_add_f32_e32 v12, v12, v13
	ds_bpermute_b32 v13, v220, v12
	s_addc_u32 s9, s9, 0
	v_lshl_add_u64 v[8:9], v[8:9], 0, 64
	s_cmpk_eq_i32 s8, 0x4000
	s_waitcnt lgkmcnt(0)
	v_add_f32_e32 v12, v12, v13
	ds_bpermute_b32 v13, v144, v12
	s_waitcnt lgkmcnt(0)
	v_add_f32_e32 v12, v12, v13
	ds_bpermute_b32 v13, v148, v12
	s_waitcnt lgkmcnt(0)
	v_add_f32_e32 v12, v12, v13
	ds_bpermute_b32 v13, v149, v12
	s_waitcnt lgkmcnt(0)
	v_add_f32_e32 v12, v12, v13
	ds_bpermute_b32 v13, v150, v12
	s_waitcnt lgkmcnt(0)
	v_add_f32_e32 v12, v12, v13
	v_fmamk_f32 v12, v12, 0x3a800000, v180
	v_cmp_gt_f32_e64 s[40:41], s53, v12
	v_mul_f32_e32 v13, 0x4b800000, v12
	s_nop 0
	v_cndmask_b32_e64 v12, v12, v13, s[40:41]
	v_rsq_f32_e32 v36, v12
	v_lshl_add_u64 v[12:13], s[88:89], 0, v[6:7]
	v_add_co_u32_e64 v24, s[42:43], s0, v12
	v_mul_f32_e32 v37, 0x45800000, v36
	s_nop 0
	v_addc_co_u32_e64 v25, s[42:43], 0, v13, s[42:43]
	global_load_dwordx2 v[28:29], v[24:25], off
	global_load_dwordx4 v[12:15], v[10:11], off
	global_load_dwordx2 v[30:31], v[24:25], off offset:512
	global_load_dwordx4 v[16:19], v[10:11], off offset:1024
	global_load_dwordx2 v[32:33], v[24:25], off offset:1024
	global_load_dwordx4 v[20:23], v[10:11], off offset:2048
	global_load_dwordx2 v[34:35], v[24:25], off offset:1536
	s_nop 0
	global_load_dwordx4 v[24:27], v[10:11], off offset:3072
	v_cndmask_b32_e64 v36, v36, v37, s[40:41]
	v_lshl_add_u64 v[6:7], v[6:7], 0, s[68:69]
	s_waitcnt vmcnt(0) lgkmcnt(0)
	v_lshlrev_b32_e32 v38, 16, v28
	v_and_b32_e32 v39, 0xffff0000, v28
	v_lshlrev_b32_e32 v28, 16, v29
	v_and_b32_e32 v29, 0xffff0000, v29
	v_pk_mul_f32 v[12:13], v[12:13], v[38:39]
	v_pk_mul_f32 v[14:15], v[14:15], v[28:29]
	v_pk_mul_f32 v[12:13], v[12:13], v[36:37] op_sel_hi:[1,0]
	v_pk_mul_f32 v[14:15], v[14:15], v[36:37] op_sel_hi:[1,0]
	v_lshl_add_u64 v[28:29], v[0:1], 2, s[10:11]
	global_store_dwordx4 v[28:29], v[12:15], off sc1
	s_nop 1
	v_lshlrev_b32_e32 v12, 16, v30
	v_and_b32_e32 v13, 0xffff0000, v30
	v_lshlrev_b32_e32 v14, 16, v31
	v_and_b32_e32 v15, 0xffff0000, v31
	v_pk_mul_f32 v[12:13], v[16:17], v[12:13]
	v_pk_mul_f32 v[14:15], v[18:19], v[14:15]
	v_pk_mul_f32 v[12:13], v[36:37], v[12:13] op_sel_hi:[0,1]
	v_pk_mul_f32 v[14:15], v[36:37], v[14:15] op_sel_hi:[0,1]
	v_lshl_add_u64 v[16:17], v[28:29], 0, s[24:25]
	global_store_dwordx4 v[16:17], v[12:15], off sc1
	s_nop 1
	v_lshlrev_b32_e32 v12, 16, v32
	v_and_b32_e32 v13, 0xffff0000, v32
	v_lshlrev_b32_e32 v14, 16, v33
	v_and_b32_e32 v15, 0xffff0000, v33
	v_pk_mul_f32 v[12:13], v[20:21], v[12:13]
	v_pk_mul_f32 v[14:15], v[22:23], v[14:15]
	v_pk_mul_f32 v[12:13], v[36:37], v[12:13] op_sel_hi:[0,1]
	v_pk_mul_f32 v[14:15], v[36:37], v[14:15] op_sel_hi:[0,1]
	v_lshl_add_u64 v[16:17], v[28:29], 0, s[68:69]
	global_store_dwordx4 v[16:17], v[12:15], off sc1
	s_nop 1
	v_lshlrev_b32_e32 v12, 16, v34
	v_and_b32_e32 v13, 0xffff0000, v34
	v_lshlrev_b32_e32 v14, 16, v35
	v_and_b32_e32 v15, 0xffff0000, v35
	v_pk_mul_f32 v[12:13], v[24:25], v[12:13]
	v_pk_mul_f32 v[14:15], v[26:27], v[14:15]
	v_pk_mul_f32 v[12:13], v[36:37], v[12:13] op_sel_hi:[0,1]
	v_pk_mul_f32 v[14:15], v[36:37], v[14:15] op_sel_hi:[0,1]
	v_lshl_add_u64 v[16:17], v[28:29], 0, s[56:57]
	global_store_dwordx4 v[16:17], v[12:15], off sc1
	s_nop 1
	s_cbranch_scc1 .LBB0_17
.LBB0_33:
	v_mov_b32_e32 v12, 0
	s_and_saveexec_b64 s[10:11], vcc
	s_cbranch_execz .LBB0_32
	v_lshl_add_u64 v[12:13], s[88:89], 0, v[8:9]
	global_load_dword v12, v[12:13], off
	s_branch .LBB0_32

.LBB0_45:
	s_cmpk_gt_i32 s2, 0x4f
	s_mov_b64 s[12:13], -1
	s_cbranch_scc0 .LBB0_131
	s_add_i32 s17, s2, 0xffffffb0
	s_bfe_u32 s0, s17, 0xc0004
	s_mulk_i32 s0, 0xb22
	s_lshr_b32 s12, s0, 16
	s_mul_i32 s0, s12, 0x170
	s_sub_i32 s0, s17, s0
	s_lshl_b32 s0, s0, 3
	s_mul_i32 s60, s12, 0xf000
	s_mul_i32 s15, s12, 0xb80
	s_and_b32 s13, s0, 0xfff8
	v_lshl_add_u64 v[36:37], v[138:139], 0, s[60:61]
	s_add_i32 s14, s60, 0x9000
	s_add_i32 s60, s60, 0xc000
	s_add_i32 s15, s15, s13
	s_waitcnt lgkmcnt(0)
	v_lshl_add_u64 v[0:1], v[138:139], 0, s[60:61]
	s_lshl_b32 s60, s15, 11
	v_lshl_add_u64 v[90:91], v[140:141], 0, s[60:61]
	global_load_dwordx4 v[82:85], v[90:91], off
	global_load_dwordx4 v[86:89], v[90:91], off offset:16
	global_load_dwordx4 v[76:79], v[36:37], off
	global_load_dwordx4 v[72:75], v[36:37], off offset:16
	global_load_dwordx4 v[68:71], v[36:37], off offset:32
	global_load_dwordx4 v[64:67], v[36:37], off offset:48
	v_add_co_u32_e32 v44, vcc, 0x3000, v36
	s_mov_b64 s[18:19], 0x6000
	s_nop 0
	v_addc_co_u32_e32 v45, vcc, 0, v37, vcc
	s_mov_b32 s15, s61
	v_lshl_add_u64 v[38:39], v[36:37], 0, s[20:21]
	v_lshl_add_u64 v[92:93], v[36:37], 0, s[18:19]
	v_add_co_u32_e32 v36, vcc, 0x6000, v36
	v_lshl_add_u64 v[2:3], v[138:139], 0, s[14:15]
	s_nop 0
	v_addc_co_u32_e32 v37, vcc, 0, v37, vcc
	global_load_dwordx4 v[56:59], v[38:39], off offset:16
	global_load_dwordx4 v[48:51], v[38:39], off offset:32
	global_load_dwordx4 v[40:43], v[92:93], off offset:16
	global_load_dwordx4 v[32:35], v[92:93], off offset:32
	global_load_dwordx4 v[28:31], v[2:3], off
	global_load_dwordx4 v[24:27], v[2:3], off offset:16
	global_load_dwordx4 v[20:23], v[2:3], off offset:32
	global_load_dwordx4 v[16:19], v[2:3], off offset:48
	global_load_dwordx4 v[12:15], v[0:1], off
	global_load_dwordx4 v[8:11], v[0:1], off offset:16
	global_load_dwordx4 v[4:7], v[0:1], off offset:32
	s_nop 0
	global_load_dwordx4 v[0:3], v[0:1], off offset:48
	s_nop 0
	global_load_dwordx4 v[60:63], v[44:45], off
	global_load_dwordx4 v[52:55], v[38:39], off offset:48
	s_nop 0
	global_load_dwordx4 v[44:47], v[36:37], off
	s_nop 0
	global_load_dwordx4 v[36:39], v[92:93], off offset:48
	global_load_dwordx4 v[134:137], v[90:91], off offset:2048
	global_load_dwordx4 v[130:133], v[90:91], off offset:2064
	v_add_co_u32_e32 v92, vcc, s54, v90
	s_movk_i32 s0, 0x2000
	s_nop 0
	v_addc_co_u32_e32 v93, vcc, 0, v91, vcc
	v_add_co_u32_e32 v94, vcc, s0, v90
	s_mul_i32 s0, s12, 5
	s_nop 0
	v_addc_co_u32_e32 v95, vcc, 0, v91, vcc
	v_add_co_u32_e32 v162, vcc, s1, v90
	s_lshl_b32 s12, s13, 2
	s_nop 0
	v_addc_co_u32_e32 v163, vcc, 0, v91, vcc
	global_load_dwordx4 v[126:129], v[92:93], off
	global_load_dwordx4 v[122:125], v[92:93], off offset:16
	global_load_dwordx4 v[118:121], v[92:93], off offset:2048
	global_load_dwordx4 v[114:117], v[92:93], off offset:2064
	global_load_dwordx4 v[110:113], v[94:95], off
	global_load_dwordx4 v[106:109], v[94:95], off offset:16
	global_load_dwordx4 v[102:105], v[94:95], off offset:2048
	global_load_dwordx4 v[98:101], v[94:95], off offset:2064
	s_nop 0
	global_load_dwordx4 v[94:97], v[162:163], off
	global_load_dwordx4 v[90:93], v[162:163], off offset:16
	s_add_u32 s12, s3, s12
	s_addc_u32 s13, s16, 0
	s_mul_i32 s18, s0, 0x2e00
	s_waitcnt vmcnt(0) lgkmcnt(0)
	v_and_b32_e32 v158, 0xffff0000, v82
	v_and_b32_e32 v160, 0xffff0000, v83
	v_lshlrev_b32_e32 v154, 16, v82
	v_lshlrev_b32_e32 v156, 16, v83
	v_mul_f32_e32 v82, v77, v158
	v_mul_f32_e32 v83, v79, v160
	v_and_b32_e32 v159, 0xffff0000, v84
	v_and_b32_e32 v161, 0xffff0000, v85
	v_fmac_f32_e32 v82, v76, v154
	v_fmac_f32_e32 v83, v78, v156
	v_lshlrev_b32_e32 v155, 16, v84
	v_lshlrev_b32_e32 v157, 16, v85
	v_add_f32_e32 v82, v82, v83
	v_mul_f32_e32 v83, v73, v159
	v_mul_f32_e32 v84, v75, v161
	v_fmac_f32_e32 v83, v72, v155
	v_fmac_f32_e32 v84, v74, v157
	v_and_b32_e32 v147, 0xffff0000, v86
	v_and_b32_e32 v152, 0xffff0000, v87
	v_add_f32_e32 v82, 0, v82
	v_add_f32_e32 v83, v83, v84
	v_lshlrev_b32_e32 v80, 16, v86
	v_lshlrev_b32_e32 v145, 16, v87
	v_add_f32_e32 v82, v83, v82
	v_mul_f32_e32 v83, v69, v147
	v_mul_f32_e32 v84, v71, v152
	v_fmac_f32_e32 v83, v68, v80
	v_fmac_f32_e32 v84, v70, v145
	v_and_b32_e32 v151, 0xffff0000, v88
	v_and_b32_e32 v153, 0xffff0000, v89
	v_add_f32_e32 v83, v83, v84
	v_lshlrev_b32_e32 v143, 16, v88
	v_lshlrev_b32_e32 v146, 16, v89
	v_add_f32_e32 v164, v83, v82
	v_mul_f32_e32 v82, v65, v151
	v_mul_f32_e32 v83, v67, v153
	v_fmac_f32_e32 v82, v64, v143
	v_fmac_f32_e32 v83, v66, v146
	v_add_f32_e32 v165, v82, v83
	global_load_dwordx4 v[86:89], v[162:163], off offset:2048
	global_load_dwordx4 v[82:85], v[162:163], off offset:2064
	v_add_f32_e32 v162, v165, v164
	s_waitcnt lgkmcnt(0)
	s_nop 1
	v_add_f32_dpp v162, v162, v162 quad_perm:[1,0,3,2] row_mask:0xf bank_mask:0xf
	s_nop 1
	v_add_f32_dpp v162, v162, v162 quad_perm:[2,3,0,1] row_mask:0xf bank_mask:0xf
	s_nop 1
	v_add_f32_dpp v162, v162, v162 row_half_mirror row_mask:0xf bank_mask:0xf
	s_nop 1
	v_add_f32_dpp v162, v162, v162 row_mirror row_mask:0xf bank_mask:0xf
	s_nop 1
	v_readlane_b32 s100, v162, 16
	v_readlane_b32 s101, v162, 32
	s_nop 1
	v_add_f32_e32 v163, s100, v162
	v_readlane_b32 s100, v162, 48
	v_add_f32_e32 v163, s101, v163
	s_nop 1
	v_add_f32_e32 v162, s100, v163
	s_and_saveexec_b64 s[14:15], s[38:39]
	s_cbranch_execz .LBB0_48
	v_mov_b32_e32 v163, s18
	global_store_dword v163, v162, s[12:13] sc1

.LBB0_126:
	s_or_b64 exec, exec, s[14:15]
	s_cmpk_gt_u32 s17, 0x16f
	s_cbranch_scc1 .LBB0_130
	s_waitcnt vmcnt(0)
	s_and_saveexec_b64 s[12:13], s[38:39]
	s_cbranch_execz .LBB0_129
	s_waitcnt lgkmcnt(0)
	v_mov_b64_e32 v[0:1], s[8:9]
	global_atomic_add v[0:1], v181, off

.LBB0_131:
	s_and_b64 vcc, exec, s[12:13]
	s_cbranch_vccz .LBB0_44
	v_ashrrev_i32_e32 v2, 10, v142
	s_mov_b32 s0, 0x66666667
	s_load_dwordx2 s[12:13], s[86:87], 0x48
	v_mul_hi_i32 v0, v2, s0
	s_waitcnt lgkmcnt(0)
	v_lshrrev_b32_e32 v1, 31, v0
	v_lshrrev_b32_e32 v0, 1, v0
	v_add_lshl_u32 v0, v0, v1, 10
	v_ashrrev_i32_e32 v1, 31, v0
	v_and_b32_e32 v3, 0x3fc, v142
	v_lshl_add_u64 v[4:5], v[0:1], 2, s[12:13]
	v_mul_hi_i32_i24_e32 v1, 0x3000, v2
	v_mul_i32_i24_e32 v0, 0x3000, v2
	v_lshlrev_b32_e32 v80, 2, v3
	v_lshl_add_u64 v[0:1], s[6:7], 0, v[0:1]
	v_lshl_add_u64 v[0:1], v[0:1], 0, v[80:81]
	v_add_co_u32_e32 v0, vcc, s54, v0
	v_lshl_add_u64 v[4:5], v[4:5], 0, v[80:81]
	s_nop 0
	v_addc_co_u32_e32 v1, vcc, 0, v1, vcc
	global_load_dwordx4 v[0:3], v[0:1], off
	v_ashrrev_i32_e32 v143, 31, v142
	global_load_dwordx4 v[4:7], v[4:5], off
	s_waitcnt vmcnt(0) lgkmcnt(0)
	v_pk_add_f32 v[2:3], v[2:3], 1.0 op_sel_hi:[1,0]
	v_pk_add_f32 v[0:1], v[0:1], 1.0 op_sel_hi:[1,0]
	v_pk_mul_f32 v[2:3], v[6:7], v[2:3]
	v_pk_mul_f32 v[0:1], v[4:5], v[0:1]
	v_lshl_add_u64 v[4:5], v[142:143], 2, s[10:11]
	global_store_dwordx4 v[4:5], v[0:3], off sc1
	s_nop 1
	s_branch .LBB0_44

.LBB0_142:
	v_lshl_add_u64 v[20:21], v[8:9], 2, s[18:19]
	v_add_co_u32_e32 v0, vcc, s54, v20
	global_load_dwordx4 v[34:37], v[20:21], off offset:16
	global_load_dwordx4 v[38:41], v[20:21], off
	s_waitcnt lgkmcnt(0)
	v_addc_co_u32_e32 v1, vcc, 0, v21, vcc
	v_lshl_add_u64 v[22:23], v[20:21], 0, s[82:83]
	global_load_dwordx4 v[4:7], v[0:1], off
	s_nop 0
	global_load_dwordx4 v[0:3], v[22:23], off offset:16
	global_load_dwordx4 v[42:45], v[12:13], off offset:16
	global_load_dwordx4 v[26:29], v[12:13], off
	global_load_dwordx4 v[46:49], v[16:17], off
	global_load_dwordx4 v[50:53], v[16:17], off offset:16
	s_lshl_b64 s[16:17], s[14:15], 11
	s_waitcnt vmcnt(0)
	v_mul_f32_e32 v33, v37, v37
	v_fmac_f32_e32 v33, v36, v36
	s_waitcnt lgkmcnt(0)
	v_pk_add_f32 v[18:19], v[48:49], 1.0 op_sel_hi:[1,0]
	s_nop 0
	v_pk_mul_f32 v[24:25], v[28:29], v[18:19]
	v_pk_add_f32 v[18:19], v[52:53], 1.0 op_sel_hi:[1,0]
	v_pk_add_f32 v[30:31], v[46:47], 1.0 op_sel_hi:[1,0]
	v_pk_mul_f32 v[28:29], v[44:45], v[18:19]
	v_mul_f32_e32 v18, v39, v39
	v_mul_f32_e32 v19, v41, v41
	v_fmac_f32_e32 v18, v38, v38
	v_fmac_f32_e32 v19, v40, v40
	v_add_f32_e32 v18, v18, v19
	v_mul_f32_e32 v19, v35, v35
	v_fmac_f32_e32 v19, v34, v34
	v_add_f32_e32 v19, v19, v33
	v_add_f32_e32 v33, v18, v19
	v_mul_f32_e32 v18, v5, v5
	v_mul_f32_e32 v19, v7, v7
	v_pk_mul_f32 v[26:27], v[26:27], v[30:31]
	v_pk_add_f32 v[30:31], v[50:51], 1.0 op_sel_hi:[1,0]
	v_fmac_f32_e32 v18, v4, v4
	v_fmac_f32_e32 v19, v6, v6
	v_pk_mul_f32 v[30:31], v[42:43], v[30:31]
	v_add_f32_e32 v18, v18, v19
	v_mul_f32_e32 v19, v1, v1
	v_mul_f32_e32 v42, v3, v3
	v_fmac_f32_e32 v19, v0, v0
	v_fmac_f32_e32 v42, v2, v2
	v_add_f32_e32 v19, v19, v42
	v_add_f32_e32 v46, v18, v19
	v_pk_mul_f32 v[18:19], v[40:41], v[24:25]
	v_pk_mul_f32 v[38:39], v[38:39], v[26:27]
	v_pk_mul_f32 v[34:35], v[34:35], v[30:31]
	v_cvt_pk_bf16_f32 v38, v38, v39
	v_cvt_pk_bf16_f32 v39, v18, v19
	v_pk_mul_f32 v[18:19], v[36:37], v[28:29]
	v_cvt_pk_bf16_f32 v40, v34, v35
	v_cvt_pk_bf16_f32 v41, v18, v19
	v_lshl_add_u64 v[18:19], v[14:15], 0, s[16:17]
	global_store_dwordx4 v[18:19], v[38:41], off sc1
	s_nop 1
	v_pk_mul_f32 v[6:7], v[6:7], v[24:25]
	v_pk_mul_f32 v[4:5], v[4:5], v[26:27]
	v_pk_mul_f32 v[2:3], v[2:3], v[28:29]
	v_pk_mul_f32 v[0:1], v[0:1], v[30:31]
	v_cvt_pk_bf16_f32 v4, v4, v5
	v_cvt_pk_bf16_f32 v5, v6, v7
	v_cvt_pk_bf16_f32 v6, v0, v1
	v_cvt_pk_bf16_f32 v7, v2, v3
	v_lshl_add_u64 v[0:1], v[18:19], 0, s[68:69]
	global_store_dwordx4 v[0:1], v[4:7], off sc1
	s_nop 1
	global_load_dwordx4 v[24:27], v[20:21], off offset:2064
	global_load_dwordx4 v[28:31], v[20:21], off offset:2048
	global_load_dwordx4 v[0:3], v[22:23], off offset:2064
	global_load_dwordx4 v[4:7], v[22:23], off offset:2048
	s_nop 0
	global_load_dwordx4 v[20:23], v[12:13], off offset:2064
	global_load_dwordx4 v[34:37], v[12:13], off offset:2048
	global_load_dwordx4 v[38:41], v[16:17], off offset:2048
	global_load_dwordx4 v[42:45], v[16:17], off offset:2064
	s_waitcnt vmcnt(0) lgkmcnt(0)
	v_pk_add_f32 v[40:41], v[40:41], 1.0 op_sel_hi:[1,0]
	s_nop 0
	v_pk_mul_f32 v[36:37], v[36:37], v[40:41]
	v_pk_add_f32 v[40:41], v[42:43], 1.0 op_sel_hi:[1,0]
	v_pk_add_f32 v[38:39], v[38:39], 1.0 op_sel_hi:[1,0]
	v_pk_mul_f32 v[40:41], v[20:21], v[40:41]
	v_mul_f32_e32 v20, v29, v29
	v_mul_f32_e32 v21, v31, v31
	v_pk_mul_f32 v[34:35], v[34:35], v[38:39]
	v_pk_add_f32 v[38:39], v[44:45], 1.0 op_sel_hi:[1,0]
	v_fmac_f32_e32 v20, v28, v28
	v_fmac_f32_e32 v21, v30, v30
	v_pk_mul_f32 v[38:39], v[22:23], v[38:39]
	v_add_f32_e32 v20, v20, v21
	v_mul_f32_e32 v21, v25, v25
	v_mul_f32_e32 v22, v27, v27
	v_fmac_f32_e32 v21, v24, v24
	v_fmac_f32_e32 v22, v26, v26
	v_add_f32_e32 v21, v21, v22
	v_add_f32_e32 v20, v20, v21
	v_add_f32_e32 v21, v33, v20
	v_mul_f32_e32 v20, v5, v5
	v_mul_f32_e32 v22, v7, v7
	v_fmac_f32_e32 v20, v4, v4
	v_fmac_f32_e32 v22, v6, v6
	v_add_f32_e32 v20, v20, v22
	v_mul_f32_e32 v22, v1, v1
	v_mul_f32_e32 v23, v3, v3
	v_fmac_f32_e32 v22, v0, v0
	v_fmac_f32_e32 v23, v2, v2
	v_add_f32_e32 v22, v22, v23
	v_add_f32_e32 v20, v20, v22
	v_pk_mul_f32 v[30:31], v[30:31], v[36:37]
	v_pk_mul_f32 v[22:23], v[28:29], v[34:35]
	v_pk_mul_f32 v[26:27], v[26:27], v[38:39]
	v_pk_mul_f32 v[24:25], v[24:25], v[40:41]
	v_pk_mul_f32 v[6:7], v[6:7], v[36:37]
	v_pk_mul_f32 v[4:5], v[4:5], v[34:35]
	v_pk_mul_f32 v[0:1], v[0:1], v[40:41]
	v_add_f32_e32 v20, v46, v20
	v_cvt_pk_bf16_f32 v22, v22, v23
	v_cvt_pk_bf16_f32 v23, v30, v31
	v_cvt_pk_bf16_f32 v24, v24, v25
	v_cvt_pk_bf16_f32 v25, v26, v27
	v_lshl_add_u64 v[26:27], v[18:19], 0, s[24:25]
	global_store_dwordx4 v[26:27], v[22:25], off sc1
	s_nop 1
	v_cvt_pk_bf16_f32 v4, v4, v5
	v_cvt_pk_bf16_f32 v5, v6, v7
	v_pk_mul_f32 v[2:3], v[2:3], v[38:39]
	v_cvt_pk_bf16_f32 v6, v0, v1
	v_lshl_add_u64 v[0:1], v[18:19], 0, s[56:57]
	v_cvt_pk_bf16_f32 v7, v2, v3
	global_store_dwordx4 v[0:1], v[4:7], off sc1
	s_nop 1
	ds_bpermute_b32 v0, v219, v21
	ds_bpermute_b32 v2, v219, v20
	s_waitcnt lgkmcnt(1)
	v_add_f32_e32 v0, v21, v0
	s_waitcnt lgkmcnt(0)
	v_add_f32_e32 v2, v20, v2
	ds_bpermute_b32 v1, v220, v0
	ds_bpermute_b32 v3, v220, v2
	s_waitcnt lgkmcnt(1)
	v_add_f32_e32 v0, v0, v1
	s_waitcnt lgkmcnt(0)
	v_add_f32_e32 v2, v2, v3
	ds_bpermute_b32 v1, v144, v0
	ds_bpermute_b32 v3, v144, v2
	s_waitcnt lgkmcnt(1)
	v_add_f32_e32 v0, v0, v1
	s_waitcnt lgkmcnt(0)
	v_add_f32_e32 v2, v2, v3
	ds_bpermute_b32 v1, v148, v0
	ds_bpermute_b32 v3, v148, v2
	s_waitcnt lgkmcnt(1)
	v_add_f32_e32 v0, v0, v1
	s_waitcnt lgkmcnt(0)
	v_add_f32_e32 v2, v2, v3
	ds_bpermute_b32 v1, v149, v0
	ds_bpermute_b32 v3, v149, v2
	s_waitcnt lgkmcnt(1)
	v_add_f32_e32 v0, v0, v1
	s_waitcnt lgkmcnt(0)
	v_add_f32_e32 v2, v2, v3
	ds_bpermute_b32 v1, v150, v0
	ds_bpermute_b32 v3, v150, v2
	s_and_saveexec_b64 s[16:17], s[38:39]
	s_cbranch_execz .LBB0_137
	s_waitcnt lgkmcnt(0)
	v_add_f32_e32 v2, v2, v3
	v_add_f32_e32 v0, v0, v1
	v_cndmask_b32_e64 v0, v2, v0, s[42:43]
	v_cndmask_b32_e64 v2, 0, v0, s[40:41]
	v_add_u32_e32 v0, s14, v32
	v_ashrrev_i32_e32 v1, 31, v0
	v_lshlrev_b64 v[0:1], 6, v[0:1]
	v_lshl_add_u64 v[0:1], v[10:11], 0, v[0:1]
	global_store_dword v[0:1], v2, off sc1
	s_branch .LBB0_137
.LBB0_144:
	s_waitcnt vmcnt(0)
	s_waitcnt lgkmcnt(0)
	s_barrier
	s_and_saveexec_b64 s[10:11], s[8:9]
	s_cbranch_execz .LBB0_135
	s_lshl_b32 s0, s28, 4
	s_add_u32 s12, s2, s0
	s_addc_u32 s13, s3, 0
	v_mov_b64_e32 v[0:1], s[12:13]
	global_atomic_add v[0:1], v181, off
	s_branch .LBB0_135
.LBB0_146:
	s_waitcnt vmcnt(0)
	s_cmp_eq_u32 s73, 0
	v_readlane_b32 s6, v254, 6
	s_cselect_b64 s[2:3], -1, 0
	v_readlane_b32 s7, v254, 7
	s_and_b64 s[2:3], s[2:3], s[6:7]
	s_waitcnt lgkmcnt(0)
	s_barrier
	s_and_saveexec_b64 s[6:7], s[2:3]
	s_cbranch_execz .LBB0_148
	v_mov_b32_e32 v0, s88
	v_add_co_u32_e32 v0, vcc, 0xa000, v0
	v_mov_b32_e32 v1, s89
	s_nop 0
	v_addc_co_u32_e32 v1, vcc, 0, v1, vcc
	global_atomic_add v[0:1], v181, off offset:2192

.LBB0_184:
	s_mov_b64 s[92:93], 0
	s_and_saveexec_b64 s[90:91], s[40:41]
	s_cbranch_execz .LBB0_186
	global_load_dword v4, v[0:1], off sc1
	s_waitcnt vmcnt(0) lgkmcnt(0)
	v_cmp_gt_u32_e32 vcc, 8, v4
	s_and_b64 s[92:93], vcc, exec

.LBB0_190:
	v_mov_b64_e32 v[4:5], s[14:15]
	global_load_dword v4, v[4:5], off sc1
	s_mov_b64 s[94:95], 0
	s_waitcnt vmcnt(0) lgkmcnt(0)
	v_cmp_eq_u32_e32 vcc, 0, v4
	s_and_saveexec_b64 s[96:97], vcc
	s_cmp_lt_u32 s33, 0x100001
	s_cselect_b64 s[36:37], -1, 0
	s_xor_b64 s[92:93], exec, -1
	s_and_b64 s[94:95], s[36:37], exec
	s_or_b64 exec, exec, s[96:97]
	s_and_saveexec_b64 s[96:97], s[94:95]
	s_cbranch_execz .LBB0_182

.LBB0_196:
	s_or_b64 exec, exec, s[62:63]
	s_xor_b64 s[36:37], s[64:65], -1
	s_and_saveexec_b64 s[40:41], s[36:37]
	s_xor_b64 s[40:41], exec, s[40:41]
	s_cbranch_execz .LBB0_198
	v_mov_b64_e32 v[0:1], s[14:15]
	global_atomic_add v[0:1], v181, off

.LBB0_223:
	v_mov_b64_e32 v[4:5], s[14:15]
	global_load_dword v4, v[4:5], off sc1
	s_mov_b64 s[94:95], 0
	s_waitcnt vmcnt(0) lgkmcnt(0)
	v_cmp_eq_u32_e32 vcc, 0, v4
	s_and_saveexec_b64 s[96:97], vcc
	s_cmp_lt_u32 s2, 0x100001
	s_cselect_b64 s[54:55], -1, 0
	s_xor_b64 s[92:93], exec, -1
	s_and_b64 s[94:95], s[54:55], exec
	s_or_b64 exec, exec, s[96:97]
	s_and_saveexec_b64 s[96:97], s[94:95]
	s_cbranch_execz .LBB0_215

.LBB0_227:
	s_or_b64 exec, exec, s[62:63]
	s_xor_b64 s[40:41], s[64:65], -1
	s_and_saveexec_b64 s[54:55], s[40:41]
	s_xor_b64 s[40:41], exec, s[54:55]
	s_cbranch_execz .LBB0_229
	v_mov_b64_e32 v[0:1], s[14:15]
	global_atomic_add v[0:1], v181, off

.LBB0_230:
	s_min_u32 s2, s5, 0x100
	s_lshl_b32 s2, s2, 8
	s_and_b32 s33, s2, 0x300
	s_add_i32 s40, s58, s33
	s_ashr_i32 s41, s40, 31
	s_lshl_b64 s[54:55], s[40:41], 9
	v_readlane_b32 s1, v254, 52
	s_add_u32 s36, s1, s54
	v_readlane_b32 s1, v254, 53
	s_addc_u32 s41, s1, s55
	s_lshl_b32 s2, s0, 6
	s_lshl_b32 s60, s0, 7
	s_waitcnt vmcnt(0)
	v_mul_f32_e32 v0, 0xbfb8aa3b, v3
	s_add_u32 s66, s36, s60
	v_exp_f32_e32 v3, v0
	s_addc_u32 s67, s41, 0
	s_lshl_b64 s[58:59], s[58:59], 9
	v_readlane_b32 s0, v254, 54
	s_add_u32 s0, s0, s58
	v_readlane_b32 s1, v254, 56
	s_addc_u32 s36, s1, s59
	s_add_u32 s62, s0, s60
	v_add_f32_e32 v4, 1.0, v3
	s_addc_u32 s63, s36, 0
	v_readlane_b32 s0, v254, 57
	v_add_f32_e32 v0, -1.0, v4
	s_add_u32 s0, s0, s58
	v_readlane_b32 s1, v254, 58
	v_sub_f32_e32 v1, v0, v4
	s_addc_u32 s36, s1, s59
	v_add_f32_e32 v1, 1.0, v1
	v_sub_f32_e32 v0, v3, v0
	s_add_u32 s64, s0, s60
	v_add_f32_e32 v5, v0, v1
	v_frexp_mant_f32_e32 v6, v4
	v_cvt_f64_f32_e32 v[0:1], v4
	s_mov_b32 s0, 0x3f2aaaab
	v_frexp_exp_i32_f64_e32 v0, v[0:1]
	v_cmp_gt_f32_e32 vcc, s0, v6
	s_mov_b32 s1, 0x3f317218
	s_addc_u32 s65, s36, 0
	v_subbrev_co_u32_e32 v0, vcc, 0, v0, vcc
	v_sub_u32_e32 v1, 0, v0
	v_ldexp_f32 v4, v4, v1
	v_ldexp_f32 v1, v5, v1
	v_add_f32_e32 v5, -1.0, v4
	v_add_f32_e32 v8, 1.0, v4
	v_add_f32_e32 v6, 1.0, v5
	v_add_f32_e32 v9, -1.0, v8
	v_sub_f32_e32 v6, v4, v6
	v_sub_f32_e32 v4, v4, v9
	v_add_f32_e32 v6, v1, v6
	v_add_f32_e32 v1, v1, v4
	v_add_f32_e32 v4, v8, v1
	v_rcp_f32_e32 v9, v4
	v_add_f32_e32 v7, v5, v6
	v_sub_f32_e32 v5, v7, v5
	v_sub_f32_e32 v5, v6, v5
	v_sub_f32_e32 v6, v4, v8
	v_sub_f32_e32 v1, v1, v6
	v_mul_f32_e32 v6, v7, v9
	v_mul_f32_e32 v8, v4, v6
	v_fma_f32 v10, v6, v4, -v8
	v_fmac_f32_e32 v10, v6, v1
	v_add_f32_e32 v11, v8, v10
	v_sub_f32_e32 v12, v7, v11
	v_sub_f32_e32 v7, v7, v12
	v_sub_f32_e32 v8, v11, v8
	v_sub_f32_e32 v7, v7, v11
	v_add_f32_e32 v5, v5, v7
	v_sub_f32_e32 v7, v8, v10
	v_add_f32_e32 v5, v7, v5
	v_add_f32_e32 v7, v12, v5
	v_mul_f32_e32 v8, v9, v7
	v_mul_f32_e32 v10, v4, v8
	v_fma_f32 v4, v8, v4, -v10
	v_fmac_f32_e32 v4, v8, v1
	v_sub_f32_e32 v1, v12, v7
	v_add_f32_e32 v1, v5, v1
	v_add_f32_e32 v5, v10, v4
	v_sub_f32_e32 v11, v7, v5
	v_sub_f32_e32 v7, v7, v11
	v_sub_f32_e32 v10, v5, v10
	v_sub_f32_e32 v5, v7, v5
	v_add_f32_e32 v1, v1, v5
	v_sub_f32_e32 v4, v10, v4
	v_cvt_f32_i32_e32 v0, v0
	v_add_f32_e32 v1, v4, v1
	v_add_f32_e32 v4, v6, v8
	v_add_f32_e32 v1, v11, v1
	v_sub_f32_e32 v5, v4, v6
	v_mul_f32_e32 v1, v9, v1
	v_sub_f32_e32 v5, v8, v5
	v_add_f32_e32 v1, v5, v1
	v_mul_f32_e32 v8, 0x3f317218, v0
	v_add_f32_e32 v5, v4, v1
	v_fma_f32 v9, v0, s1, -v8
	v_mul_f32_e32 v6, v5, v5
	v_mov_b32_e32 v12, 0x3ecc95a3
	v_fmac_f32_e32 v9, 0xb102e308, v0
	v_sub_f32_e32 v0, v5, v4
	v_fmamk_f32 v7, v6, 0x3e9b6dac, v12
	v_sub_f32_e32 v0, v1, v0
	v_add_f32_e32 v1, v8, v9
	v_fmaak_f32 v7, v6, v7, 0x3f2aaada
	v_sub_f32_e32 v4, v1, v8
	v_ldexp_f32 v8, v5, 1
	v_mul_f32_e32 v5, v5, v6
	v_mul_f32_e32 v5, v5, v7
	v_add_f32_e32 v6, v8, v5
	v_sub_f32_e32 v7, v6, v8
	v_ldexp_f32 v0, v0, 1
	v_sub_f32_e32 v5, v5, v7
	v_add_f32_e32 v0, v0, v5
	v_add_f32_e32 v5, v6, v0
	v_sub_f32_e32 v6, v5, v6
	v_sub_f32_e32 v0, v0, v6
	v_add_f32_e32 v6, v1, v5
	v_sub_f32_e32 v7, v6, v1
	v_sub_f32_e32 v8, v6, v7
	v_sub_f32_e32 v4, v9, v4
	v_sub_f32_e32 v1, v1, v8
	v_sub_f32_e32 v5, v5, v7
	v_add_f32_e32 v1, v5, v1
	v_add_f32_e32 v5, v4, v0
	v_sub_f32_e32 v7, v5, v4
	v_sub_f32_e32 v8, v5, v7
	v_sub_f32_e32 v4, v4, v8
	v_sub_f32_e32 v0, v0, v7
	v_add_f32_e32 v1, v5, v1
	v_add_f32_e32 v0, v0, v4
	v_add_f32_e32 v4, v6, v1
	v_sub_f32_e32 v5, v4, v6
	v_sub_f32_e32 v1, v1, v5
	v_add_f32_e32 v0, v0, v1
	s_mov_b32 s36, 0x7f800000
	v_mul_f32_e32 v1, 0xbfb8aa3b, v2
	v_add_f32_e32 v0, v4, v0
	v_cmp_neq_f32_e32 vcc, s36, v3
	v_mov_b32_e32 v13, 0x7f800000
	v_exp_f32_e32 v2, v1
	v_cndmask_b32_e32 v0, v13, v0, vcc
	v_cmp_ngt_f32_e32 vcc, -1.0, v3
	v_mov_b32_e32 v14, 0x7fc00000
	v_mov_b32_e32 v15, 0xff800000
	v_cndmask_b32_e32 v0, v14, v0, vcc
	v_cmp_neq_f32_e32 vcc, -1.0, v3
	s_mov_b32 s50, 0x33800000
	v_mov_b32_e32 v80, v188
	v_cndmask_b32_e32 v0, v15, v0, vcc
	v_cmp_lt_f32_e64 vcc, |v3|, s50
	s_waitcnt lgkmcnt(0)
	s_barrier
	v_cndmask_b32_e32 v0, v0, v3, vcc
	v_add_f32_e32 v3, 1.0, v2
	v_mul_f32_e32 v115, 0xbfb8aa3b, v0
	v_add_f32_e32 v0, -1.0, v3
	v_sub_f32_e32 v1, v0, v3
	v_add_f32_e32 v1, 1.0, v1
	v_sub_f32_e32 v0, v2, v0
	v_add_f32_e32 v4, v0, v1
	v_frexp_mant_f32_e32 v5, v3
	v_cvt_f64_f32_e32 v[0:1], v3
	v_frexp_exp_i32_f64_e32 v0, v[0:1]
	v_cmp_gt_f32_e32 vcc, s0, v5
	s_mov_b64 s[54:55], 0x8000
	s_nop 0
	v_subbrev_co_u32_e32 v0, vcc, 0, v0, vcc
	v_sub_u32_e32 v1, 0, v0
	v_ldexp_f32 v3, v3, v1
	v_ldexp_f32 v1, v4, v1
	v_add_f32_e32 v4, -1.0, v3
	v_add_f32_e32 v7, 1.0, v3
	v_add_f32_e32 v5, 1.0, v4
	v_add_f32_e32 v8, -1.0, v7
	v_sub_f32_e32 v5, v3, v5
	v_sub_f32_e32 v3, v3, v8
	v_add_f32_e32 v5, v1, v5
	v_add_f32_e32 v1, v1, v3
	v_add_f32_e32 v3, v7, v1
	v_rcp_f32_e32 v8, v3
	v_add_f32_e32 v6, v4, v5
	v_sub_f32_e32 v4, v6, v4
	v_sub_f32_e32 v4, v5, v4
	v_sub_f32_e32 v5, v3, v7
	v_sub_f32_e32 v1, v1, v5
	v_mul_f32_e32 v5, v6, v8
	v_mul_f32_e32 v7, v3, v5
	v_fma_f32 v9, v5, v3, -v7
	v_fmac_f32_e32 v9, v5, v1
	v_add_f32_e32 v10, v7, v9
	v_sub_f32_e32 v11, v6, v10
	v_sub_f32_e32 v6, v6, v11
	v_sub_f32_e32 v7, v10, v7
	v_sub_f32_e32 v6, v6, v10
	v_add_f32_e32 v4, v4, v6
	v_sub_f32_e32 v6, v7, v9
	v_add_f32_e32 v4, v6, v4
	v_add_f32_e32 v6, v11, v4
	v_mul_f32_e32 v7, v8, v6
	v_mul_f32_e32 v9, v3, v7
	v_fma_f32 v3, v7, v3, -v9
	v_fmac_f32_e32 v3, v7, v1
	v_sub_f32_e32 v1, v11, v6
	v_add_f32_e32 v1, v4, v1
	v_add_f32_e32 v4, v9, v3
	v_sub_f32_e32 v10, v6, v4
	v_sub_f32_e32 v6, v6, v10
	v_sub_f32_e32 v9, v4, v9
	v_sub_f32_e32 v4, v6, v4
	v_add_f32_e32 v1, v1, v4
	v_sub_f32_e32 v3, v9, v3
	v_cvt_f32_i32_e32 v0, v0
	v_add_f32_e32 v1, v3, v1
	v_add_f32_e32 v3, v5, v7
	v_add_f32_e32 v1, v10, v1
	v_sub_f32_e32 v4, v3, v5
	v_mul_f32_e32 v1, v8, v1
	v_sub_f32_e32 v4, v7, v4
	v_add_f32_e32 v1, v4, v1
	v_mul_f32_e32 v7, 0x3f317218, v0
	v_add_f32_e32 v4, v3, v1
	v_fma_f32 v8, v0, s1, -v7
	v_mul_f32_e32 v5, v4, v4
	v_fmac_f32_e32 v8, 0xb102e308, v0
	v_sub_f32_e32 v0, v4, v3
	v_fmamk_f32 v6, v5, 0x3e9b6dac, v12
	v_sub_f32_e32 v0, v1, v0
	v_add_f32_e32 v1, v7, v8
	v_fmaak_f32 v6, v5, v6, 0x3f2aaada
	v_sub_f32_e32 v3, v1, v7
	v_ldexp_f32 v7, v4, 1
	v_mul_f32_e32 v4, v4, v5
	v_mul_f32_e32 v4, v4, v6
	v_add_f32_e32 v5, v7, v4
	v_sub_f32_e32 v6, v5, v7
	v_ldexp_f32 v0, v0, 1
	v_sub_f32_e32 v4, v4, v6
	v_add_f32_e32 v0, v0, v4
	v_add_f32_e32 v4, v5, v0
	v_sub_f32_e32 v5, v4, v5
	v_sub_f32_e32 v0, v0, v5
	v_add_f32_e32 v5, v1, v4
	v_sub_f32_e32 v6, v5, v1
	v_sub_f32_e32 v7, v5, v6
	v_sub_f32_e32 v3, v8, v3
	v_sub_f32_e32 v1, v1, v7
	v_sub_f32_e32 v4, v4, v6
	v_add_f32_e32 v1, v4, v1
	v_add_f32_e32 v4, v3, v0
	v_sub_f32_e32 v6, v4, v3
	v_sub_f32_e32 v7, v4, v6
	v_sub_f32_e32 v3, v3, v7
	v_sub_f32_e32 v0, v0, v6
	v_add_f32_e32 v1, v4, v1
	v_add_f32_e32 v0, v0, v3
	v_add_f32_e32 v3, v5, v1
	v_sub_f32_e32 v4, v3, v5
	v_sub_f32_e32 v1, v1, v4
	v_add_f32_e32 v0, v0, v1
	v_add_f32_e32 v0, v3, v0
	v_cmp_neq_f32_e32 vcc, s36, v2
	v_ashrrev_i32_e32 v4, 3, v80
	v_add_u32_e32 v5, s10, v4
	v_cndmask_b32_e32 v0, v13, v0, vcc
	v_cmp_ngt_f32_e32 vcc, -1.0, v2
	v_and_b32_e32 v114, 31, v80
	v_or_b32_e32 v116, s51, v114
	v_cndmask_b32_e32 v0, v14, v0, vcc
	v_cmp_neq_f32_e32 vcc, -1.0, v2
	v_ashrrev_i32_e32 v136, 5, v80
	v_ashrrev_i32_e32 v117, 31, v116
	v_cndmask_b32_e32 v0, v15, v0, vcc
	v_cmp_lt_f32_e64 vcc, |v2|, s50
	v_readlane_b32 s1, v253, 62
	v_lshlrev_b32_e32 v141, 2, v136
	v_cndmask_b32_e32 v0, v0, v2, vcc
	v_mul_f32_e32 v137, 0xbfb8aa3b, v0
	v_lshrrev_b32_e32 v0, 1, v5
	v_xor_b32_e32 v0, v0, v80
	v_lshlrev_b32_e32 v0, 3, v0
	v_and_b32_e32 v6, 56, v0
	v_lshlrev_b32_e32 v0, 3, v80
	v_and_b32_e32 v142, 24, v0
	v_lshlrev_b64 v[0:1], 9, v[116:117]
	v_lshlrev_b32_e32 v2, 3, v136
	v_lshl_add_u64 v[0:1], s[66:67], 0, v[0:1]
	v_ashrrev_i32_e32 v3, 31, v2
	v_lshl_add_u64 v[0:1], v[2:3], 1, v[0:1]
	global_load_dwordx4 v[94:97], v[0:1], off
	global_load_dwordx4 v[90:93], v[0:1], off offset:32
	global_load_dwordx4 v[86:89], v[0:1], off offset:64
	global_load_dwordx4 v[82:85], v[0:1], off offset:96
	v_lshlrev_b32_e32 v1, 6, v80
	v_readlane_b32 s66, v255, 13
	v_lshl_or_b32 v0, v5, 8, v6
	v_and_b32_e32 v5, 0xffffff00, v1
	v_or_b32_e32 v1, s66, v142
	v_add_u32_e32 v2, v1, v5
	v_ashrrev_i32_e32 v1, 31, v0
	v_lshl_add_u64 v[0:1], v[0:1], 1, s[62:63]
	s_mov_b32 s0, m0
	s_mov_b32 m0, s17
	s_nop 0
	global_load_lds_dwordx4 v[0:1], off
	s_mov_b32 m0, s0
	v_ashrrev_i32_e32 v3, 31, v2
	v_lshl_add_u64 v[2:3], v[2:3], 1, s[64:65]
	s_mov_b32 s0, m0
	s_mov_b32 m0, s38
	s_nop 0
	global_load_lds_dwordx4 v[2:3], off
	s_mov_b32 m0, s0
	v_lshl_add_u64 v[0:1], v[0:1], 0, s[54:55]
	s_add_i32 s0, s16, s1
	s_mov_b32 s36, m0
	s_mov_b32 m0, s0
	s_nop 0
	global_load_lds_dwordx4 v[0:1], off
	s_mov_b32 m0, s36
	v_sub_u32_e32 v0, 63, v80
	v_cvt_f32_i32_e32 v7, v0
	v_lshl_add_u64 v[0:1], v[2:3], 0, s[54:55]
	s_add_i32 s0, s80, s1
	s_mov_b32 s36, m0
	s_mov_b32 m0, s0
	s_nop 0
	global_load_lds_dwordx4 v[0:1], off
	s_mov_b32 m0, s36
	v_cvt_f32_i32_e32 v1, v80
	v_mul_f32_e32 v0, v115, v7
	v_exp_f32_e32 v0, v0
	v_cvt_f32_i32_e32 v3, v116
	v_mul_f32_e32 v1, v137, v1
	v_exp_f32_e32 v1, v1
	v_sub_u32_e32 v7, 0xff, v116
	v_cvt_f32_i32_e32 v7, v7
	v_readlane_b32 s0, v255, 12
	s_or_b32 s50, s33, 0xff
	s_sub_i32 s36, s33, 63
	v_lshl_add_u32 v2, v80, 2, s0
	ds_write2st64_b32 v2, v0, v1 offset1:1
	v_mul_f32_e32 v0, v115, v3
	v_exp_f32_e32 v139, v0
	v_mul_f32_e32 v0, v137, v7
	v_exp_f32_e32 v138, v0
	v_lshrrev_b32_e32 v0, 2, v80
	v_and_or_b32 v0, v0, 3, v141
	v_lshlrev_b32_e32 v117, 6, v0
	v_lshlrev_b32_e32 v0, 1, v80
	v_and_b32_e32 v143, 32, v0
	v_lshrrev_b32_e32 v0, 1, v80
	v_bitop3_b32 v1, v0, v136, 7 bitop3:0x6c
	v_lshlrev_b32_e32 v151, 4, v1
	v_add_u32_e32 v1, 2, v136
	v_bitop3_b32 v1, v1, v0, 7 bitop3:0x78
	v_lshlrev_b32_e32 v145, 4, v1
	v_add_u32_e32 v1, 4, v136
	v_bitop3_b32 v1, v1, v0, 7 bitop3:0x78
	v_lshl_add_u32 v140, v136, 4, s0
	v_lshlrev_b32_e32 v146, 4, v1
	v_add_u32_e32 v1, 6, v136
	s_lshl_b32 s0, s37, 6
	v_bitop3_b32 v0, v1, v0, 7 bitop3:0x78
	s_sub_i32 s55, s0, 64
	s_or_b32 s0, s58, s60
	v_readlane_b32 s1, v255, 22
	v_lshlrev_b32_e32 v147, 4, v0
	v_add3_u32 v0, s66, v5, v142
	s_add_u32 s62, s1, s0
	v_readlane_b32 s1, v255, 23
	v_ashrrev_i32_e32 v1, 31, v0
	s_addc_u32 s63, s1, s59
	v_lshl_add_u64 v[118:119], v[0:1], 1, s[62:63]
	v_lshlrev_b32_e32 v0, 8, v4
	v_readlane_b32 s1, v255, 26
	s_waitcnt lgkmcnt(0)
	s_mov_b32 s41, 0
	s_mov_b32 s54, 2
	v_add3_u32 v0, s1, v0, v6
	v_readlane_b32 s1, v255, 24
	s_add_u32 s58, s1, s0
	v_readlane_b32 s0, v255, 25
	v_ashrrev_i32_e32 v1, 31, v0
	s_addc_u32 s59, s0, s59
	s_add_i32 s0, s51, s33
	v_lshl_add_u64 v[120:121], v[0:1], 1, s[58:59]
	v_add_u32_e32 v0, s0, v114
	v_sub_u32_e32 v152, v0, v141
	v_mov_b32_e32 v0, 0
	v_lshlrev_b32_e32 v144, 7, v114
	s_xor_b32 s64, s33, 0xffffff01
	s_mov_b32 s60, 0
	s_mov_b32 s65, 0
	v_mov_b32_e32 v1, v0
	v_mov_b32_e32 v2, v0
	v_mov_b32_e32 v3, v0
	v_mov_b32_e32 v4, v0
	v_mov_b32_e32 v5, v0
	v_mov_b32_e32 v6, v0
	v_mov_b32_e32 v7, v0
	v_mov_b32_e32 v8, v0
	v_mov_b32_e32 v9, v0
	v_mov_b32_e32 v10, v0
	v_mov_b32_e32 v11, v0
	v_mov_b32_e32 v12, v0
	v_mov_b32_e32 v13, v0
	v_mov_b32_e32 v14, v0
	v_mov_b32_e32 v15, v0
	v_mov_b32_e32 v16, v0
	v_mov_b32_e32 v17, v0
	v_mov_b32_e32 v18, v0
	v_mov_b32_e32 v19, v0
	v_mov_b32_e32 v20, v0
	v_mov_b32_e32 v21, v0
	v_mov_b32_e32 v22, v0
	v_mov_b32_e32 v23, v0
	v_mov_b32_e32 v24, v0
	v_mov_b32_e32 v25, v0
	v_mov_b32_e32 v26, v0
	v_mov_b32_e32 v27, v0
	v_mov_b32_e32 v28, v0
	v_mov_b32_e32 v29, v0
	v_mov_b32_e32 v30, v0
	v_mov_b32_e32 v31, v0
	s_waitcnt vmcnt(0) lgkmcnt(0)
	s_branch .LBB0_232

.LBB0_232:
	s_mul_i32 s66, s60, 0x5000
	s_add_i32 s0, s66, 0
	v_add_u32_e32 v36, s0, v144
	s_waitcnt vmcnt(2)
	s_barrier
	v_add_u32_e32 v32, v36, v151
	ds_read_b128 v[48:51], v32
	ds_read_b128 v[32:35], v32 offset:4096
	v_add_u32_e32 v37, v36, v145
	ds_read_b128 v[64:67], v37
	ds_read_b128 v[52:55], v37 offset:4096
	v_add_u32_e32 v37, v36, v146
	v_add_u32_e32 v36, v36, v147
	ds_read_b128 v[68:71], v37
	ds_read_b128 v[56:59], v37 offset:4096
	ds_read_b128 v[72:75], v36
	ds_read_b128 v[60:63], v36 offset:4096
	s_waitcnt lgkmcnt(0)
	v_mfma_f32_32x32x16_bf16 v[32:47], v[32:35], v[94:97], 0
	v_mfma_f32_32x32x16_bf16 v[32:47], v[52:55], v[90:93], v[32:47]
	v_add3_u32 v52, s0, v117, v143
	v_add_u32_e32 v153, v52, v142
	ds_read_b64_tr_b16 v[110:111], v153 offset:12288
	ds_read_b64_tr_b16 v[112:113], v153 offset:12800
	ds_read_b64_tr_b16 v[106:107], v153 offset:13312
	ds_read_b64_tr_b16 v[108:109], v153 offset:13824
	ds_read_b64_tr_b16 v[102:103], v153 offset:14336
	ds_read_b64_tr_b16 v[104:105], v153 offset:14848
	ds_read_b64_tr_b16 v[98:99], v153 offset:15360
	ds_read_b64_tr_b16 v[100:101], v153 offset:15872
	s_add_i32 s0, s41, 63
	s_cmp_ge_u32 s0, s33
	s_cselect_b64 s[58:59], -1, 0
	s_cmp_lt_u32 s0, s33
	v_mfma_f32_32x32x16_bf16 v[32:47], v[56:59], v[86:89], v[32:47]
	s_cselect_b64 s[62:63], -1, 0
	s_cmp_gt_u32 s41, s50
	s_cselect_b64 s[72:73], -1, 0
	s_or_b64 s[72:73], s[62:63], s[72:73]
	s_mov_b64 s[62:63], -1
	s_andn2_b64 vcc, exec, s[72:73]
	v_mfma_f32_32x32x16_bf16 v[32:47], v[60:63], v[82:85], v[32:47]
	v_mfma_f32_32x32x16_bf16 v[48:63], v[48:51], v[94:97], 0
	v_mfma_f32_32x32x16_bf16 v[48:63], v[64:67], v[90:93], v[48:63]
	v_mfma_f32_32x32x16_bf16 v[48:63], v[68:71], v[86:89], v[48:63]
	v_mfma_f32_32x32x16_bf16 v[48:63], v[72:75], v[82:85], v[48:63]
	s_cbranch_vccz .LBB0_235
	v_cvt_f32_i32_e32 v64, v152
	s_mov_b32 s0, 0xc2000000
	v_cmp_lt_f32_e32 vcc, 0, v64
	v_add_f32_e32 v65, -1.0, v64
	s_mov_b32 s62, -2.0
	v_cndmask_b32_e32 v66, v137, v115, vcc
	v_mul_f32_e64 v66, |v64|, v66
	v_cmp_lt_f32_e32 vcc, 0, v65
	v_exp_f32_e32 v155, v66
	s_mov_b32 s63, 0xc0400000
	v_cndmask_b32_e32 v66, v137, v115, vcc
	v_mul_f32_e64 v66, |v65|, v66
	v_exp_f32_e32 v156, v66
	v_pk_add_f32 v[66:67], v[64:65], s[0:1] op_sel_hi:[1,0]
	s_nop 0
	v_cmp_lt_f32_e32 vcc, 0, v66
	s_nop 1
	v_cndmask_b32_e32 v68, v137, v115, vcc
	v_cmp_lt_f32_e32 vcc, 0, v67
	v_mul_f32_e64 v68, |v66|, v68
	v_exp_f32_e32 v68, v68
	v_cndmask_b32_e32 v69, v137, v115, vcc
	v_mul_f32_e64 v69, |v67|, v69
	v_exp_f32_e32 v69, v69
	v_cmp_neq_f32_e32 vcc, 0, v67
	s_nop 1
	v_cndmask_b32_e32 v67, 2.0, v69, vcc
	v_cmp_neq_f32_e32 vcc, 0, v66
	s_nop 1
	v_cndmask_b32_e32 v66, 2.0, v68, vcc
	v_pk_mul_f32 v[122:123], v[32:33], v[66:67]
	v_pk_add_f32 v[66:67], v[64:65], s[62:63] op_sel_hi:[0,1]
	v_cmp_lt_f32_e32 vcc, 0, v66
	s_mov_b32 s62, 0xc1000000
	s_mov_b32 s63, 0xc1100000
	v_cndmask_b32_e32 v68, v137, v115, vcc
	v_mul_f32_e64 v68, |v66|, v68
	v_cmp_lt_f32_e32 vcc, 0, v67
	v_exp_f32_e32 v157, v68
	s_nop 0
	v_cndmask_b32_e32 v68, v137, v115, vcc
	v_mul_f32_e64 v68, |v67|, v68
	v_exp_f32_e32 v158, v68
	v_pk_add_f32 v[68:69], v[66:67], s[0:1] op_sel_hi:[1,0]
	s_nop 0
	v_cmp_lt_f32_e32 vcc, 0, v68
	s_nop 1
	v_cndmask_b32_e32 v70, v137, v115, vcc
	v_cmp_lt_f32_e32 vcc, 0, v69
	v_mul_f32_e64 v70, |v68|, v70
	v_exp_f32_e32 v70, v70
	v_cndmask_b32_e32 v71, v137, v115, vcc
	v_mul_f32_e64 v71, |v69|, v71
	v_exp_f32_e32 v71, v71
	v_cmp_neq_f32_e32 vcc, 0, v69
	s_nop 1
	v_cndmask_b32_e32 v69, 2.0, v71, vcc
	v_cmp_neq_f32_e32 vcc, 0, v68
	s_nop 1
	v_cndmask_b32_e32 v68, 2.0, v70, vcc
	v_pk_mul_f32 v[124:125], v[34:35], v[68:69]
	v_pk_add_f32 v[68:69], v[64:65], s[62:63] op_sel_hi:[0,1]
	v_cmp_lt_f32_e32 vcc, 0, v68
	s_mov_b32 s62, 0xc1200000
	s_mov_b32 s63, 0xc1300000
	v_cndmask_b32_e32 v70, v137, v115, vcc
	v_mul_f32_e64 v70, |v68|, v70
	v_cmp_lt_f32_e32 vcc, 0, v69
	v_exp_f32_e32 v159, v70
	s_nop 0
	v_cndmask_b32_e32 v70, v137, v115, vcc
	v_mul_f32_e64 v70, |v69|, v70
	v_exp_f32_e32 v160, v70
	v_pk_add_f32 v[70:71], v[68:69], s[0:1] op_sel_hi:[1,0]
	s_nop 0
	v_cmp_lt_f32_e32 vcc, 0, v70
	s_nop 1
	v_cndmask_b32_e32 v72, v137, v115, vcc
	v_cmp_lt_f32_e32 vcc, 0, v71
	v_mul_f32_e64 v72, |v70|, v72
	v_exp_f32_e32 v72, v72
	v_cndmask_b32_e32 v73, v137, v115, vcc
	v_mul_f32_e64 v73, |v71|, v73
	v_exp_f32_e32 v73, v73
	v_cmp_neq_f32_e32 vcc, 0, v71
	s_nop 1
	v_cndmask_b32_e32 v71, 2.0, v73, vcc
	v_cmp_neq_f32_e32 vcc, 0, v70
	s_nop 1
	v_cndmask_b32_e32 v70, 2.0, v72, vcc
	v_pk_mul_f32 v[126:127], v[36:37], v[70:71]
	v_pk_add_f32 v[70:71], v[64:65], s[62:63] op_sel_hi:[0,1]
	v_cmp_lt_f32_e32 vcc, 0, v70
	s_mov_b32 s62, 0xc1800000
	s_mov_b32 s63, 0xc1880000
	v_cndmask_b32_e32 v72, v137, v115, vcc
	v_mul_f32_e64 v72, |v70|, v72
	v_cmp_lt_f32_e32 vcc, 0, v71
	v_exp_f32_e32 v161, v72
	s_nop 0
	v_cndmask_b32_e32 v72, v137, v115, vcc
	v_mul_f32_e64 v72, |v71|, v72
	v_exp_f32_e32 v162, v72
	v_pk_add_f32 v[72:73], v[70:71], s[0:1] op_sel_hi:[1,0]
	s_nop 0
	v_cmp_lt_f32_e32 vcc, 0, v72
	s_nop 1
	v_cndmask_b32_e32 v74, v137, v115, vcc
	v_cmp_lt_f32_e32 vcc, 0, v73
	v_mul_f32_e64 v74, |v72|, v74
	v_exp_f32_e32 v74, v74
	v_cndmask_b32_e32 v75, v137, v115, vcc
	v_mul_f32_e64 v75, |v73|, v75
	v_exp_f32_e32 v75, v75
	v_cmp_neq_f32_e32 vcc, 0, v73
	s_nop 1
	v_cndmask_b32_e32 v73, 2.0, v75, vcc
	v_cmp_neq_f32_e32 vcc, 0, v72
	s_nop 1
	v_cndmask_b32_e32 v72, 2.0, v74, vcc
	v_pk_mul_f32 v[128:129], v[38:39], v[72:73]
	v_pk_add_f32 v[72:73], v[64:65], s[62:63] op_sel_hi:[0,1]
	v_cmp_lt_f32_e32 vcc, 0, v72
	s_mov_b32 s62, 0xc1900000
	s_mov_b32 s63, 0xc1980000
	v_cndmask_b32_e32 v74, v137, v115, vcc
	v_mul_f32_e64 v74, |v72|, v74
	v_cmp_lt_f32_e32 vcc, 0, v73
	v_exp_f32_e32 v163, v74
	s_nop 0
	v_cndmask_b32_e32 v74, v137, v115, vcc
	v_mul_f32_e64 v74, |v73|, v74
	v_exp_f32_e32 v164, v74
	v_pk_add_f32 v[74:75], v[72:73], s[0:1] op_sel_hi:[1,0]
	s_nop 0
	v_cmp_lt_f32_e32 vcc, 0, v74
	s_nop 1
	v_cndmask_b32_e32 v76, v137, v115, vcc
	v_cmp_lt_f32_e32 vcc, 0, v75
	v_mul_f32_e64 v76, |v74|, v76
	v_exp_f32_e32 v76, v76
	v_cndmask_b32_e32 v77, v137, v115, vcc
	v_mul_f32_e64 v77, |v75|, v77
	v_exp_f32_e32 v77, v77
	v_cmp_neq_f32_e32 vcc, 0, v75
	s_nop 1
	v_cndmask_b32_e32 v75, 2.0, v77, vcc
	v_cmp_neq_f32_e32 vcc, 0, v74
	s_nop 1
	v_cndmask_b32_e32 v74, 2.0, v76, vcc
	v_pk_mul_f32 v[130:131], v[40:41], v[74:75]
	v_pk_add_f32 v[74:75], v[64:65], s[62:63] op_sel_hi:[0,1]
	v_cmp_lt_f32_e32 vcc, 0, v74
	s_mov_b32 s62, 0xc1c00000
	s_mov_b32 s63, 0xc1c80000
	v_cndmask_b32_e32 v76, v137, v115, vcc
	v_mul_f32_e64 v76, |v74|, v76
	v_cmp_lt_f32_e32 vcc, 0, v75
	v_exp_f32_e32 v165, v76
	s_nop 0
	v_cndmask_b32_e32 v76, v137, v115, vcc
	v_mul_f32_e64 v76, |v75|, v76
	v_exp_f32_e32 v166, v76
	v_pk_add_f32 v[76:77], v[74:75], s[0:1] op_sel_hi:[1,0]
	s_nop 0
	v_cmp_lt_f32_e32 vcc, 0, v76
	s_nop 1
	v_cndmask_b32_e32 v78, v137, v115, vcc
	v_cmp_lt_f32_e32 vcc, 0, v77
	v_mul_f32_e64 v78, |v76|, v78
	v_exp_f32_e32 v78, v78
	v_cndmask_b32_e32 v79, v137, v115, vcc
	v_mul_f32_e64 v79, |v77|, v79
	v_exp_f32_e32 v79, v79
	v_cmp_neq_f32_e32 vcc, 0, v77
	s_nop 1
	v_cndmask_b32_e32 v77, 2.0, v79, vcc
	v_cmp_neq_f32_e32 vcc, 0, v76
	s_nop 1
	v_cndmask_b32_e32 v76, 2.0, v78, vcc
	v_pk_mul_f32 v[132:133], v[42:43], v[76:77]
	v_pk_add_f32 v[76:77], v[64:65], s[62:63] op_sel_hi:[0,1]
	v_cmp_lt_f32_e32 vcc, 0, v76
	s_mov_b32 s62, 0xc1d00000
	s_mov_b32 s63, 0xc1d80000
	v_cndmask_b32_e32 v78, v137, v115, vcc
	v_mul_f32_e64 v78, |v76|, v78
	v_cmp_lt_f32_e32 vcc, 0, v77
	v_exp_f32_e32 v167, v78
	s_nop 0
	v_cndmask_b32_e32 v78, v137, v115, vcc
	v_mul_f32_e64 v78, |v77|, v78
	v_exp_f32_e32 v168, v78
	v_pk_add_f32 v[78:79], v[76:77], s[0:1] op_sel_hi:[1,0]
	s_nop 0
	v_cmp_lt_f32_e32 vcc, 0, v78
	s_nop 1
	v_cndmask_b32_e32 v134, v137, v115, vcc
	v_cmp_lt_f32_e32 vcc, 0, v79
	v_mul_f32_e64 v134, |v78|, v134
	v_exp_f32_e32 v134, v134
	v_cndmask_b32_e32 v135, v137, v115, vcc
	v_mul_f32_e64 v135, |v79|, v135
	v_exp_f32_e32 v135, v135
	v_cmp_neq_f32_e32 vcc, 0, v79
	s_nop 1
	v_cndmask_b32_e32 v79, 2.0, v135, vcc
	v_cmp_neq_f32_e32 vcc, 0, v78
	s_nop 1
	v_cndmask_b32_e32 v78, 2.0, v134, vcc
	v_pk_mul_f32 v[134:135], v[44:45], v[78:79]
	v_pk_add_f32 v[78:79], v[64:65], s[62:63] op_sel_hi:[0,1]
	v_add_f32_e32 v154, 0xc2000000, v78
	v_cmp_lt_f32_e32 vcc, 0, v78
	s_nop 1
	v_cndmask_b32_e32 v169, v137, v115, vcc
	v_cmp_lt_f32_e32 vcc, 0, v154
	v_mul_f32_e64 v169, |v78|, v169
	v_exp_f32_e32 v169, v169
	v_cndmask_b32_e32 v170, v137, v115, vcc
	v_mul_f32_e64 v170, |v154|, v170
	v_exp_f32_e32 v170, v170
	v_cmp_lt_f32_e32 vcc, 0, v79
	s_nop 1
	v_cndmask_b32_e32 v171, v137, v115, vcc
	v_mul_f32_e64 v171, |v79|, v171
	v_exp_f32_e32 v171, v171
	v_cmp_neq_f32_e32 vcc, 0, v154
	s_nop 1
	v_cndmask_b32_e32 v154, 2.0, v170, vcc
	v_add_f32_e32 v170, 0xc2000000, v79
	v_cmp_lt_f32_e32 vcc, 0, v170
	v_mul_f32_e32 v154, v46, v154
	s_nop 0
	v_cndmask_b32_e32 v172, v137, v115, vcc
	v_cmp_neq_f32_e32 vcc, 0, v79
	v_mul_f32_e64 v172, |v170|, v172
	v_exp_f32_e32 v172, v172
	v_cndmask_b32_e32 v79, 2.0, v171, vcc
	v_cmp_neq_f32_e32 vcc, 0, v78
	s_nop 1
	v_cndmask_b32_e32 v78, 2.0, v169, vcc
	v_cmp_neq_f32_e32 vcc, 0, v77
	s_nop 1
	v_cndmask_b32_e32 v77, 2.0, v168, vcc
	v_cmp_neq_f32_e32 vcc, 0, v76
	s_nop 1
	v_cndmask_b32_e32 v76, 2.0, v167, vcc
	v_cmp_neq_f32_e32 vcc, 0, v75
	s_nop 1
	v_cndmask_b32_e32 v75, 2.0, v166, vcc
	v_cmp_neq_f32_e32 vcc, 0, v74
	s_nop 1
	v_cndmask_b32_e32 v74, 2.0, v165, vcc
	v_cmp_neq_f32_e32 vcc, 0, v73
	s_nop 1
	v_cndmask_b32_e32 v73, 2.0, v164, vcc
	v_cmp_neq_f32_e32 vcc, 0, v72
	s_nop 1
	v_cndmask_b32_e32 v72, 2.0, v163, vcc
	v_cmp_neq_f32_e32 vcc, 0, v71
	s_nop 1
	v_cndmask_b32_e32 v71, 2.0, v162, vcc
	v_cmp_neq_f32_e32 vcc, 0, v70
	s_nop 1
	v_cndmask_b32_e32 v70, 2.0, v161, vcc
	v_cmp_neq_f32_e32 vcc, 0, v69
	s_nop 1
	v_cndmask_b32_e32 v69, 2.0, v160, vcc
	v_cmp_neq_f32_e32 vcc, 0, v68
	s_nop 1
	v_cndmask_b32_e32 v68, 2.0, v159, vcc
	v_cmp_neq_f32_e32 vcc, 0, v67
	s_nop 1
	v_cndmask_b32_e32 v67, 2.0, v158, vcc
	v_cmp_neq_f32_e32 vcc, 0, v66
	s_nop 1
	v_cndmask_b32_e32 v66, 2.0, v157, vcc
	v_cmp_neq_f32_e32 vcc, 0, v64
	s_nop 1
	v_cndmask_b32_e32 v64, 2.0, v155, vcc
	v_cmp_neq_f32_e32 vcc, 0, v65
	s_nop 1
	v_cndmask_b32_e32 v65, 2.0, v156, vcc
	v_cmp_neq_f32_e32 vcc, 0, v170
	s_nop 1
	v_cndmask_b32_e32 v155, 2.0, v172, vcc
	s_cbranch_execz .LBB0_236

.LBB0_250:
	s_nop 8
	v_pk_mul_f32 v[36:37], v[54:55], v[70:71]
	v_pk_mul_f32 v[34:35], v[52:53], v[68:69]
	v_pk_mul_f32 v[38:39], v[50:51], v[66:67]
	v_pk_mul_f32 v[32:33], v[48:49], v[64:65]
	v_cvt_pk_bf16_f32 v34, v34, v35
	v_cvt_pk_bf16_f32 v32, v32, v33
	v_cvt_pk_bf16_f32 v33, v38, v39
	v_cvt_pk_bf16_f32 v35, v36, v37
	ds_read_b64_tr_b16 v[48:49], v131 offset:16384
	ds_read_b64_tr_b16 v[50:51], v131 offset:16896
	ds_read_b64_tr_b16 v[52:53], v131 offset:17408
	ds_read_b64_tr_b16 v[54:55], v131 offset:17920
	s_waitcnt lgkmcnt(10)
	v_mfma_f32_32x32x16_bf16 v[16:31], v[32:35], v[110:113], v[16:31]
	v_mul_f32_e64 v40, v62, v78
	v_mul_f32_e64 v41, v63, v79
	v_mul_f32_e64 v38, v60, v76
	v_mul_f32_e64 v39, v61, v77
	v_mul_f32_e64 v42, v58, v74
	v_mul_f32_e64 v43, v59, v75
	v_pk_mul_f32 v[36:37], v[56:57], v[72:73]
	v_cvt_pk_bf16_f32 v38, v38, v39
	v_cvt_pk_bf16_f32 v36, v36, v37
	v_cvt_pk_bf16_f32 v37, v42, v43
	s_waitcnt lgkmcnt(2)
	v_mfma_f32_32x32x16_bf16 v[0:15], v[32:35], v[48:51], v[0:15]
	v_cvt_pk_bf16_f32 v39, v40, v41
	v_cvt_pk_bf16_f32 v40, v116, v117
	v_cvt_pk_bf16_f32 v41, v118, v119
	v_cvt_pk_bf16_f32 v42, v120, v121
	v_cvt_pk_bf16_f32 v43, v122, v123
	v_mul_f32_e32 v47, v47, v133
	v_cvt_pk_bf16_f32 v44, v124, v125
	v_mfma_f32_32x32x16_bf16 v[16:31], v[36:39], v[106:109], v[16:31]
	v_cvt_pk_bf16_f32 v45, v126, v127
	v_cvt_pk_bf16_f32 v46, v128, v129
	v_cvt_pk_bf16_f32 v47, v132, v47
	s_cmp_lg_u64 s[52:53], 0
	s_waitcnt lgkmcnt(0)
	v_mfma_f32_32x32x16_bf16 v[0:15], v[36:39], v[52:55], v[0:15]
	ds_read_b64_tr_b16 v[32:33], v131 offset:18432
	ds_read_b64_tr_b16 v[34:35], v131 offset:18944
	ds_read_b64_tr_b16 v[36:37], v131 offset:19456
	ds_read_b64_tr_b16 v[38:39], v131 offset:19968
	v_mfma_f32_32x32x16_bf16 v[16:31], v[40:43], v[102:105], v[16:31]
	s_waitcnt lgkmcnt(2)
	v_mfma_f32_32x32x16_bf16 v[0:15], v[40:43], v[32:35], v[0:15]
	v_mfma_f32_32x32x16_bf16 v[16:31], v[44:47], v[98:101], v[16:31]
	s_waitcnt lgkmcnt(0)
	v_mfma_f32_32x32x16_bf16 v[0:15], v[44:47], v[36:39], v[0:15]
	s_cbranch_scc0 .LBB0_252
	v_add_u32_e32 v32, 1, v130
	v_cvt_f32_i32_e32 v32, v32
	v_lshlrev_b32_e32 v34, 16, v94
	v_and_b32_e32 v35, 0xffff0000, v94
	v_lshlrev_b32_e32 v40, 16, v97
	v_mul_f32_e32 v32, v115, v32
	v_exp_f32_e32 v46, v32
	v_sub_u32_e32 v32, s3, v130
	v_cvt_f32_i32_e32 v32, v32
	v_ashrrev_i32_e32 v115, 31, v114
	v_and_b32_e32 v41, 0xffff0000, v97
	v_lshlrev_b64 v[60:61], 7, v[114:115]
	v_mul_f32_e32 v32, v137, v32
	v_exp_f32_e32 v48, v32
	v_lshlrev_b32_e32 v32, 3, v136
	v_ashrrev_i32_e32 v33, 31, v32
	v_lshlrev_b64 v[32:33], 1, v[32:33]
	v_lshl_add_u64 v[56:57], s[52:53], 0, v[32:33]
	v_lshl_add_u64 v[58:59], s[56:57], 0, v[32:33]
	v_pk_mul_f32 v[32:33], v[46:47], v[34:35] op_sel_hi:[0,1]
	v_pk_mul_f32 v[34:35], v[48:49], v[34:35] op_sel_hi:[0,1]
	v_cvt_pk_bf16_f32 v36, v34, v35
	v_lshlrev_b32_e32 v34, 16, v95
	v_and_b32_e32 v35, 0xffff0000, v95
	v_pk_mul_f32 v[38:39], v[46:47], v[34:35] op_sel_hi:[0,1]
	v_cvt_pk_bf16_f32 v32, v32, v33
	v_cvt_pk_bf16_f32 v33, v38, v39
	v_pk_mul_f32 v[34:35], v[48:49], v[34:35] op_sel_hi:[0,1]
	v_lshlrev_b32_e32 v38, 16, v96
	v_and_b32_e32 v39, 0xffff0000, v96
	v_cvt_pk_bf16_f32 v37, v34, v35
	v_pk_mul_f32 v[34:35], v[46:47], v[38:39] op_sel_hi:[0,1]
	v_pk_mul_f32 v[38:39], v[48:49], v[38:39] op_sel_hi:[0,1]
	v_pk_mul_f32 v[42:43], v[46:47], v[40:41] op_sel_hi:[0,1]
	v_pk_mul_f32 v[40:41], v[48:49], v[40:41] op_sel_hi:[0,1]
	v_lshl_add_u64 v[50:51], v[56:57], 0, v[60:61]
	v_cvt_pk_bf16_f32 v34, v34, v35
	v_cvt_pk_bf16_f32 v38, v38, v39
	v_cvt_pk_bf16_f32 v35, v42, v43
	v_cvt_pk_bf16_f32 v39, v40, v41
	global_load_dwordx4 v[40:43], v[50:51], off
	v_lshl_add_u64 v[44:45], v[58:59], 0, v[60:61]
	global_load_dwordx4 v[52:55], v[44:45], off
	s_waitcnt vmcnt(0) lgkmcnt(0)
	v_mfma_f32_32x32x16_bf16 v[16:31], v[32:35], v[40:43], v[16:31]
	v_lshl_add_u64 v[40:41], v[60:61], 0, s[82:83]
	v_lshl_add_u64 v[42:43], v[56:57], 0, v[40:41]
	v_lshl_add_u64 v[40:41], v[58:59], 0, v[40:41]
	global_load_dwordx4 v[56:59], v[40:41], off
	v_mfma_f32_32x32x16_bf16 v[16:31], v[36:39], v[52:55], v[16:31]
	global_load_dwordx4 v[52:55], v[42:43], off
	s_waitcnt vmcnt(0) lgkmcnt(0)
	v_mfma_f32_32x32x16_bf16 v[0:15], v[32:35], v[52:55], v[0:15]
	v_lshlrev_b32_e32 v34, 16, v90
	v_and_b32_e32 v35, 0xffff0000, v90
	v_mul_f32_e64 v32, v46, v34
	v_mul_f32_e64 v33, v46, v35
	v_mul_f32_e64 v34, v48, v34
	v_mul_f32_e64 v35, v48, v35
	v_cvt_pk_bf16_f32 v32, v32, v33
	v_lshlrev_b32_e32 v52, 16, v93
	v_and_b32_e32 v53, 0xffff0000, v93
	v_mfma_f32_32x32x16_bf16 v[0:15], v[36:39], v[56:59], v[0:15]
	v_cvt_pk_bf16_f32 v36, v34, v35
	v_lshlrev_b32_e32 v34, 16, v91
	v_and_b32_e32 v35, 0xffff0000, v91
	v_mul_f32_e64 v38, v46, v34
	v_mul_f32_e64 v39, v46, v35
	v_cvt_pk_bf16_f32 v33, v38, v39
	v_pk_mul_f32 v[34:35], v[48:49], v[34:35] op_sel_hi:[0,1]
	v_lshlrev_b32_e32 v38, 16, v92
	v_and_b32_e32 v39, 0xffff0000, v92
	v_cvt_pk_bf16_f32 v37, v34, v35
	v_pk_mul_f32 v[34:35], v[46:47], v[38:39] op_sel_hi:[0,1]
	v_pk_mul_f32 v[38:39], v[48:49], v[38:39] op_sel_hi:[0,1]
	v_pk_mul_f32 v[54:55], v[46:47], v[52:53] op_sel_hi:[0,1]
	v_pk_mul_f32 v[52:53], v[48:49], v[52:53] op_sel_hi:[0,1]
	v_cvt_pk_bf16_f32 v34, v34, v35
	v_cvt_pk_bf16_f32 v38, v38, v39
	v_cvt_pk_bf16_f32 v35, v54, v55
	v_cvt_pk_bf16_f32 v39, v52, v53
	global_load_dwordx4 v[52:55], v[50:51], off offset:32
	global_load_dwordx4 v[56:59], v[44:45], off offset:32
	s_waitcnt vmcnt(0) lgkmcnt(0)
	v_mfma_f32_32x32x16_bf16 v[16:31], v[32:35], v[52:55], v[16:31]
	v_mfma_f32_32x32x16_bf16 v[16:31], v[36:39], v[56:59], v[16:31]
	global_load_dwordx4 v[52:55], v[42:43], off offset:32
	global_load_dwordx4 v[56:59], v[40:41], off offset:32
	s_waitcnt vmcnt(0) lgkmcnt(0)
	v_mfma_f32_32x32x16_bf16 v[0:15], v[32:35], v[52:55], v[0:15]
	v_lshlrev_b32_e32 v34, 16, v86
	v_and_b32_e32 v35, 0xffff0000, v86
	v_mul_f32_e64 v32, v46, v34
	v_mul_f32_e64 v33, v46, v35
	v_mul_f32_e64 v34, v48, v34
	v_mul_f32_e64 v35, v48, v35
	v_cvt_pk_bf16_f32 v32, v32, v33
	v_lshlrev_b32_e32 v52, 16, v89
	v_and_b32_e32 v53, 0xffff0000, v89
	v_mfma_f32_32x32x16_bf16 v[0:15], v[36:39], v[56:59], v[0:15]
	v_cvt_pk_bf16_f32 v36, v34, v35
	v_lshlrev_b32_e32 v34, 16, v87
	v_and_b32_e32 v35, 0xffff0000, v87
	v_mul_f32_e64 v38, v46, v34
	v_mul_f32_e64 v39, v46, v35
	v_cvt_pk_bf16_f32 v33, v38, v39
	v_pk_mul_f32 v[34:35], v[48:49], v[34:35] op_sel_hi:[0,1]
	v_lshlrev_b32_e32 v38, 16, v88
	v_and_b32_e32 v39, 0xffff0000, v88
	v_cvt_pk_bf16_f32 v37, v34, v35
	v_pk_mul_f32 v[34:35], v[46:47], v[38:39] op_sel_hi:[0,1]
	v_pk_mul_f32 v[38:39], v[48:49], v[38:39] op_sel_hi:[0,1]
	v_pk_mul_f32 v[54:55], v[46:47], v[52:53] op_sel_hi:[0,1]
	v_pk_mul_f32 v[52:53], v[48:49], v[52:53] op_sel_hi:[0,1]
	v_cvt_pk_bf16_f32 v34, v34, v35
	v_cvt_pk_bf16_f32 v38, v38, v39
	v_cvt_pk_bf16_f32 v35, v54, v55
	v_cvt_pk_bf16_f32 v39, v52, v53
	global_load_dwordx4 v[52:55], v[50:51], off offset:64
	global_load_dwordx4 v[56:59], v[44:45], off offset:64
	s_waitcnt vmcnt(0) lgkmcnt(0)
	v_mfma_f32_32x32x16_bf16 v[16:31], v[32:35], v[52:55], v[16:31]
	v_mfma_f32_32x32x16_bf16 v[16:31], v[36:39], v[56:59], v[16:31]
	global_load_dwordx4 v[52:55], v[42:43], off offset:64
	global_load_dwordx4 v[56:59], v[40:41], off offset:64
	s_waitcnt vmcnt(0) lgkmcnt(0)
	v_mfma_f32_32x32x16_bf16 v[0:15], v[32:35], v[52:55], v[0:15]
	v_lshlrev_b32_e32 v32, 16, v82
	v_and_b32_e32 v33, 0xffff0000, v82
	v_mul_f32_e64 v34, v46, v32
	v_mul_f32_e64 v35, v46, v33
	v_mul_f32_e64 v32, v48, v32
	v_mul_f32_e64 v33, v48, v33
	v_cvt_pk_bf16_f32 v32, v32, v33
	v_lshlrev_b32_e32 v52, 16, v85
	v_and_b32_e32 v53, 0xffff0000, v85
	v_mfma_f32_32x32x16_bf16 v[0:15], v[36:39], v[56:59], v[0:15]
	v_cvt_pk_bf16_f32 v36, v34, v35
	v_lshlrev_b32_e32 v34, 16, v83
	v_and_b32_e32 v35, 0xffff0000, v83
	v_mul_f32_e64 v38, v46, v34
	v_mul_f32_e64 v39, v46, v35
	v_pk_mul_f32 v[34:35], v[48:49], v[34:35] op_sel_hi:[0,1]
	v_cvt_pk_bf16_f32 v33, v34, v35
	v_lshlrev_b32_e32 v34, 16, v84
	v_and_b32_e32 v35, 0xffff0000, v84
	v_cvt_pk_bf16_f32 v37, v38, v39
	v_pk_mul_f32 v[38:39], v[46:47], v[34:35] op_sel_hi:[0,1]
	v_pk_mul_f32 v[46:47], v[46:47], v[52:53] op_sel_hi:[0,1]
	v_cvt_pk_bf16_f32 v38, v38, v39
	v_pk_mul_f32 v[34:35], v[48:49], v[34:35] op_sel_hi:[0,1]
	v_cvt_pk_bf16_f32 v39, v46, v47
	v_pk_mul_f32 v[46:47], v[48:49], v[52:53] op_sel_hi:[0,1]
	v_cvt_pk_bf16_f32 v34, v34, v35
	v_cvt_pk_bf16_f32 v35, v46, v47
	global_load_dwordx4 v[46:49], v[50:51], off offset:96
	s_nop 0
	global_load_dwordx4 v[50:53], v[44:45], off offset:96
	s_waitcnt vmcnt(0) lgkmcnt(0)
	v_mfma_f32_32x32x16_bf16 v[16:31], v[36:39], v[46:49], v[16:31]
	global_load_dwordx4 v[42:45], v[42:43], off offset:96
	s_nop 0
	global_load_dwordx4 v[46:49], v[40:41], off offset:96
	v_mfma_f32_32x32x16_bf16 v[16:31], v[32:35], v[50:53], v[16:31]
	s_waitcnt vmcnt(0) lgkmcnt(0)
	v_mfma_f32_32x32x16_bf16 v[0:15], v[36:39], v[42:45], v[0:15]
	v_mfma_f32_32x32x16_bf16 v[0:15], v[32:35], v[46:49], v[0:15]
.LBB0_252:
	s_ashr_i32 s0, s40, 8
	s_add_i32 s0, s0, s79
	s_lshl_b32 s52, s0, 2
	s_ashr_i32 s53, s52, 31
	s_and_saveexec_b64 s[56:57], s[42:43]
	s_cbranch_execz .LBB0_264
	s_lshl_b64 s[36:37], s[52:53], 2
	v_readlane_b32 s0, v255, 10
	s_add_u32 s58, s0, s36
	v_readlane_b32 s0, v255, 11
	s_addc_u32 s59, s0, s37
	v_mov_b64_e32 v[32:33], s[58:59]
	global_load_dword v32, v[32:33], off sc1
	s_waitcnt vmcnt(0) lgkmcnt(0)
	v_cmp_gt_u32_e32 vcc, 4, v32
	s_and_b64 exec, exec, vcc
	s_cbranch_execz .LBB0_264
	s_mov_b32 s0, 1
	s_mov_b64 s[62:63], 0
	s_branch .LBB0_256

.LBB0_256:
	s_and_b32 s3, s0, 0xff
	s_mov_b64 s[90:91], -1
	s_cmp_lg_u32 s3, 0
	s_mov_b64 s[92:93], -1
	s_sleep 1
	s_cbranch_scc1 .LBB0_260
	v_mov_b64_e32 v[32:33], s[14:15]
	global_load_dword v32, v[32:33], off sc1
	s_mov_b64 s[92:93], 0
	s_mov_b64 s[94:95], -1
	s_waitcnt vmcnt(0) lgkmcnt(0)
	v_cmp_eq_u32_e32 vcc, 0, v32
	s_and_saveexec_b64 s[96:97], vcc
	s_cmp_lt_u32 s0, 0x100001
	s_cselect_b64 s[36:37], -1, 0
	s_xor_b64 s[94:95], exec, -1
	s_and_b64 s[92:93], s[36:37], exec
	s_or_b64 exec, exec, s[96:97]
.LBB0_260:
	s_andn2_b64 s[36:37], s[66:67], exec
	s_and_b64 s[54:55], s[94:95], exec
	s_or_b64 s[66:67], s[36:37], s[54:55]
	s_and_saveexec_b64 s[94:95], s[92:93]
	s_cbranch_execz .LBB0_255
	v_mov_b64_e32 v[32:33], s[58:59]
	global_load_dword v32, v[32:33], off sc1
	s_add_i32 s0, s0, 1
	s_or_b64 s[66:67], s[66:67], exec
	s_waitcnt vmcnt(0) lgkmcnt(0)
	v_cmp_lt_u32_e32 vcc, 3, v32
	s_orn2_b64 s[90:91], vcc, exec
	s_branch .LBB0_255
.LBB0_262:
	s_or_b64 exec, exec, s[62:63]
	s_xor_b64 s[36:37], s[64:65], -1
	s_and_saveexec_b64 s[54:55], s[36:37]
	s_mov_b32 s1, 0x800000
	s_mov_b64 s[66:67], 0x4000
	s_xor_b64 s[54:55], exec, s[54:55]
	s_cbranch_execz .LBB0_264
	v_mov_b64_e32 v[32:33], s[14:15]
	global_atomic_add v[32:33], v181, off
.LBB0_264:
	s_or_b64 exec, exec, s[56:57]
	s_lshl_b64 s[36:37], s[52:53], 2
	s_add_u32 s64, s39, s36
	s_addc_u32 s65, s8, s37
	v_ashrrev_i32_e32 v56, 3, v80
	s_add_i32 s0, s40, s51
	s_lshl_b32 s60, s2, 1
	v_lshlrev_b32_e32 v33, 3, v80
	v_add_u32_e32 v32, s0, v56
	s_add_u32 s2, s18, s60
	v_and_b32_e32 v57, 56, v33
	s_addc_u32 s3, s19, 0
	v_lshlrev_b32_e32 v80, 1, v57
	v_ashrrev_i32_e32 v33, 31, v32
	v_add_u32_e32 v38, 8, v32
	v_lshl_add_u64 v[34:35], s[2:3], 0, v[80:81]
	v_lshlrev_b64 v[52:53], 11, v[32:33]
	v_ashrrev_i32_e32 v39, 31, v38
	v_lshl_add_u64 v[36:37], v[34:35], 0, v[52:53]
	v_lshlrev_b64 v[54:55], 11, v[38:39]
	s_waitcnt lgkmcnt(0)
	s_barrier
	v_lshl_add_u64 v[38:39], v[34:35], 0, v[54:55]
	global_load_dwordx4 v[40:43], v[36:37], off
	global_load_dwordx4 v[44:47], v[38:39], off
	v_add_u32_e32 v36, 16, v32
	v_add_u32_e32 v32, 24, v32
	v_ashrrev_i32_e32 v37, 31, v36
	v_ashrrev_i32_e32 v33, 31, v32
	s_movk_i32 s0, 0x440
	v_lshlrev_b64 v[38:39], 11, v[36:37]
	v_lshlrev_b64 v[36:37], 11, v[32:33]
	v_lshlrev_b32_e32 v58, 2, v114
	v_mul_lo_u32 v59, v136, s0
	v_lshl_add_u64 v[48:49], v[34:35], 0, v[38:39]
	v_lshl_add_u64 v[32:33], v[34:35], 0, v[36:37]
	v_add3_u32 v58, s9, v58, v59
	global_load_dwordx4 v[48:51], v[48:49], off
	s_nop 0
	global_load_dwordx4 v[32:35], v[32:33], off
	ds_write2_b32 v58, v16, v0 offset1:32
	ds_write2_b32 v58, v17, v1 offset0:68 offset1:100
	ds_write2_b32 v58, v18, v2 offset0:136 offset1:168
	ds_write2_b32 v58, v19, v3 offset0:204 offset1:236
	v_add_u32_e32 v0, 0x800, v58
	ds_write2_b32 v0, v20, v4 offset0:32 offset1:64
	ds_write2_b32 v0, v21, v5 offset0:100 offset1:132
	ds_write2_b32 v0, v22, v6 offset0:168 offset1:200
	v_add_u32_e32 v0, 0xa00, v58
	ds_write2_b32 v0, v23, v7 offset0:108 offset1:140
	v_add_u32_e32 v0, 0x1000, v58
	ds_write2_b32 v0, v24, v8 offset0:64 offset1:96
	ds_write2_b32 v0, v25, v9 offset0:132 offset1:164
	ds_write2_b32 v0, v26, v10 offset0:200 offset1:232
	v_add_u32_e32 v0, 0x1400, v58
	ds_write2_b32 v0, v27, v11 offset0:12 offset1:44
	v_add_u32_e32 v0, 0x1800, v58
	ds_write2_b32 v0, v28, v12 offset0:96 offset1:128
	ds_write2_b32 v0, v29, v13 offset0:164 offset1:196
	v_add_u32_e32 v0, 0x1a00, v58
	ds_write2_b32 v0, v30, v14 offset0:104 offset1:136
	v_add_u32_e32 v0, 0x1c00, v58
	ds_write2_b32 v0, v31, v15 offset0:44 offset1:76
	v_lshlrev_b32_e32 v0, 2, v57
	v_mul_lo_u32 v1, v56, s77
	v_add3_u32 v16, s9, v0, v1
	s_waitcnt lgkmcnt(0)
	ds_read_b128 v[0:3], v16
	ds_read_b128 v[4:7], v16 offset:16
	s_mov_b64 s[40:41], s[42:43]
	s_waitcnt lgkmcnt(0)
	v_pk_mul_f32 v[8:9], v[2:3], v[2:3]
	v_pk_mul_f32 v[10:11], v[0:1], v[0:1]
	s_nop 0
	v_pk_mov_b32 v[12:13], v[10:11], v[8:9] op_sel:[1,0]
	v_mov_b32_e32 v11, v9
	v_pk_add_f32 v[8:9], v[12:13], v[10:11]
	v_pk_mul_f32 v[10:11], v[6:7], v[6:7]
	v_pk_mul_f32 v[12:13], v[4:5], v[4:5]
	v_mov_b32_e32 v14, v10
	v_mov_b32_e32 v15, v12
	v_mov_b32_e32 v12, v11
	v_pk_add_f32 v[10:11], v[14:15], v[12:13]
	v_add_f32_e32 v8, v8, v9
	v_add_f32_e32 v8, v8, v11
	v_add_f32_e32 v8, v10, v8
	ds_bpermute_b32 v9, v150, v8
	s_waitcnt lgkmcnt(0)
	v_add_f32_e32 v8, v8, v9
	ds_bpermute_b32 v9, v149, v8
	s_waitcnt lgkmcnt(0)
	v_add_f32_e32 v8, v8, v9
	ds_bpermute_b32 v9, v148, v8
	s_waitcnt lgkmcnt(0)
	v_add_f32_e32 v8, v8, v9
	v_fmamk_f32 v8, v8, 0x3c800000, v180
	v_mul_f32_e32 v9, 0x4b800000, v8
	v_cmp_gt_f32_e32 vcc, s1, v8
	s_waitcnt vmcnt(0)
	v_lshlrev_b32_e32 v10, 16, v40
	v_cndmask_b32_e32 v8, v8, v9, vcc
	v_rsq_f32_e32 v8, v8
	v_and_b32_e32 v11, 0xffff0000, v40
	v_mul_f32_e32 v9, 0x45800000, v8
	v_cndmask_b32_e32 v8, v8, v9, vcc
	v_pk_mul_f32 v[0:1], v[0:1], v[8:9] op_sel_hi:[1,0]
	v_pk_mul_f32 v[2:3], v[2:3], v[8:9] op_sel_hi:[1,0]
	v_pk_mul_f32 v[0:1], v[0:1], v[10:11]
	v_lshlrev_b32_e32 v10, 16, v41
	v_and_b32_e32 v11, 0xffff0000, v41
	v_pk_mul_f32 v[2:3], v[2:3], v[10:11]
	v_cvt_pk_bf16_f32 v0, v0, v1
	v_cvt_pk_bf16_f32 v1, v2, v3
	v_pk_mul_f32 v[2:3], v[4:5], v[8:9] op_sel_hi:[1,0]
	v_lshlrev_b32_e32 v4, 16, v42
	v_and_b32_e32 v5, 0xffff0000, v42
	v_pk_mul_f32 v[2:3], v[2:3], v[4:5]
	v_pk_mul_f32 v[4:5], v[6:7], v[8:9] op_sel_hi:[1,0]
	v_lshlrev_b32_e32 v6, 16, v43
	v_and_b32_e32 v7, 0xffff0000, v43
	v_pk_mul_f32 v[4:5], v[4:5], v[6:7]
	v_cvt_pk_bf16_f32 v2, v2, v3
	v_cvt_pk_bf16_f32 v3, v4, v5
	v_lshl_add_u64 v[4:5], s[26:27], 0, v[52:53]
	v_lshl_add_u64 v[4:5], v[4:5], 0, s[60:61]
	v_lshl_add_u64 v[4:5], v[4:5], 0, v[80:81]
	global_store_dwordx4 v[4:5], v[0:3], off sc1
	s_nop 1
	ds_read_b128 v[0:3], v16 offset:2176
	ds_read_b128 v[4:7], v16 offset:2192
	s_waitcnt lgkmcnt(1)
	v_pk_mul_f32 v[8:9], v[2:3], v[2:3]
	v_pk_mul_f32 v[10:11], v[0:1], v[0:1]
	s_nop 0
	v_pk_mov_b32 v[12:13], v[10:11], v[8:9] op_sel:[1,0]
	v_mov_b32_e32 v11, v9
	v_pk_add_f32 v[8:9], v[12:13], v[10:11]
	s_waitcnt lgkmcnt(0)
	v_pk_mul_f32 v[10:11], v[6:7], v[6:7]
	v_pk_mul_f32 v[12:13], v[4:5], v[4:5]
	v_mov_b32_e32 v14, v10
	v_mov_b32_e32 v15, v12
	v_mov_b32_e32 v12, v11
	v_pk_add_f32 v[10:11], v[14:15], v[12:13]
	v_add_f32_e32 v8, v8, v9
	v_add_f32_e32 v8, v8, v11
	v_add_f32_e32 v8, v10, v8
	ds_bpermute_b32 v9, v150, v8
	v_lshlrev_b32_e32 v10, 16, v44
	v_and_b32_e32 v11, 0xffff0000, v44
	s_waitcnt lgkmcnt(0)
	v_add_f32_e32 v8, v8, v9
	ds_bpermute_b32 v9, v149, v8
	s_waitcnt lgkmcnt(0)
	v_add_f32_e32 v8, v8, v9
	ds_bpermute_b32 v9, v148, v8
	s_waitcnt lgkmcnt(0)
	v_add_f32_e32 v8, v8, v9
	v_fmamk_f32 v8, v8, 0x3c800000, v180
	v_mul_f32_e32 v9, 0x4b800000, v8
	v_cmp_gt_f32_e32 vcc, s1, v8
	s_nop 1
	v_cndmask_b32_e32 v8, v8, v9, vcc
	v_rsq_f32_e32 v8, v8
	s_nop 0
	v_mul_f32_e32 v9, 0x45800000, v8
	v_cndmask_b32_e32 v8, v8, v9, vcc
	v_pk_mul_f32 v[0:1], v[0:1], v[8:9] op_sel_hi:[1,0]
	v_pk_mul_f32 v[2:3], v[2:3], v[8:9] op_sel_hi:[1,0]
	v_pk_mul_f32 v[0:1], v[0:1], v[10:11]
	v_lshlrev_b32_e32 v10, 16, v45
	v_and_b32_e32 v11, 0xffff0000, v45
	v_pk_mul_f32 v[2:3], v[2:3], v[10:11]
	v_cvt_pk_bf16_f32 v0, v0, v1
	v_cvt_pk_bf16_f32 v1, v2, v3
	v_pk_mul_f32 v[2:3], v[4:5], v[8:9] op_sel_hi:[1,0]
	v_lshlrev_b32_e32 v4, 16, v46
	v_and_b32_e32 v5, 0xffff0000, v46
	v_pk_mul_f32 v[2:3], v[2:3], v[4:5]
	v_pk_mul_f32 v[4:5], v[6:7], v[8:9] op_sel_hi:[1,0]
	v_lshlrev_b32_e32 v6, 16, v47
	v_and_b32_e32 v7, 0xffff0000, v47
	v_pk_mul_f32 v[4:5], v[4:5], v[6:7]
	v_cvt_pk_bf16_f32 v2, v2, v3
	v_cvt_pk_bf16_f32 v3, v4, v5
	v_lshl_add_u64 v[4:5], s[26:27], 0, v[54:55]
	v_lshl_add_u64 v[4:5], v[4:5], 0, s[60:61]
	v_lshl_add_u64 v[4:5], v[4:5], 0, v[80:81]
	global_store_dwordx4 v[4:5], v[0:3], off sc1
	s_nop 1
	ds_read_b128 v[0:3], v16 offset:4352
	ds_read_b128 v[4:7], v16 offset:4368
	s_waitcnt lgkmcnt(1)
	v_pk_mul_f32 v[8:9], v[2:3], v[2:3]
	v_pk_mul_f32 v[10:11], v[0:1], v[0:1]
	s_nop 0
	v_pk_mov_b32 v[12:13], v[10:11], v[8:9] op_sel:[1,0]
	v_mov_b32_e32 v11, v9
	v_pk_add_f32 v[8:9], v[12:13], v[10:11]
	s_waitcnt lgkmcnt(0)
	v_pk_mul_f32 v[10:11], v[6:7], v[6:7]
	v_pk_mul_f32 v[12:13], v[4:5], v[4:5]
	v_mov_b32_e32 v14, v10
	v_mov_b32_e32 v15, v12
	v_mov_b32_e32 v12, v11
	v_pk_add_f32 v[10:11], v[14:15], v[12:13]
	v_add_f32_e32 v8, v8, v9
	v_add_f32_e32 v8, v8, v11
	v_add_f32_e32 v8, v10, v8
	ds_bpermute_b32 v9, v150, v8
	v_lshlrev_b32_e32 v10, 16, v48
	v_and_b32_e32 v11, 0xffff0000, v48
	s_waitcnt lgkmcnt(0)
	v_add_f32_e32 v8, v8, v9
	ds_bpermute_b32 v9, v149, v8
	s_waitcnt lgkmcnt(0)
	v_add_f32_e32 v8, v8, v9
	ds_bpermute_b32 v9, v148, v8
	s_waitcnt lgkmcnt(0)
	v_add_f32_e32 v8, v8, v9
	v_fmamk_f32 v8, v8, 0x3c800000, v180
	v_mul_f32_e32 v9, 0x4b800000, v8
	v_cmp_gt_f32_e32 vcc, s1, v8
	s_nop 1
	v_cndmask_b32_e32 v8, v8, v9, vcc
	v_rsq_f32_e32 v8, v8
	s_nop 0
	v_mul_f32_e32 v9, 0x45800000, v8
	v_cndmask_b32_e32 v8, v8, v9, vcc
	v_pk_mul_f32 v[0:1], v[0:1], v[8:9] op_sel_hi:[1,0]
	v_pk_mul_f32 v[2:3], v[2:3], v[8:9] op_sel_hi:[1,0]
	v_pk_mul_f32 v[0:1], v[0:1], v[10:11]
	v_lshlrev_b32_e32 v10, 16, v49
	v_and_b32_e32 v11, 0xffff0000, v49
	v_pk_mul_f32 v[2:3], v[2:3], v[10:11]
	v_cvt_pk_bf16_f32 v0, v0, v1
	v_cvt_pk_bf16_f32 v1, v2, v3
	v_pk_mul_f32 v[2:3], v[4:5], v[8:9] op_sel_hi:[1,0]
	v_lshlrev_b32_e32 v4, 16, v50
	v_and_b32_e32 v5, 0xffff0000, v50
	v_pk_mul_f32 v[2:3], v[2:3], v[4:5]
	v_pk_mul_f32 v[4:5], v[6:7], v[8:9] op_sel_hi:[1,0]
	v_lshlrev_b32_e32 v6, 16, v51
	v_and_b32_e32 v7, 0xffff0000, v51
	v_pk_mul_f32 v[4:5], v[4:5], v[6:7]
	v_cvt_pk_bf16_f32 v2, v2, v3
	v_cvt_pk_bf16_f32 v3, v4, v5
	v_lshl_add_u64 v[4:5], s[26:27], 0, v[38:39]
	v_lshl_add_u64 v[4:5], v[4:5], 0, s[60:61]
	v_lshl_add_u64 v[4:5], v[4:5], 0, v[80:81]
	global_store_dwordx4 v[4:5], v[0:3], off sc1
	s_nop 1
	ds_read_b128 v[0:3], v16 offset:6528
	ds_read_b128 v[4:7], v16 offset:6544
	s_waitcnt lgkmcnt(1)
	v_pk_mul_f32 v[8:9], v[2:3], v[2:3]
	v_pk_mul_f32 v[10:11], v[0:1], v[0:1]
	s_nop 0
	v_pk_mov_b32 v[12:13], v[10:11], v[8:9] op_sel:[1,0]
	v_mov_b32_e32 v11, v9
	v_pk_add_f32 v[8:9], v[12:13], v[10:11]
	s_waitcnt lgkmcnt(0)
	v_pk_mul_f32 v[10:11], v[6:7], v[6:7]
	v_pk_mul_f32 v[12:13], v[4:5], v[4:5]
	v_mov_b32_e32 v14, v10
	v_mov_b32_e32 v15, v12
	v_mov_b32_e32 v12, v11
	v_pk_add_f32 v[10:11], v[14:15], v[12:13]
	v_add_f32_e32 v8, v8, v9
	v_add_f32_e32 v8, v8, v11
	v_add_f32_e32 v8, v10, v8
	ds_bpermute_b32 v9, v150, v8
	v_lshlrev_b32_e32 v10, 16, v32
	v_and_b32_e32 v11, 0xffff0000, v32
	s_waitcnt lgkmcnt(0)
	v_add_f32_e32 v8, v8, v9
	ds_bpermute_b32 v9, v149, v8
	s_waitcnt lgkmcnt(0)
	v_add_f32_e32 v8, v8, v9
	ds_bpermute_b32 v9, v148, v8
	s_waitcnt lgkmcnt(0)
	v_add_f32_e32 v8, v8, v9
	v_fmamk_f32 v8, v8, 0x3c800000, v180
	v_mul_f32_e32 v9, 0x4b800000, v8
	v_cmp_gt_f32_e32 vcc, s1, v8
	s_nop 1
	v_cndmask_b32_e32 v8, v8, v9, vcc
	v_rsq_f32_e32 v8, v8
	s_nop 0
	v_mul_f32_e32 v9, 0x45800000, v8
	v_cndmask_b32_e32 v8, v8, v9, vcc
	v_pk_mul_f32 v[0:1], v[0:1], v[8:9] op_sel_hi:[1,0]
	v_pk_mul_f32 v[2:3], v[2:3], v[8:9] op_sel_hi:[1,0]
	v_pk_mul_f32 v[0:1], v[0:1], v[10:11]
	v_lshlrev_b32_e32 v10, 16, v33
	v_and_b32_e32 v11, 0xffff0000, v33
	v_pk_mul_f32 v[2:3], v[2:3], v[10:11]
	v_cvt_pk_bf16_f32 v0, v0, v1
	v_cvt_pk_bf16_f32 v1, v2, v3
	v_pk_mul_f32 v[2:3], v[4:5], v[8:9] op_sel_hi:[1,0]
	v_lshlrev_b32_e32 v4, 16, v34
	v_and_b32_e32 v5, 0xffff0000, v34
	v_pk_mul_f32 v[2:3], v[2:3], v[4:5]
	v_pk_mul_f32 v[4:5], v[6:7], v[8:9] op_sel_hi:[1,0]
	v_lshlrev_b32_e32 v6, 16, v35
	v_and_b32_e32 v7, 0xffff0000, v35
	v_pk_mul_f32 v[4:5], v[4:5], v[6:7]
	v_cvt_pk_bf16_f32 v2, v2, v3
	v_cvt_pk_bf16_f32 v3, v4, v5
	v_lshl_add_u64 v[4:5], s[26:27], 0, v[36:37]
	v_lshl_add_u64 v[4:5], v[4:5], 0, s[60:61]
	v_lshl_add_u64 v[4:5], v[4:5], 0, v[80:81]
	global_store_dwordx4 v[4:5], v[0:3], off sc1
	s_nop 1
	s_waitcnt vmcnt(0)
	s_barrier

.LBB0_276:
	s_mov_b64 s[92:93], 0
	s_and_saveexec_b64 s[90:91], s[40:41]
	s_cbranch_execz .LBB0_278
	global_load_dword v2, v[0:1], off sc1
	s_waitcnt vmcnt(0) lgkmcnt(0)
	v_cmp_gt_u32_e32 vcc, 8, v2
	s_and_b64 s[92:93], vcc, exec

.LBB0_282:
	v_mov_b64_e32 v[2:3], s[14:15]
	global_load_dword v2, v[2:3], off sc1
	s_mov_b64 s[94:95], 0
	s_waitcnt vmcnt(0) lgkmcnt(0)
	v_cmp_eq_u32_e32 vcc, 0, v2
	s_and_saveexec_b64 s[96:97], vcc
	s_cmp_lt_u32 s3, 0x100001
	s_cselect_b64 s[54:55], -1, 0
	s_xor_b64 s[92:93], exec, -1
	s_and_b64 s[94:95], s[54:55], exec
	s_or_b64 exec, exec, s[96:97]
	s_and_saveexec_b64 s[96:97], s[94:95]
	s_cbranch_execz .LBB0_274

.LBB0_289:
	s_min_u32 s3, s5, 0xc0
	s_lshl_b32 s3, s3, 8
	s_and_b32 s3, s3, 0x300
	s_add_i32 s3, s46, s3
	s_mul_i32 s36, s3, 0x300
	v_readlane_b32 s1, v254, 21
	v_mov_b32_e32 v80, v188
	s_sext_i32_i16 s0, s0
	s_mul_hi_i32 s33, s3, 0x300
	s_add_u32 s36, s1, s36
	v_readlane_b32 s1, v254, 23
	s_waitcnt lgkmcnt(0)
	s_barrier
	s_addc_u32 s41, s1, s33
	v_ashrrev_i32_e32 v62, 3, v80
	s_lshl_b32 s62, s0, 6
	v_add_u32_e32 v4, s10, v62
	s_ashr_i32 s63, s62, 31
	v_lshrrev_b32_e32 v0, 1, v4
	s_lshl_b64 s[46:47], s[62:63], 1
	v_xor_b32_e32 v0, v0, v80
	s_add_u32 s40, s36, s46
	v_lshlrev_b32_e32 v0, 3, v0
	s_addc_u32 s41, s41, s47
	v_and_b32_e32 v121, 31, v80
	v_and_b32_e32 v63, 56, v0
	v_lshlrev_b32_e32 v0, 3, v80
	v_ashrrev_i32_e32 v120, 5, v80
	v_and_b32_e32 v64, 24, v0
	v_or_b32_e32 v2, s51, v121
	v_mov_b64_e32 v[0:1], s[40:41]
	s_movk_i32 s0, 0x300
	v_mad_i64_i32 v[0:1], s[40:41], v2, s0, v[0:1]
	v_lshlrev_b32_e32 v2, 3, v120
	v_ashrrev_i32_e32 v3, 31, v2
	v_lshl_add_u64 v[0:1], v[2:3], 1, v[0:1]
	global_load_dwordx4 v[82:85], v[0:1], off
	global_load_dwordx4 v[86:89], v[0:1], off offset:32
	global_load_dwordx4 v[90:93], v[0:1], off offset:64
	global_load_dwordx4 v[94:97], v[0:1], off offset:96
	v_lshlrev_b32_e32 v1, 5, v80
	v_readlane_b32 s0, v255, 14
	s_or_b32 s36, s2, s37
	v_and_b32_e32 v65, 0xffffff80, v1
	v_or_b32_e32 v1, s0, v64
	s_sub_i32 s0, 0, s2
	s_and_b64 s[40:41], s[44:45], exec
	s_cselect_b32 s40, 0, s0
	s_ashr_i32 s41, s40, 31
	s_lshl_b64 s[40:41], s[40:41], 14
	v_lshl_or_b32 v0, v4, 7, v63
	s_add_u32 s54, s56, s40
	v_add_u32_e32 v2, v1, v65
	s_addc_u32 s55, s57, s41
	v_ashrrev_i32_e32 v1, 31, v0
	s_add_u32 s40, s58, s40
	v_lshlrev_b64 v[58:59], 1, v[0:1]
	v_ashrrev_i32_e32 v3, 31, v2
	s_addc_u32 s41, s59, s41
	v_lshl_add_u64 v[0:1], s[54:55], 0, v[58:59]
	s_mov_b32 s0, m0
	s_mov_b32 m0, s17
	s_nop 0
	global_load_lds_dwordx4 v[0:1], off
	s_mov_b32 m0, s0
	v_lshlrev_b64 v[60:61], 1, v[2:3]
	v_lshl_add_u64 v[0:1], s[40:41], 0, v[60:61]
	s_mov_b32 s0, m0
	s_mov_b32 m0, s38
	s_nop 0
	global_load_lds_dwordx4 v[0:1], off
	s_mov_b32 m0, s0
	s_sub_i32 s0, 1, s2
	s_and_b64 s[40:41], s[44:45], exec
	s_cselect_b32 s40, 1, s0
	s_ashr_i32 s41, s40, 31
	s_lshl_b64 s[40:41], s[40:41], 14
	s_add_u32 s54, s56, s40
	s_addc_u32 s55, s57, s41
	s_add_u32 s40, s58, s40
	s_addc_u32 s41, s59, s41
	v_readlane_b32 s1, v253, 62
	v_lshl_add_u64 v[0:1], s[54:55], 0, v[58:59]
	s_add_i32 s0, s16, s1
	s_mov_b32 s50, m0
	s_mov_b32 m0, s0
	s_nop 0
	global_load_lds_dwordx4 v[0:1], off
	s_mov_b32 m0, s50
	v_lshl_add_u64 v[0:1], s[40:41], 0, v[60:61]
	s_add_i32 s0, s80, s1
	s_mov_b32 s40, m0
	s_mov_b32 m0, s0
	s_nop 0
	global_load_lds_dwordx4 v[0:1], off
	s_mov_b32 m0, s40
	v_lshlrev_b32_e32 v0, 4, v80
	v_and_b32_e32 v0, 0xc0, v0
	v_lshrrev_b32_e32 v4, 1, v80
	v_lshl_or_b32 v32, v120, 8, v0
	v_lshlrev_b32_e32 v0, 1, v80
	v_lshlrev_b32_e32 v122, 7, v121
	v_and_b32_e32 v33, 32, v0
	v_bitop3_b32 v0, v4, v120, 7 bitop3:0x6c
	v_add_u32_e32 v5, 0, v122
	v_lshlrev_b32_e32 v125, 4, v0
	s_waitcnt vmcnt(2)
	s_barrier
	v_add_u32_e32 v6, v5, v125
	ds_read_b128 v[0:3], v6
	ds_read_b128 v[16:19], v6 offset:4096
	v_add_u32_e32 v6, 2, v120
	v_bitop3_b32 v6, v6, v4, 7 bitop3:0x78
	v_lshlrev_b32_e32 v126, 4, v6
	v_add_u32_e32 v6, v5, v126
	ds_read_b128 v[20:23], v6
	ds_read_b128 v[68:71], v6 offset:4096
	v_add_u32_e32 v6, 4, v120
	v_bitop3_b32 v6, v6, v4, 7 bitop3:0x78
	v_lshlrev_b32_e32 v127, 4, v6
	v_add_u32_e32 v6, v5, v127
	ds_read_b128 v[24:27], v6
	ds_read_b128 v[54:57], v6 offset:4096
	v_add_u32_e32 v6, 6, v120
	v_bitop3_b32 v4, v6, v4, 7 bitop3:0x78
	v_lshlrev_b32_e32 v128, 4, v4
	v_add_u32_e32 v4, v5, v128
	ds_read_b128 v[28:31], v4
	ds_read_b128 v[50:53], v4 offset:4096
	s_waitcnt vmcnt(0) lgkmcnt(0)
	v_mfma_f32_32x32x16_bf16 v[0:15], v[0:3], v[82:85], 0
	v_or3_b32 v129, v32, v33, v64
	s_sub_i32 s0, 2, s2
	s_and_b64 s[44:45], s[44:45], exec
	s_cselect_b32 s44, 2, s0
	s_ashr_i32 s45, s44, 31
	s_lshl_b64 s[44:45], s[44:45], 14
	s_add_u32 s54, s56, s44
	v_mfma_f32_32x32x16_bf16 v[0:15], v[20:23], v[86:89], v[0:15]
	s_addc_u32 s55, s57, s45
	s_add_u32 s44, s58, s44
	v_add_u32_e32 v66, 0, v129
	s_addc_u32 s45, s59, s45
	ds_read_b64_tr_b16 v[46:47], v66 offset:12288
	ds_read_b64_tr_b16 v[48:49], v66 offset:12800
	ds_read_b64_tr_b16 v[42:43], v66 offset:13312
	ds_read_b64_tr_b16 v[44:45], v66 offset:13824
	ds_read_b64_tr_b16 v[38:39], v66 offset:14336
	ds_read_b64_tr_b16 v[40:41], v66 offset:14848
	ds_read_b64_tr_b16 v[34:35], v66 offset:15360
	ds_read_b64_tr_b16 v[36:37], v66 offset:15872
	s_add_i32 s0, s17, 0xa000
	s_mov_b32 s33, 1
	v_mfma_f32_32x32x16_bf16 v[0:15], v[24:27], v[90:93], v[0:15]
	v_cmp_gt_u32_e64 s[40:41], 32, v80
	v_lshl_add_u32 v123, v121, 2, s6
	v_lshl_add_u32 v124, v120, 4, s6
	s_add_i32 s37, s2, s37
	v_mfma_f32_32x32x16_bf16 v[0:15], v[28:31], v[94:97], v[0:15]
	v_mfma_f32_32x32x16_bf16 v[16:31], v[16:19], v[82:85], 0
	s_nop 10
	v_max_f32_e32 v32, v1, v1
	v_max_f32_e32 v33, v0, v0
	v_max_f32_e32 v32, v33, v32
	v_max3_f32 v32, v32, v2, v3
	v_max3_f32 v32, v32, v4, v5
	v_max3_f32 v32, v32, v6, v7
	v_max3_f32 v32, v32, v8, v9
	v_mfma_f32_32x32x16_bf16 v[16:31], v[68:71], v[86:89], v[16:31]
	v_max3_f32 v32, v32, v10, v11
	v_max3_f32 v32, v32, v12, v13
	v_max3_f32 v32, v32, v14, v15
	v_mfma_f32_32x32x16_bf16 v[16:31], v[54:57], v[90:93], v[16:31]
	v_mfma_f32_32x32x16_bf16 v[16:31], v[50:53], v[94:97], v[16:31]
	s_nop 11
	v_max3_f32 v32, v32, v16, v17
	v_max3_f32 v32, v32, v18, v19
	v_max3_f32 v32, v32, v20, v21
	v_max3_f32 v32, v32, v22, v23
	v_max3_f32 v32, v32, v24, v25
	v_max3_f32 v32, v32, v26, v27
	v_max3_f32 v32, v32, v28, v29
	v_max3_f32 v32, v32, v30, v31
	ds_bpermute_b32 v33, v219, v32
	s_waitcnt lgkmcnt(0)
	v_max_f32_e32 v33, v33, v33
	v_max_f32_e32 v32, v32, v33
	v_sub_f32_e32 v16, v16, v32
	v_sub_f32_e32 v0, v0, v32
	v_sub_f32_e32 v17, v17, v32
	v_sub_f32_e32 v1, v1, v32
	v_exp_f32_e32 v69, v0
	v_exp_f32_e32 v70, v16
	v_sub_f32_e32 v18, v18, v32
	v_sub_f32_e32 v2, v2, v32
	v_exp_f32_e32 v71, v1
	v_exp_f32_e32 v72, v17
	v_sub_f32_e32 v19, v19, v32
	v_sub_f32_e32 v3, v3, v32
	v_exp_f32_e32 v73, v2
	v_exp_f32_e32 v74, v18
	v_exp_f32_e32 v75, v3
	v_exp_f32_e32 v76, v19
	v_add_f32_e32 v0, v70, v69
	v_add_f32_e32 v0, 0, v0
	v_add_f32_e32 v1, v72, v71
	v_add_f32_e32 v0, v1, v0
	v_add_f32_e32 v1, v74, v73
	v_sub_f32_e32 v20, v20, v32
	v_sub_f32_e32 v21, v21, v32
	v_sub_f32_e32 v4, v4, v32
	v_sub_f32_e32 v33, v5, v32
	v_add_f32_e32 v0, v1, v0
	v_add_f32_e32 v1, v76, v75
	v_add_f32_e32 v2, v1, v0
	v_exp_f32_e32 v1, v4
	v_exp_f32_e32 v5, v20
	v_exp_f32_e32 v0, v33
	v_exp_f32_e32 v4, v21
	v_sub_f32_e32 v50, v6, v32
	v_sub_f32_e32 v51, v7, v32
	v_sub_f32_e32 v22, v22, v32
	v_pk_add_f32 v[6:7], v[4:5], v[0:1]
	v_sub_f32_e32 v23, v23, v32
	v_add_f32_e32 v7, v7, v2
	v_sub_f32_e32 v54, v10, v32
	v_pk_mov_b32 v[2:3], v[0:1], v[0:1] op_sel:[1,0]
	v_pk_mov_b32 v[0:1], v[4:5], v[4:5] op_sel:[1,0]
	v_add_f32_e32 v10, v6, v7
	v_exp_f32_e32 v5, v50
	v_exp_f32_e32 v7, v22
	v_exp_f32_e32 v4, v51
	v_exp_f32_e32 v6, v23
	v_sub_f32_e32 v52, v8, v32
	v_sub_f32_e32 v53, v9, v32
	v_sub_f32_e32 v24, v24, v32
	v_pk_add_f32 v[8:9], v[6:7], v[4:5]
	v_sub_f32_e32 v25, v25, v32
	v_add_f32_e32 v9, v9, v10
	v_sub_f32_e32 v55, v11, v32
	v_sub_f32_e32 v67, v14, v32
	v_pk_mov_b32 v[10:11], v[4:5], v[4:5] op_sel:[1,0]
	v_pk_mov_b32 v[4:5], v[6:7], v[6:7] op_sel:[1,0]
	v_add_f32_e32 v14, v8, v9
	v_exp_f32_e32 v7, v52
	v_exp_f32_e32 v9, v24
	v_exp_f32_e32 v6, v53
	v_exp_f32_e32 v8, v25
	v_sub_f32_e32 v56, v12, v32
	v_sub_f32_e32 v57, v13, v32
	v_sub_f32_e32 v26, v26, v32
	v_pk_add_f32 v[12:13], v[8:9], v[6:7]
	v_sub_f32_e32 v27, v27, v32
	v_add_f32_e32 v13, v13, v14
	v_sub_f32_e32 v68, v15, v32
	v_add_f32_e32 v18, v12, v13
	v_exp_f32_e32 v13, v54
	v_exp_f32_e32 v15, v26
	v_exp_f32_e32 v12, v55
	v_exp_f32_e32 v14, v27
	v_sub_f32_e32 v28, v28, v32
	v_sub_f32_e32 v29, v29, v32
	v_exp_f32_e32 v19, v28
	v_pk_add_f32 v[16:17], v[14:15], v[12:13]
	v_sub_f32_e32 v30, v30, v32
	v_add_f32_e32 v17, v17, v18
	v_add_f32_e32 v22, v16, v17
	v_exp_f32_e32 v17, v56
	v_exp_f32_e32 v16, v57
	v_exp_f32_e32 v18, v29
	v_sub_f32_e32 v31, v31, v32
	v_pk_mov_b32 v[6:7], v[6:7], v[6:7] op_sel:[1,0]
	v_pk_mov_b32 v[8:9], v[8:9], v[8:9] op_sel:[1,0]
	v_pk_add_f32 v[20:21], v[18:19], v[16:17]
	v_pk_mov_b32 v[24:25], v[18:19], v[18:19] op_sel:[1,0]
	v_add_f32_e32 v21, v21, v22
	v_pk_mov_b32 v[22:23], v[16:17], v[16:17] op_sel:[1,0]
	v_exp_f32_e32 v17, v67
	v_exp_f32_e32 v19, v30
	v_exp_f32_e32 v16, v68
	v_exp_f32_e32 v18, v31
	v_add_f32_e32 v26, v20, v21
	v_pk_mov_b32 v[12:13], v[12:13], v[12:13] op_sel:[1,0]
	v_pk_mov_b32 v[14:15], v[14:15], v[14:15] op_sel:[1,0]
	v_pk_add_f32 v[20:21], v[18:19], v[16:17]
	v_pk_mov_b32 v[28:29], v[18:19], v[18:19] op_sel:[1,0]
	v_add_f32_e32 v21, v21, v26
	v_pk_mov_b32 v[26:27], v[16:17], v[16:17] op_sel:[1,0]
	v_lshl_add_u64 v[16:17], s[54:55], 0, v[58:59]
	s_mov_b32 s50, m0
	s_mov_b32 m0, s0
	s_nop 0
	global_load_lds_dwordx4 v[16:17], off
	s_mov_b32 m0, s50
	v_lshl_add_u64 v[16:17], s[44:45], 0, v[60:61]
	s_add_i32 s0, s38, 0xa000
	s_mov_b32 s44, m0
	s_mov_b32 m0, s0
	s_nop 0
	global_load_lds_dwordx4 v[16:17], off
	s_mov_b32 m0, s44
	v_cvt_pk_bf16_f32 v16, v69, v71
	v_cvt_pk_bf16_f32 v17, v73, v75
	v_cvt_pk_bf16_f32 v18, v2, v3
	v_cvt_pk_bf16_f32 v19, v10, v11
	v_cvt_pk_bf16_f32 v58, v6, v7
	v_cvt_pk_bf16_f32 v59, v12, v13
	v_cvt_pk_bf16_f32 v56, v0, v1
	v_cvt_pk_bf16_f32 v57, v4, v5
	v_cvt_pk_bf16_f32 v50, v8, v9
	v_cvt_pk_bf16_f32 v51, v14, v15
	v_mfma_f32_32x32x16_bf16 v[0:15], v[16:19], v[46:49], 0
	v_cvt_pk_bf16_f32 v60, v22, v23
	v_cvt_pk_bf16_f32 v61, v26, v27
	v_cvt_pk_bf16_f32 v54, v70, v72
	v_cvt_pk_bf16_f32 v55, v74, v76
	v_cvt_pk_bf16_f32 v52, v24, v25
	v_cvt_pk_bf16_f32 v53, v28, v29
	v_add_f32_e32 v33, v20, v21
	v_mfma_f32_32x32x16_bf16 v[0:15], v[58:61], v[42:45], v[0:15]
	v_add_f32_e64 v114, v32, 0
	v_add_f32_e64 v115, v33, 0
	v_readlane_b32 s0, v255, 27
	v_add_f32_e64 v32, -v114, neg(0)
	v_add_f32_e64 v33, -v115, neg(0)
	s_mov_b32 s54, 1
	v_lshlrev_b32_e32 v33, 7, v62
	v_mov_b32_e32 v46, v32
	v_mov_b32_e32 v47, v32
	v_mfma_f32_32x32x16_bf16 v[0:15], v[54:57], v[38:41], v[0:15]
	v_mfma_f32_32x32x16_bf16 v[0:15], v[50:53], v[34:37], v[0:15]
	ds_read_b64_tr_b16 v[20:21], v66 offset:16384
	ds_read_b64_tr_b16 v[22:23], v66 offset:16896
	ds_read_b64_tr_b16 v[34:35], v66 offset:17408
	ds_read_b64_tr_b16 v[36:37], v66 offset:17920
	ds_read_b64_tr_b16 v[38:39], v66 offset:18432
	ds_read_b64_tr_b16 v[40:41], v66 offset:18944
	ds_read_b64_tr_b16 v[42:43], v66 offset:19456
	ds_read_b64_tr_b16 v[44:45], v66 offset:19968
	s_waitcnt lgkmcnt(6)
	v_mfma_f32_32x32x16_bf16 v[16:31], v[16:19], v[20:23], 0
	s_waitcnt lgkmcnt(4)
	v_mfma_f32_32x32x16_bf16 v[16:31], v[58:61], v[34:37], v[16:31]
	v_add3_u32 v34, s0, v65, v64
	v_ashrrev_i32_e32 v35, 31, v34
	v_mov_b64_e32 v[36:37], 0xc000
	v_lshl_add_u64 v[116:117], v[34:35], 1, v[36:37]
	v_add3_u32 v34, s16, v33, v63
	v_ashrrev_i32_e32 v35, 31, v34
	v_lshl_add_u64 v[118:119], v[34:35], 1, v[36:37]
	s_waitcnt lgkmcnt(2)
	v_mfma_f32_32x32x16_bf16 v[16:31], v[54:57], v[38:41], v[16:31]
	v_mov_b32_e32 v33, v32
	v_mov_b32_e32 v34, v32
	v_mov_b32_e32 v35, v32
	v_mov_b32_e32 v36, v32
	v_mov_b32_e32 v37, v32
	v_mov_b32_e32 v38, v32
	v_mov_b32_e32 v39, v32
	s_waitcnt lgkmcnt(0)
	v_mfma_f32_32x32x16_bf16 v[16:31], v[50:53], v[42:45], v[16:31]
	v_mov_b32_e32 v40, v32
	v_mov_b32_e32 v41, v32
	v_mov_b32_e32 v42, v32
	v_mov_b32_e32 v43, v32
	v_mov_b32_e32 v44, v32
	v_mov_b32_e32 v45, v32
	s_add_i32 s50, s54, 1
	s_cmp_ge_u32 s50, s36
	s_mov_b64 s[44:45], -1
	s_cbranch_scc0 .LBB0_292
	s_branch .LBB0_291

.LBB0_303:
	s_or_b64 exec, exec, s[40:41]
	s_ashr_i32 s0, s3, 8
	s_add_i32 s0, s0, s79
	s_lshl_b32 s40, s0, 2
	s_ashr_i32 s41, s40, 31
	s_and_saveexec_b64 s[44:45], s[42:43]
	s_cbranch_execz .LBB0_315
	s_lshl_b64 s[36:37], s[40:41], 2
	v_readlane_b32 s0, v255, 10
	s_add_u32 s48, s0, s36
	v_readlane_b32 s0, v255, 11
	s_addc_u32 s49, s0, s37
	s_waitcnt lgkmcnt(0)
	v_mov_b64_e32 v[32:33], s[48:49]
	global_load_dword v32, v[32:33], off sc1
	s_waitcnt vmcnt(0) lgkmcnt(0)
	v_cmp_gt_u32_e32 vcc, 4, v32
	s_and_b64 exec, exec, vcc
	s_cbranch_execz .LBB0_315
	s_mov_b32 s0, 1
	s_mov_b64 s[52:53], 0
	s_branch .LBB0_307

.LBB0_307:
	s_and_b32 s2, s0, 0xff
	s_mov_b64 s[64:65], -1
	s_cmp_lg_u32 s2, 0
	s_mov_b64 s[66:67], -1
	s_sleep 1
	s_cbranch_scc1 .LBB0_311
	v_mov_b64_e32 v[32:33], s[14:15]
	global_load_dword v32, v[32:33], off sc1
	s_mov_b64 s[66:67], 0
	s_mov_b64 s[90:91], -1
	s_waitcnt vmcnt(0) lgkmcnt(0)
	v_cmp_eq_u32_e32 vcc, 0, v32
	s_and_saveexec_b64 s[92:93], vcc
	s_cmp_lt_u32 s0, 0x100001
	s_cselect_b64 s[36:37], -1, 0
	s_xor_b64 s[90:91], exec, -1
	s_and_b64 s[66:67], s[36:37], exec
	s_or_b64 exec, exec, s[92:93]
.LBB0_311:
	s_andn2_b64 s[36:37], s[58:59], exec
	s_and_b64 s[54:55], s[90:91], exec
	s_or_b64 s[58:59], s[36:37], s[54:55]
	s_and_saveexec_b64 s[90:91], s[66:67]
	s_cbranch_execz .LBB0_306
	v_mov_b64_e32 v[32:33], s[48:49]
	global_load_dword v32, v[32:33], off sc1
	s_add_i32 s0, s0, 1
	s_or_b64 s[58:59], s[58:59], exec
	s_waitcnt vmcnt(0) lgkmcnt(0)
	v_cmp_lt_u32_e32 vcc, 3, v32
	s_orn2_b64 s[64:65], vcc, exec
	s_branch .LBB0_306
.LBB0_313:
	s_or_b64 exec, exec, s[52:53]
	s_xor_b64 s[36:37], s[56:57], -1
	s_and_saveexec_b64 s[48:49], s[36:37]
	s_mov_b64 s[66:67], 0x4000
	s_xor_b64 s[48:49], exec, s[48:49]
	s_cbranch_execz .LBB0_315
	v_mov_b64_e32 v[32:33], s[14:15]
	global_atomic_add v[32:33], v181, off
.LBB0_315:
	s_or_b64 exec, exec, s[44:45]
	s_lshl_b64 s[36:37], s[40:41], 2
	s_add_u32 s64, s39, s36
	s_addc_u32 s65, s8, s37
	v_ashrrev_i32_e32 v56, 3, v80
	s_add_i32 s3, s3, s51
	v_lshlrev_b32_e32 v33, 3, v80
	s_waitcnt lgkmcnt(0)
	v_add_u32_e32 v32, s3, v56
	v_and_b32_e32 v57, 56, v33
	s_lshl_b64 s[2:3], s[62:63], 1
	v_lshlrev_b32_e32 v80, 1, v57
	v_ashrrev_i32_e32 v33, 31, v32
	s_add_u32 s2, s2, 0x200
	v_lshl_add_u64 v[34:35], s[18:19], 0, v[80:81]
	v_lshlrev_b64 v[54:55], 11, v[32:33]
	s_addc_u32 s3, s3, 0
	v_lshl_add_u64 v[36:37], v[34:35], 0, v[54:55]
	v_lshl_add_u64 v[36:37], v[36:37], 0, s[2:3]
	s_barrier
	global_load_dwordx4 v[44:47], v[36:37], off
	v_add_u32_e32 v36, 8, v32
	v_ashrrev_i32_e32 v37, 31, v36
	v_lshlrev_b64 v[52:53], 11, v[36:37]
	v_lshl_add_u64 v[36:37], v[34:35], 0, v[52:53]
	v_lshl_add_u64 v[36:37], v[36:37], 0, s[2:3]
	global_load_dwordx4 v[40:43], v[36:37], off
	v_add_u32_e32 v36, 16, v32
	v_ashrrev_i32_e32 v37, 31, v36
	v_lshlrev_b64 v[50:51], 11, v[36:37]
	v_lshl_add_u64 v[36:37], v[34:35], 0, v[50:51]
	v_lshl_add_u64 v[36:37], v[36:37], 0, s[2:3]
	global_load_dwordx4 v[36:39], v[36:37], off
	v_add_u32_e32 v32, 24, v32
	v_ashrrev_i32_e32 v33, 31, v32
	v_lshlrev_b64 v[48:49], 11, v[32:33]
	v_lshl_add_u64 v[32:33], v[34:35], 0, v[48:49]
	v_lshl_add_u64 v[32:33], v[32:33], 0, s[2:3]
	global_load_dwordx4 v[32:35], v[32:33], off
	s_movk_i32 s0, 0x440
	v_lshlrev_b32_e32 v58, 2, v121
	v_mul_lo_u32 v59, v120, s0
	v_add3_u32 v58, s9, v58, v59
	ds_write2_b32 v58, v0, v16 offset1:32
	ds_write2_b32 v58, v1, v17 offset0:68 offset1:100
	ds_write2_b32 v58, v2, v18 offset0:136 offset1:168
	ds_write2_b32 v58, v3, v19 offset0:204 offset1:236
	v_add_u32_e32 v0, 0x800, v58
	ds_write2_b32 v0, v4, v20 offset0:32 offset1:64
	ds_write2_b32 v0, v5, v21 offset0:100 offset1:132
	ds_write2_b32 v0, v6, v22 offset0:168 offset1:200
	v_add_u32_e32 v0, 0xa00, v58
	ds_write2_b32 v0, v7, v23 offset0:108 offset1:140
	v_add_u32_e32 v0, 0x1000, v58
	ds_write2_b32 v0, v8, v24 offset0:64 offset1:96
	ds_write2_b32 v0, v9, v25 offset0:132 offset1:164
	ds_write2_b32 v0, v10, v26 offset0:200 offset1:232
	v_add_u32_e32 v0, 0x1400, v58
	ds_write2_b32 v0, v11, v27 offset0:12 offset1:44
	v_add_u32_e32 v0, 0x1800, v58
	ds_write2_b32 v0, v12, v28 offset0:96 offset1:128
	ds_write2_b32 v0, v13, v29 offset0:164 offset1:196
	v_add_u32_e32 v0, 0x1a00, v58
	ds_write2_b32 v0, v14, v30 offset0:104 offset1:136
	v_add_u32_e32 v0, 0x1c00, v58
	ds_write2_b32 v0, v15, v31 offset0:44 offset1:76
	v_lshlrev_b32_e32 v0, 2, v57
	v_mul_lo_u32 v1, v56, s77
	v_add3_u32 v9, s9, v0, v1
	v_lshl_add_u32 v12, v56, 2, s6
	s_waitcnt lgkmcnt(0)
	ds_read_b128 v[4:7], v9
	ds_read_b128 v[0:3], v9 offset:16
	ds_read_b32 v8, v12
	s_mov_b64 s[0:1], 0x200
	s_mov_b64 s[40:41], s[42:43]
	s_waitcnt lgkmcnt(0)
	v_pk_mul_f32 v[4:5], v[4:5], v[8:9] op_sel_hi:[1,0]
	v_pk_mul_f32 v[6:7], v[6:7], v[8:9] op_sel_hi:[1,0]
	v_pk_mul_f32 v[0:1], v[0:1], v[8:9] op_sel_hi:[1,0]
	s_waitcnt vmcnt(0)
	v_lshlrev_b32_e32 v10, 16, v44
	v_and_b32_e32 v11, 0xffff0000, v44
	v_pk_mul_f32 v[4:5], v[4:5], v[10:11]
	v_lshlrev_b32_e32 v10, 16, v45
	v_and_b32_e32 v11, 0xffff0000, v45
	v_pk_mul_f32 v[6:7], v[6:7], v[10:11]
	v_cvt_pk_bf16_f32 v4, v4, v5
	v_cvt_pk_bf16_f32 v5, v6, v7
	v_lshlrev_b32_e32 v6, 16, v46
	v_and_b32_e32 v7, 0xffff0000, v46
	v_pk_mul_f32 v[0:1], v[0:1], v[6:7]
	v_lshlrev_b32_e32 v10, 16, v40
	v_cvt_pk_bf16_f32 v6, v0, v1
	v_pk_mul_f32 v[0:1], v[2:3], v[8:9] op_sel_hi:[1,0]
	v_lshlrev_b32_e32 v2, 16, v47
	v_and_b32_e32 v3, 0xffff0000, v47
	v_pk_mul_f32 v[0:1], v[0:1], v[2:3]
	v_and_b32_e32 v11, 0xffff0000, v40
	v_cvt_pk_bf16_f32 v7, v0, v1
	v_lshl_add_u64 v[0:1], s[26:27], 0, v[54:55]
	v_lshl_add_u64 v[0:1], v[0:1], 0, s[46:47]
	v_lshl_add_u64 v[0:1], v[0:1], 0, v[80:81]
	v_lshl_add_u64 v[0:1], v[0:1], 0, s[0:1]
	global_store_dwordx4 v[0:1], v[4:7], off sc1
	s_nop 1
	ds_read_b128 v[0:3], v9 offset:2176
	ds_read_b128 v[4:7], v9 offset:2192
	ds_read_b32 v8, v12 offset:32
	s_waitcnt lgkmcnt(0)
	v_pk_mul_f32 v[0:1], v[0:1], v[8:9] op_sel_hi:[1,0]
	s_nop 0
	v_pk_mul_f32 v[0:1], v[0:1], v[10:11]
	v_pk_mul_f32 v[2:3], v[2:3], v[8:9] op_sel_hi:[1,0]
	v_lshlrev_b32_e32 v10, 16, v41
	v_and_b32_e32 v11, 0xffff0000, v41
	v_pk_mul_f32 v[2:3], v[2:3], v[10:11]
	v_cvt_pk_bf16_f32 v0, v0, v1
	v_cvt_pk_bf16_f32 v1, v2, v3
	v_pk_mul_f32 v[2:3], v[4:5], v[8:9] op_sel_hi:[1,0]
	v_lshlrev_b32_e32 v4, 16, v42
	v_and_b32_e32 v5, 0xffff0000, v42
	v_pk_mul_f32 v[2:3], v[2:3], v[4:5]
	v_pk_mul_f32 v[4:5], v[6:7], v[8:9] op_sel_hi:[1,0]
	v_lshlrev_b32_e32 v6, 16, v43
	v_and_b32_e32 v7, 0xffff0000, v43
	v_pk_mul_f32 v[4:5], v[4:5], v[6:7]
	v_cvt_pk_bf16_f32 v2, v2, v3
	v_cvt_pk_bf16_f32 v3, v4, v5
	v_lshl_add_u64 v[4:5], s[26:27], 0, v[52:53]
	v_lshl_add_u64 v[4:5], v[4:5], 0, s[46:47]
	v_lshl_add_u64 v[4:5], v[4:5], 0, v[80:81]
	v_lshl_add_u64 v[4:5], v[4:5], 0, s[0:1]
	global_store_dwordx4 v[4:5], v[0:3], off sc1
	s_nop 1
	ds_read_b128 v[0:3], v9 offset:4352
	ds_read_b128 v[4:7], v9 offset:4368
	ds_read_b32 v8, v12 offset:64
	v_lshlrev_b32_e32 v10, 16, v36
	v_and_b32_e32 v11, 0xffff0000, v36
	s_waitcnt lgkmcnt(0)
	v_pk_mul_f32 v[0:1], v[0:1], v[8:9] op_sel_hi:[1,0]
	s_nop 0
	v_pk_mul_f32 v[0:1], v[0:1], v[10:11]
	v_pk_mul_f32 v[2:3], v[2:3], v[8:9] op_sel_hi:[1,0]
	v_lshlrev_b32_e32 v10, 16, v37
	v_and_b32_e32 v11, 0xffff0000, v37
	v_pk_mul_f32 v[2:3], v[2:3], v[10:11]
	v_cvt_pk_bf16_f32 v0, v0, v1
	v_cvt_pk_bf16_f32 v1, v2, v3
	v_pk_mul_f32 v[2:3], v[4:5], v[8:9] op_sel_hi:[1,0]
	v_lshlrev_b32_e32 v4, 16, v38
	v_and_b32_e32 v5, 0xffff0000, v38
	v_pk_mul_f32 v[2:3], v[2:3], v[4:5]
	v_pk_mul_f32 v[4:5], v[6:7], v[8:9] op_sel_hi:[1,0]
	v_lshlrev_b32_e32 v6, 16, v39
	v_and_b32_e32 v7, 0xffff0000, v39
	v_pk_mul_f32 v[4:5], v[4:5], v[6:7]
	v_cvt_pk_bf16_f32 v2, v2, v3
	v_cvt_pk_bf16_f32 v3, v4, v5
	v_lshl_add_u64 v[4:5], s[26:27], 0, v[50:51]
	v_lshl_add_u64 v[4:5], v[4:5], 0, s[46:47]
	v_lshl_add_u64 v[4:5], v[4:5], 0, v[80:81]
	v_lshl_add_u64 v[4:5], v[4:5], 0, s[0:1]
	global_store_dwordx4 v[4:5], v[0:3], off sc1
	s_nop 1
	ds_read_b128 v[0:3], v9 offset:6528
	ds_read_b128 v[4:7], v9 offset:6544
	ds_read_b32 v8, v12 offset:96
	v_lshlrev_b32_e32 v10, 16, v32
	v_and_b32_e32 v11, 0xffff0000, v32
	s_waitcnt lgkmcnt(0)
	v_pk_mul_f32 v[0:1], v[0:1], v[8:9] op_sel_hi:[1,0]
	s_nop 0
	v_pk_mul_f32 v[0:1], v[0:1], v[10:11]
	v_pk_mul_f32 v[2:3], v[2:3], v[8:9] op_sel_hi:[1,0]
	v_lshlrev_b32_e32 v10, 16, v33
	v_and_b32_e32 v11, 0xffff0000, v33
	v_pk_mul_f32 v[2:3], v[2:3], v[10:11]
	v_cvt_pk_bf16_f32 v0, v0, v1
	v_cvt_pk_bf16_f32 v1, v2, v3
	v_pk_mul_f32 v[2:3], v[4:5], v[8:9] op_sel_hi:[1,0]
	v_lshlrev_b32_e32 v4, 16, v34
	v_and_b32_e32 v5, 0xffff0000, v34
	v_pk_mul_f32 v[2:3], v[2:3], v[4:5]
	v_pk_mul_f32 v[4:5], v[6:7], v[8:9] op_sel_hi:[1,0]
	v_lshlrev_b32_e32 v6, 16, v35
	v_and_b32_e32 v7, 0xffff0000, v35
	v_pk_mul_f32 v[4:5], v[4:5], v[6:7]
	v_cvt_pk_bf16_f32 v2, v2, v3
	v_cvt_pk_bf16_f32 v3, v4, v5
	v_lshl_add_u64 v[4:5], s[26:27], 0, v[48:49]
	v_lshl_add_u64 v[4:5], v[4:5], 0, s[46:47]
	v_lshl_add_u64 v[4:5], v[4:5], 0, v[80:81]
	v_lshl_add_u64 v[4:5], v[4:5], 0, s[0:1]
	global_store_dwordx4 v[4:5], v[0:3], off sc1
	s_nop 1
	s_waitcnt vmcnt(0)
	s_barrier

.LBB0_327:
	s_mov_b64 s[92:93], 0
	s_and_saveexec_b64 s[90:91], s[40:41]
	s_cbranch_execz .LBB0_329
	global_load_dword v3, v[0:1], off sc1
	s_waitcnt vmcnt(0) lgkmcnt(0)
	v_cmp_lt_u32_e32 vcc, v3, v2
	s_and_b64 s[92:93], vcc, exec

.LBB0_333:
	v_mov_b64_e32 v[4:5], s[14:15]
	global_load_dword v3, v[4:5], off sc1
	s_mov_b64 s[94:95], 0
	s_waitcnt vmcnt(0) lgkmcnt(0)
	v_cmp_eq_u32_e32 vcc, 0, v3
	s_and_saveexec_b64 s[96:97], vcc
	s_cmp_lt_u32 s0, 0x100001
	s_cselect_b64 s[54:55], -1, 0
	s_xor_b64 s[92:93], exec, -1
	s_and_b64 s[94:95], s[54:55], exec
	s_or_b64 exec, exec, s[96:97]
	s_and_saveexec_b64 s[96:97], s[94:95]
	s_cbranch_execz .LBB0_325

.LBB0_340:
	s_min_i32 s0, s5, 0x60
	s_lshl_b32 s0, s0, 8
	s_and_b32 s0, s0, 0x300
	s_add_i32 s5, s58, s0
	s_mul_i32 s11, s5, 0x480
	v_readlane_b32 s1, v254, 28
	s_mul_hi_i32 s0, s5, 0x480
	s_add_u32 s33, s1, s11
	v_readlane_b32 s1, v254, 30
	s_mul_i32 s40, s2, 0x60
	s_addc_u32 s0, s1, s0
	s_ashr_i32 s41, s40, 31
	s_lshl_b64 s[40:41], s[40:41], 1
	s_add_u32 s40, s33, s40
	v_mov_b32_e32 v80, v188
	s_addc_u32 s41, s0, s41
	s_waitcnt lgkmcnt(0)
	s_barrier
	v_readlane_b32 s0, v255, 19
	v_and_b32_e32 v131, 31, v80
	v_ashrrev_i32_e32 v76, 2, v80
	v_ashrrev_i32_e32 v130, 5, v80
	v_add_u32_e32 v6, s0, v76
	v_or_b32_e32 v4, s51, v131
	v_mov_b64_e32 v[2:3], s[40:41]
	s_movk_i32 s0, 0x480
	v_mad_i64_i32 v[2:3], s[40:41], v4, s0, v[2:3]
	v_lshlrev_b32_e32 v4, 3, v130
	v_ashrrev_i32_e32 v5, 31, v4
	v_lshl_add_u64 v[2:3], v[4:5], 1, v[2:3]
	global_load_dwordx4 v[82:85], v[2:3], off
	global_load_dwordx4 v[86:89], v[2:3], off offset:32
	global_load_dwordx4 v[90:93], v[2:3], off offset:64
	global_load_dwordx4 v[94:97], v[2:3], off offset:96
	global_load_dwordx4 v[98:101], v[2:3], off offset:128
	global_load_dwordx4 v[102:105], v[2:3], off offset:160
	v_ashrrev_i32_e32 v74, 3, v80
	v_add_u32_e32 v1, s10, v74
	v_lshrrev_b32_e32 v0, 1, v1
	v_xor_b32_e32 v0, v0, v80
	v_lshlrev_b32_e32 v0, 3, v0
	v_ashrrev_i32_e32 v7, 4, v80
	v_and_b32_e32 v75, 56, v0
	v_xor_b32_e32 v0, v7, v80
	v_lshlrev_b32_e32 v0, 3, v0
	v_and_b32_e32 v78, 24, v0
	v_lshlrev_b32_e32 v0, 3, v80
	v_and_b32_e32 v77, 24, v0
	s_movk_i32 s50, 0x300
	v_or_b32_e32 v0, s81, v77
	s_or_b32 s33, s3, s36
	v_mul_lo_u32 v1, v1, s50
	s_sub_i32 s0, 0, s3
	v_or_b32_e32 v2, v75, v1
	v_mad_u64_u32 v[0:1], s[40:41], v6, s50, v[0:1]
	s_and_b64 s[40:41], s[28:29], exec
	s_cselect_b32 s40, 0, s0
	s_ashr_i32 s41, s40, 31
	s_mul_i32 s37, s40, 0x18000
	s_mul_hi_i32 s0, s40, 0x18000
	s_add_u32 s54, s48, s37
	s_addc_u32 s55, s49, s0
	s_add_u32 s58, s52, s37
	v_lshl_or_b32 v4, v6, 5, v78
	s_addc_u32 s59, s53, s0
	v_ashrrev_i32_e32 v3, 31, v2
	s_lshl_b64 s[40:41], s[40:41], 12
	v_lshlrev_b64 v[68:69], 1, v[2:3]
	s_add_u32 s40, s56, s40
	v_ashrrev_i32_e32 v5, 31, v4
	v_lshl_add_u64 v[2:3], s[54:55], 0, v[68:69]
	s_mov_b32 s0, m0
	s_mov_b32 m0, s17
	s_nop 0
	global_load_lds_dwordx4 v[2:3], off
	s_mov_b32 m0, s0
	s_addc_u32 s41, s57, s41
	v_lshlrev_b64 v[70:71], 1, v[4:5]
	v_ashrrev_i32_e32 v1, 31, v0
	v_lshl_add_u64 v[2:3], s[40:41], 0, v[70:71]
	s_mov_b32 s0, m0
	s_mov_b32 m0, s7
	s_nop 0
	global_load_lds_dwordx4 v[2:3], off
	s_mov_b32 m0, s0
	v_lshlrev_b64 v[72:73], 1, v[0:1]
	v_lshl_add_u64 v[0:1], s[58:59], 0, v[72:73]
	s_mov_b32 s0, m0
	s_mov_b32 m0, s38
	s_nop 0
	global_load_lds_dwordx4 v[0:1], off
	s_mov_b32 m0, s0
	s_sub_i32 s0, 1, s3
	s_and_b64 s[40:41], s[28:29], exec
	s_cselect_b32 s40, 1, s0
	s_ashr_i32 s41, s40, 31
	s_mul_i32 s37, s40, 0x18000
	s_mul_hi_i32 s0, s40, 0x18000
	s_add_u32 s54, s48, s37
	s_addc_u32 s55, s49, s0
	s_add_u32 s58, s52, s37
	v_readlane_b32 s1, v253, 62
	s_addc_u32 s59, s53, s0
	s_add_i32 s0, s16, s1
	s_lshl_b64 s[40:41], s[40:41], 12
	s_add_u32 s40, s56, s40
	v_lshl_add_u64 v[0:1], s[54:55], 0, v[68:69]
	s_addc_u32 s41, s57, s41
	s_mov_b32 s37, m0
	s_mov_b32 m0, s0
	s_nop 0
	global_load_lds_dwordx4 v[0:1], off
	s_mov_b32 m0, s37
	v_readlane_b32 s0, v255, 20
	v_lshl_add_u64 v[0:1], s[40:41], 0, v[70:71]
	s_addk_i32 s0, 0x7000
	s_mov_b32 s37, m0
	s_mov_b32 m0, s0
	s_nop 0
	global_load_lds_dwordx4 v[0:1], off
	s_mov_b32 m0, s37
	v_lshl_add_u64 v[0:1], s[58:59], 0, v[72:73]
	s_add_i32 s0, s80, s1
	s_mov_b32 s37, m0
	s_mov_b32 m0, s0
	s_nop 0
	global_load_lds_dwordx4 v[0:1], off
	s_mov_b32 m0, s37
	v_lshlrev_b32_e32 v0, 4, v80
	v_and_b32_e32 v0, 0xc0, v0
	v_lshrrev_b32_e32 v4, 1, v80
	v_lshl_or_b32 v40, v130, 8, v0
	v_lshlrev_b32_e32 v0, 5, v7
	v_lshlrev_b32_e32 v132, 7, v131
	v_and_b32_e32 v41, 32, v0
	v_bitop3_b32 v0, v4, v130, 7 bitop3:0x6c
	v_add_u32_e32 v5, 0, v132
	v_lshlrev_b32_e32 v136, 4, v0
	s_waitcnt vmcnt(3)
	s_barrier
	v_add_u32_e32 v6, v5, v136
	ds_read_b128 v[0:3], v6
	ds_read_b128 v[16:19], v6 offset:4096
	v_add_u32_e32 v6, 2, v130
	v_bitop3_b32 v7, v6, v4, 7 bitop3:0x78
	v_lshlrev_b32_e32 v137, 4, v7
	v_add_u32_e32 v7, v5, v137
	ds_read_b128 v[20:23], v7
	ds_read_b128 v[56:59], v7 offset:4096
	v_add_u32_e32 v7, 4, v130
	v_bitop3_b32 v7, v7, v4, 7 bitop3:0x78
	v_lshlrev_b32_e32 v138, 4, v7
	v_add_u32_e32 v7, v5, v138
	ds_read_b128 v[24:27], v7
	ds_read_b128 v[64:67], v7 offset:4096
	v_add_u32_e32 v7, 6, v130
	v_bitop3_b32 v4, v7, v4, 7 bitop3:0x78
	v_lshlrev_b32_e32 v139, 4, v4
	v_lshlrev_b32_e32 v133, 6, v131
	v_add_u32_e32 v4, v5, v139
	ds_read_b128 v[28:31], v4
	ds_read_b128 v[60:63], v4 offset:4096
	v_sub_u32_e32 v4, v5, v133
	v_bitop3_b32 v5, v76, v130, 3 bitop3:0x6c
	v_lshlrev_b32_e32 v140, 4, v5
	v_add_u32_e32 v5, v4, v140
	ds_read_b128 v[32:35], v5 offset:8192
	ds_read_b128 v[52:55], v5 offset:10240
	v_bitop3_b32 v5, v6, v76, 3 bitop3:0x78
	v_lshlrev_b32_e32 v141, 4, v5
	v_add_u32_e32 v4, v4, v141
	ds_read_b128 v[36:39], v4 offset:8192
	ds_read_b128 v[48:51], v4 offset:10240
	s_waitcnt vmcnt(0) lgkmcnt(0)
	v_mfma_f32_32x32x16_bf16 v[0:15], v[0:3], v[82:85], 0
	s_sub_i32 s0, 2, s3
	s_and_b64 s[28:29], s[28:29], exec
	s_cselect_b32 s28, 2, s0
	s_ashr_i32 s29, s28, 31
	s_mul_i32 s37, s28, 0x18000
	s_mul_hi_i32 s0, s28, 0x18000
	s_add_u32 s54, s48, s37
	v_mfma_f32_32x32x16_bf16 v[0:15], v[20:23], v[86:89], v[0:15]
	s_addc_u32 s55, s49, s0
	s_add_u32 s58, s52, s37
	s_addc_u32 s59, s53, s0
	s_add_i32 s0, s17, 0xa000
	s_lshl_b64 s[28:29], s[28:29], 12
	v_or3_b32 v142, v40, v41, v77
	s_add_u32 s28, s56, s28
	v_mfma_f32_32x32x16_bf16 v[0:15], v[24:27], v[90:93], v[0:15]
	v_add_u32_e32 v79, 0, v142
	s_addc_u32 s29, s57, s29
	s_mov_b32 s11, 1
	v_cmp_gt_u32_e64 s[40:41], 32, v80
	v_lshl_add_u32 v134, v131, 2, s6
	v_lshl_add_u32 v135, v130, 4, s6
	s_add_i32 s36, s3, s36
	v_mfma_f32_32x32x16_bf16 v[0:15], v[28:31], v[94:97], v[0:15]
	v_mfma_f32_32x32x16_bf16 v[16:31], v[16:19], v[82:85], 0
	v_mfma_f32_32x32x16_bf16 v[16:31], v[56:59], v[86:89], v[16:31]
	v_mfma_f32_32x32x16_bf16 v[16:31], v[64:67], v[90:93], v[16:31]
	v_mfma_f32_32x32x16_bf16 v[0:15], v[32:35], v[98:101], v[0:15]
	v_mfma_f32_32x32x16_bf16 v[16:31], v[60:63], v[94:97], v[16:31]
	v_mfma_f32_32x32x16_bf16 v[0:15], v[36:39], v[102:105], v[0:15]
	ds_read_b64_tr_b16 v[44:45], v79 offset:12288
	ds_read_b64_tr_b16 v[46:47], v79 offset:12800
	ds_read_b64_tr_b16 v[40:41], v79 offset:13312
	ds_read_b64_tr_b16 v[42:43], v79 offset:13824
	ds_read_b64_tr_b16 v[36:37], v79 offset:14336
	ds_read_b64_tr_b16 v[38:39], v79 offset:14848
	ds_read_b64_tr_b16 v[32:33], v79 offset:15360
	ds_read_b64_tr_b16 v[34:35], v79 offset:15872
	v_mfma_f32_32x32x16_bf16 v[16:31], v[52:55], v[98:101], v[16:31]
	v_mfma_f32_32x32x16_bf16 v[16:31], v[48:51], v[102:105], v[16:31]
	s_nop 1
	v_max_f32_e32 v48, v1, v1
	v_max_f32_e32 v49, v0, v0
	v_max_f32_e32 v48, v49, v48
	v_max3_f32 v48, v48, v2, v3
	v_max3_f32 v48, v48, v4, v5
	v_max3_f32 v48, v48, v6, v7
	v_max3_f32 v48, v48, v8, v9
	v_max3_f32 v48, v48, v10, v11
	v_max3_f32 v48, v48, v12, v13
	v_max3_f32 v48, v48, v14, v15
	v_max3_f32 v48, v48, v16, v17
	v_max3_f32 v48, v48, v18, v19
	v_max3_f32 v48, v48, v20, v21
	v_max3_f32 v48, v48, v22, v23
	v_max3_f32 v48, v48, v24, v25
	v_max3_f32 v48, v48, v26, v27
	v_max3_f32 v48, v48, v28, v29
	v_max3_f32 v48, v48, v30, v31
	ds_bpermute_b32 v49, v219, v48
	s_waitcnt lgkmcnt(0)
	v_max_f32_e32 v49, v49, v49
	v_max_f32_e32 v48, v48, v49
	v_sub_f32_e32 v16, v16, v48
	v_sub_f32_e32 v0, v0, v48
	v_sub_f32_e32 v17, v17, v48
	v_sub_f32_e32 v1, v1, v48
	v_exp_f32_e32 v60, v0
	v_exp_f32_e32 v61, v16
	v_sub_f32_e32 v18, v18, v48
	v_sub_f32_e32 v2, v2, v48
	v_exp_f32_e32 v62, v1
	v_exp_f32_e32 v63, v17
	v_sub_f32_e32 v19, v19, v48
	v_sub_f32_e32 v3, v3, v48
	v_exp_f32_e32 v64, v2
	v_exp_f32_e32 v65, v18
	v_exp_f32_e32 v66, v3
	v_exp_f32_e32 v67, v19
	v_add_f32_e32 v0, v61, v60
	v_add_f32_e32 v0, 0, v0
	v_add_f32_e32 v1, v63, v62
	v_add_f32_e32 v0, v1, v0
	v_add_f32_e32 v1, v65, v64
	v_sub_f32_e32 v20, v20, v48
	v_sub_f32_e32 v21, v21, v48
	v_sub_f32_e32 v49, v30, v48
	v_sub_f32_e32 v4, v4, v48
	v_sub_f32_e32 v30, v5, v48
	v_add_f32_e32 v0, v1, v0
	v_add_f32_e32 v1, v67, v66
	v_add_f32_e32 v2, v1, v0
	v_exp_f32_e32 v1, v4
	v_exp_f32_e32 v5, v20
	v_exp_f32_e32 v0, v30
	v_exp_f32_e32 v4, v21
	v_sub_f32_e32 v50, v31, v48
	v_sub_f32_e32 v31, v6, v48
	v_sub_f32_e32 v51, v7, v48
	v_pk_add_f32 v[6:7], v[4:5], v[0:1]
	v_sub_f32_e32 v22, v22, v48
	v_sub_f32_e32 v23, v23, v48
	v_add_f32_e32 v7, v7, v2
	v_sub_f32_e32 v54, v10, v48
	v_pk_mov_b32 v[2:3], v[0:1], v[0:1] op_sel:[1,0]
	v_pk_mov_b32 v[0:1], v[4:5], v[4:5] op_sel:[1,0]
	v_add_f32_e32 v10, v6, v7
	v_exp_f32_e32 v5, v31
	v_exp_f32_e32 v7, v22
	v_exp_f32_e32 v4, v51
	v_exp_f32_e32 v6, v23
	v_sub_f32_e32 v52, v8, v48
	v_sub_f32_e32 v53, v9, v48
	v_sub_f32_e32 v24, v24, v48
	v_pk_add_f32 v[8:9], v[6:7], v[4:5]
	v_sub_f32_e32 v25, v25, v48
	v_add_f32_e32 v9, v9, v10
	v_sub_f32_e32 v55, v11, v48
	v_sub_f32_e32 v58, v14, v48
	v_pk_mov_b32 v[10:11], v[4:5], v[4:5] op_sel:[1,0]
	v_pk_mov_b32 v[4:5], v[6:7], v[6:7] op_sel:[1,0]
	v_add_f32_e32 v14, v8, v9
	v_exp_f32_e32 v7, v52
	v_exp_f32_e32 v9, v24
	v_exp_f32_e32 v6, v53
	v_exp_f32_e32 v8, v25
	v_sub_f32_e32 v56, v12, v48
	v_sub_f32_e32 v57, v13, v48
	v_sub_f32_e32 v26, v26, v48
	v_pk_add_f32 v[12:13], v[8:9], v[6:7]
	v_sub_f32_e32 v27, v27, v48
	v_add_f32_e32 v13, v13, v14
	v_sub_f32_e32 v59, v15, v48
	v_add_f32_e32 v18, v12, v13
	v_exp_f32_e32 v13, v54
	v_exp_f32_e32 v15, v26
	v_exp_f32_e32 v12, v55
	v_exp_f32_e32 v14, v27
	v_sub_f32_e32 v28, v28, v48
	v_sub_f32_e32 v29, v29, v48
	v_exp_f32_e32 v19, v28
	v_pk_add_f32 v[16:17], v[14:15], v[12:13]
	v_cvt_pk_bf16_f32 v51, v10, v11
	v_add_f32_e32 v17, v17, v18
	v_add_f32_e32 v22, v16, v17
	v_exp_f32_e32 v17, v56
	v_exp_f32_e32 v16, v57
	v_exp_f32_e32 v18, v29
	v_pk_mov_b32 v[6:7], v[6:7], v[6:7] op_sel:[1,0]
	v_pk_mov_b32 v[8:9], v[8:9], v[8:9] op_sel:[1,0]
	v_pk_mov_b32 v[12:13], v[12:13], v[12:13] op_sel:[1,0]
	v_pk_add_f32 v[20:21], v[18:19], v[16:17]
	v_pk_mov_b32 v[30:31], v[18:19], v[18:19] op_sel:[1,0]
	v_add_f32_e32 v21, v21, v22
	v_pk_mov_b32 v[22:23], v[16:17], v[16:17] op_sel:[1,0]
	v_exp_f32_e32 v17, v58
	v_exp_f32_e32 v19, v49
	v_exp_f32_e32 v16, v59
	v_exp_f32_e32 v18, v50
	v_add_f32_e32 v24, v20, v21
	v_cvt_pk_bf16_f32 v50, v2, v3
	v_pk_mov_b32 v[14:15], v[14:15], v[14:15] op_sel:[1,0]
	v_pk_add_f32 v[20:21], v[18:19], v[16:17]
	v_pk_mov_b32 v[52:53], v[18:19], v[18:19] op_sel:[1,0]
	v_add_f32_e32 v21, v21, v24
	v_add_f32_e32 v49, v20, v21
	v_pk_add_f32 v[122:123], v[48:49], 0 op_sel_hi:[1,0]
	v_cvt_pk_bf16_f32 v48, v60, v62
	v_cvt_pk_bf16_f32 v49, v64, v66
	v_lshl_add_u64 v[18:19], s[54:55], 0, v[68:69]
	s_mov_b32 s37, m0
	s_mov_b32 m0, s0
	s_nop 0
	global_load_lds_dwordx4 v[18:19], off
	s_mov_b32 m0, s37
	v_lshl_add_u64 v[18:19], s[28:29], 0, v[70:71]
	v_pk_mov_b32 v[24:25], v[16:17], v[16:17] op_sel:[1,0]
	s_add_i32 s0, s7, 0xa000
	s_mov_b32 s28, m0
	s_mov_b32 m0, s0
	s_nop 0
	global_load_lds_dwordx4 v[18:19], off
	s_mov_b32 m0, s28
	v_lshl_add_u64 v[18:19], s[58:59], 0, v[72:73]
	s_add_i32 s0, s38, 0xa000
	s_mov_b32 s28, m0
	s_mov_b32 m0, s0
	s_nop 0
	global_load_lds_dwordx4 v[18:19], off
	s_mov_b32 m0, s28
	v_cvt_pk_bf16_f32 v26, v6, v7
	v_cvt_pk_bf16_f32 v27, v12, v13
	v_cvt_pk_bf16_f32 v29, v24, v25
	v_cvt_pk_bf16_f32 v24, v0, v1
	v_cvt_pk_bf16_f32 v25, v4, v5
	v_cvt_pk_bf16_f32 v18, v8, v9
	v_cvt_pk_bf16_f32 v19, v14, v15
	v_mfma_f32_32x32x16_bf16 v[0:15], v[48:51], v[44:47], 0
	v_cvt_pk_bf16_f32 v28, v22, v23
	v_cvt_pk_bf16_f32 v22, v61, v63
	v_cvt_pk_bf16_f32 v23, v65, v67
	v_cvt_pk_bf16_f32 v20, v30, v31
	v_cvt_pk_bf16_f32 v21, v52, v53
	v_pk_add_f32 v[16:17], v[122:123], 0 neg_lo:[1,1] neg_hi:[1,1]
	v_readlane_b32 s0, v255, 29
	v_mfma_f32_32x32x16_bf16 v[0:15], v[26:29], v[40:43], v[0:15]
	v_lshlrev_b32_e32 v17, 5, v76
	v_mfma_f32_32x32x16_bf16 v[0:15], v[22:25], v[36:39], v[0:15]
	v_mfma_f32_32x32x16_bf16 v[0:15], v[18:21], v[32:35], v[0:15]
	ds_read_b64_tr_b16 v[30:31], v79 offset:16384
	ds_read_b64_tr_b16 v[32:33], v79 offset:16896
	ds_read_b64_tr_b16 v[52:53], v79 offset:17408
	ds_read_b64_tr_b16 v[54:55], v79 offset:17920
	ds_read_b64_tr_b16 v[56:57], v79 offset:18432
	ds_read_b64_tr_b16 v[58:59], v79 offset:18944
	ds_read_b64_tr_b16 v[60:61], v79 offset:19456
	ds_read_b64_tr_b16 v[62:63], v79 offset:19968
	s_waitcnt lgkmcnt(6)
	v_mfma_f32_32x32x16_bf16 v[32:47], v[48:51], v[30:33], 0
	v_mov_b32_e32 v30, v16
	v_mov_b32_e32 v31, v16
	s_waitcnt lgkmcnt(4)
	v_mfma_f32_32x32x16_bf16 v[32:47], v[26:29], v[52:55], v[32:47]
	v_mov_b32_e32 v26, v16
	v_mov_b32_e32 v27, v16
	v_mov_b32_e32 v28, v16
	v_mov_b32_e32 v29, v16
	s_waitcnt lgkmcnt(2)
	v_mfma_f32_32x32x16_bf16 v[32:47], v[22:25], v[56:59], v[32:47]
	v_mov_b32_e32 v22, v16
	v_mov_b32_e32 v23, v16
	v_mov_b32_e32 v24, v16
	v_mov_b32_e32 v25, v16
	s_waitcnt lgkmcnt(0)
	v_mfma_f32_32x32x16_bf16 v[32:47], v[18:21], v[60:63], v[32:47]
	v_add3_u32 v18, s0, v17, v78
	v_ashrrev_i32_e32 v19, 31, v18
	v_mov_b64_e32 v[20:21], 0x3000
	v_mul_lo_u32 v17, v76, s50
	v_readlane_b32 s0, v255, 30
	v_lshl_add_u64 v[124:125], v[18:19], 1, v[20:21]
	v_mov_b32_e32 v20, v16
	v_add3_u32 v18, s0, v17, v77
	v_ashrrev_i32_e32 v19, 31, v18
	v_mul_lo_u32 v17, v74, s50
	s_mul_i32 s0, s73, 0x1800
	v_lshl_add_u64 v[126:127], v[18:19], 1, v[186:187]
	v_add3_u32 v18, s0, v17, v75
	v_ashrrev_i32_e32 v19, 31, v18
	v_lshl_add_u64 v[128:129], v[18:19], 1, v[186:187]
	s_mov_b32 s50, 1
	v_mov_b32_e32 v17, v16
	v_mov_b32_e32 v18, v16
	v_mov_b32_e32 v19, v16
	v_mov_b32_e32 v21, v16
	s_add_i32 s37, s50, 1
	s_cmp_ge_u32 s37, s33
	s_mov_b64 s[28:29], -1
	s_cbranch_scc0 .LBB0_343
	s_branch .LBB0_342

.LBB0_354:
	s_or_b64 exec, exec, s[28:29]
	s_ashr_i32 s0, s5, 8
	s_add_i32 s0, s0, s79
	s_lshl_b32 s28, s0, 2
	s_ashr_i32 s29, s28, 31
	s_lshl_b64 s[28:29], s[28:29], 2
	s_add_u32 s64, s39, s28
	s_addc_u32 s65, s8, s29
	s_lshl_b32 s0, s2, 6
	s_add_i32 s60, s0, 0x280
	v_ashrrev_i32_e32 v56, 3, v80
	s_add_i32 s5, s5, s51
	s_lshl_b64 s[28:29], s[60:61], 1
	v_lshlrev_b32_e32 v17, 3, v80
	s_waitcnt lgkmcnt(0)
	v_add_u32_e32 v16, s5, v56
	s_add_u32 s2, s18, s28
	v_and_b32_e32 v57, 56, v17
	s_addc_u32 s3, s19, s29
	v_lshlrev_b32_e32 v80, 1, v57
	v_ashrrev_i32_e32 v17, 31, v16
	v_lshl_add_u64 v[18:19], s[2:3], 0, v[80:81]
	v_lshlrev_b64 v[54:55], 11, v[16:17]
	v_lshl_add_u64 v[20:21], v[18:19], 0, v[54:55]
	s_barrier
	global_load_dwordx4 v[28:31], v[20:21], off
	v_add_u32_e32 v20, 8, v16
	v_ashrrev_i32_e32 v21, 31, v20
	v_lshlrev_b64 v[52:53], 11, v[20:21]
	v_lshl_add_u64 v[20:21], v[18:19], 0, v[52:53]
	global_load_dwordx4 v[24:27], v[20:21], off
	v_add_u32_e32 v20, 16, v16
	v_ashrrev_i32_e32 v21, 31, v20
	v_lshlrev_b64 v[50:51], 11, v[20:21]
	v_lshl_add_u64 v[20:21], v[18:19], 0, v[50:51]
	global_load_dwordx4 v[20:23], v[20:21], off
	v_add_u32_e32 v16, 24, v16
	v_ashrrev_i32_e32 v17, 31, v16
	v_lshlrev_b64 v[48:49], 11, v[16:17]
	v_lshl_add_u64 v[16:17], v[18:19], 0, v[48:49]
	global_load_dwordx4 v[16:19], v[16:17], off
	s_movk_i32 s0, 0x440
	v_lshlrev_b32_e32 v58, 2, v131
	v_mul_lo_u32 v59, v130, s0
	v_add3_u32 v58, s9, v58, v59
	ds_write2_b32 v58, v0, v32 offset1:32
	ds_write2_b32 v58, v1, v33 offset0:68 offset1:100
	ds_write2_b32 v58, v2, v34 offset0:136 offset1:168
	ds_write2_b32 v58, v3, v35 offset0:204 offset1:236
	v_add_u32_e32 v0, 0x800, v58
	ds_write2_b32 v0, v4, v36 offset0:32 offset1:64
	ds_write2_b32 v0, v5, v37 offset0:100 offset1:132
	ds_write2_b32 v0, v6, v38 offset0:168 offset1:200
	v_add_u32_e32 v0, 0xa00, v58
	ds_write2_b32 v0, v7, v39 offset0:108 offset1:140
	v_add_u32_e32 v0, 0x1000, v58
	ds_write2_b32 v0, v8, v40 offset0:64 offset1:96
	ds_write2_b32 v0, v9, v41 offset0:132 offset1:164
	ds_write2_b32 v0, v10, v42 offset0:200 offset1:232
	v_add_u32_e32 v0, 0x1400, v58
	ds_write2_b32 v0, v11, v43 offset0:12 offset1:44
	v_add_u32_e32 v0, 0x1800, v58
	ds_write2_b32 v0, v12, v44 offset0:96 offset1:128
	ds_write2_b32 v0, v13, v45 offset0:164 offset1:196
	v_add_u32_e32 v0, 0x1a00, v58
	ds_write2_b32 v0, v14, v46 offset0:104 offset1:136
	v_add_u32_e32 v0, 0x1c00, v58
	ds_write2_b32 v0, v15, v47 offset0:44 offset1:76
	v_lshlrev_b32_e32 v0, 2, v57
	v_mul_lo_u32 v1, v56, s77
	v_add3_u32 v9, s9, v0, v1
	v_lshl_add_u32 v12, v56, 2, s6
	s_waitcnt lgkmcnt(0)
	ds_read_b128 v[0:3], v9
	ds_read_b128 v[4:7], v9 offset:16
	ds_read_b32 v8, v12
	s_mov_b64 s[40:41], s[42:43]
	s_waitcnt lgkmcnt(0)
	v_pk_mul_f32 v[0:1], v[0:1], v[8:9] op_sel_hi:[1,0]
	v_pk_mul_f32 v[2:3], v[2:3], v[8:9] op_sel_hi:[1,0]
	s_waitcnt vmcnt(0)
	v_lshlrev_b32_e32 v10, 16, v28
	v_and_b32_e32 v11, 0xffff0000, v28
	v_pk_mul_f32 v[0:1], v[0:1], v[10:11]
	v_lshlrev_b32_e32 v10, 16, v29
	v_and_b32_e32 v11, 0xffff0000, v29
	v_pk_mul_f32 v[2:3], v[2:3], v[10:11]
	v_cvt_pk_bf16_f32 v0, v0, v1
	v_cvt_pk_bf16_f32 v1, v2, v3
	v_pk_mul_f32 v[2:3], v[4:5], v[8:9] op_sel_hi:[1,0]
	v_lshlrev_b32_e32 v4, 16, v30
	v_and_b32_e32 v5, 0xffff0000, v30
	v_pk_mul_f32 v[2:3], v[2:3], v[4:5]
	v_pk_mul_f32 v[4:5], v[6:7], v[8:9] op_sel_hi:[1,0]
	v_lshlrev_b32_e32 v6, 16, v31
	v_and_b32_e32 v7, 0xffff0000, v31
	v_pk_mul_f32 v[4:5], v[4:5], v[6:7]
	v_cvt_pk_bf16_f32 v2, v2, v3
	v_cvt_pk_bf16_f32 v3, v4, v5
	v_lshl_add_u64 v[4:5], s[26:27], 0, v[54:55]
	v_lshl_add_u64 v[4:5], v[4:5], 0, s[28:29]
	v_lshl_add_u64 v[4:5], v[4:5], 0, v[80:81]
	global_store_dwordx4 v[4:5], v[0:3], off sc1
	s_nop 1
	ds_read_b128 v[0:3], v9 offset:2176
	ds_read_b128 v[4:7], v9 offset:2192
	ds_read_b32 v8, v12 offset:32
	v_lshlrev_b32_e32 v10, 16, v24
	v_and_b32_e32 v11, 0xffff0000, v24
	s_waitcnt lgkmcnt(0)
	v_pk_mul_f32 v[0:1], v[0:1], v[8:9] op_sel_hi:[1,0]
	s_nop 0
	v_pk_mul_f32 v[0:1], v[0:1], v[10:11]
	v_pk_mul_f32 v[2:3], v[2:3], v[8:9] op_sel_hi:[1,0]
	v_lshlrev_b32_e32 v10, 16, v25
	v_and_b32_e32 v11, 0xffff0000, v25
	v_pk_mul_f32 v[2:3], v[2:3], v[10:11]
	v_cvt_pk_bf16_f32 v0, v0, v1
	v_cvt_pk_bf16_f32 v1, v2, v3
	v_pk_mul_f32 v[2:3], v[4:5], v[8:9] op_sel_hi:[1,0]
	v_lshlrev_b32_e32 v4, 16, v26
	v_and_b32_e32 v5, 0xffff0000, v26
	v_pk_mul_f32 v[2:3], v[2:3], v[4:5]
	v_pk_mul_f32 v[4:5], v[6:7], v[8:9] op_sel_hi:[1,0]
	v_lshlrev_b32_e32 v6, 16, v27
	v_and_b32_e32 v7, 0xffff0000, v27
	v_pk_mul_f32 v[4:5], v[4:5], v[6:7]
	v_cvt_pk_bf16_f32 v2, v2, v3
	v_cvt_pk_bf16_f32 v3, v4, v5
	v_lshl_add_u64 v[4:5], s[26:27], 0, v[52:53]
	v_lshl_add_u64 v[4:5], v[4:5], 0, s[28:29]
	v_lshl_add_u64 v[4:5], v[4:5], 0, v[80:81]
	global_store_dwordx4 v[4:5], v[0:3], off sc1
	s_nop 1
	ds_read_b128 v[0:3], v9 offset:4352
	ds_read_b128 v[4:7], v9 offset:4368
	ds_read_b32 v8, v12 offset:64
	v_lshlrev_b32_e32 v10, 16, v20
	v_and_b32_e32 v11, 0xffff0000, v20
	s_waitcnt lgkmcnt(0)
	v_pk_mul_f32 v[0:1], v[0:1], v[8:9] op_sel_hi:[1,0]
	s_nop 0
	v_pk_mul_f32 v[0:1], v[0:1], v[10:11]
	v_pk_mul_f32 v[2:3], v[2:3], v[8:9] op_sel_hi:[1,0]
	v_lshlrev_b32_e32 v10, 16, v21
	v_and_b32_e32 v11, 0xffff0000, v21
	v_pk_mul_f32 v[2:3], v[2:3], v[10:11]
	v_cvt_pk_bf16_f32 v0, v0, v1
	v_cvt_pk_bf16_f32 v1, v2, v3
	v_pk_mul_f32 v[2:3], v[4:5], v[8:9] op_sel_hi:[1,0]
	v_lshlrev_b32_e32 v4, 16, v22
	v_and_b32_e32 v5, 0xffff0000, v22
	v_pk_mul_f32 v[2:3], v[2:3], v[4:5]
	v_pk_mul_f32 v[4:5], v[6:7], v[8:9] op_sel_hi:[1,0]
	v_lshlrev_b32_e32 v6, 16, v23
	v_and_b32_e32 v7, 0xffff0000, v23
	v_pk_mul_f32 v[4:5], v[4:5], v[6:7]
	v_cvt_pk_bf16_f32 v2, v2, v3
	v_cvt_pk_bf16_f32 v3, v4, v5
	v_lshl_add_u64 v[4:5], s[26:27], 0, v[50:51]
	v_lshl_add_u64 v[4:5], v[4:5], 0, s[28:29]
	v_lshl_add_u64 v[4:5], v[4:5], 0, v[80:81]
	global_store_dwordx4 v[4:5], v[0:3], off sc1
	s_nop 1
	ds_read_b128 v[0:3], v9 offset:6528
	ds_read_b128 v[4:7], v9 offset:6544
	ds_read_b32 v8, v12 offset:96
	v_lshlrev_b32_e32 v10, 16, v16
	v_and_b32_e32 v11, 0xffff0000, v16
	s_waitcnt lgkmcnt(0)
	v_pk_mul_f32 v[0:1], v[0:1], v[8:9] op_sel_hi:[1,0]
	s_nop 0
	v_pk_mul_f32 v[0:1], v[0:1], v[10:11]
	v_pk_mul_f32 v[2:3], v[2:3], v[8:9] op_sel_hi:[1,0]
	v_lshlrev_b32_e32 v10, 16, v17
	v_and_b32_e32 v11, 0xffff0000, v17
	v_pk_mul_f32 v[2:3], v[2:3], v[10:11]
	v_cvt_pk_bf16_f32 v0, v0, v1
	v_cvt_pk_bf16_f32 v1, v2, v3
	v_pk_mul_f32 v[2:3], v[4:5], v[8:9] op_sel_hi:[1,0]
	v_lshlrev_b32_e32 v4, 16, v18
	v_and_b32_e32 v5, 0xffff0000, v18
	v_pk_mul_f32 v[2:3], v[2:3], v[4:5]
	v_pk_mul_f32 v[4:5], v[6:7], v[8:9] op_sel_hi:[1,0]
	v_lshlrev_b32_e32 v6, 16, v19
	v_and_b32_e32 v7, 0xffff0000, v19
	v_pk_mul_f32 v[4:5], v[4:5], v[6:7]
	v_cvt_pk_bf16_f32 v2, v2, v3
	v_cvt_pk_bf16_f32 v3, v4, v5
	v_lshl_add_u64 v[4:5], s[26:27], 0, v[48:49]
	v_lshl_add_u64 v[4:5], v[4:5], 0, s[28:29]
	v_lshl_add_u64 v[4:5], v[4:5], 0, v[80:81]
	global_store_dwordx4 v[4:5], v[0:3], off sc1
	s_nop 1
	s_waitcnt vmcnt(0)
	s_barrier
.LBB0_355:
	s_and_saveexec_b64 s[2:3], s[40:41]
	s_xor_b64 s[28:29], exec, s[2:3]
	s_cbranch_execz .LBB0_154
	v_mov_b64_e32 v[0:1], s[64:65]
	global_atomic_add v[0:1], v181, off
	s_branch .LBB0_154

.LBB0_392:
	s_or_b64 exec, exec, s[16:17]
	s_ashr_i32 s18, s72, 5
	s_and_b32 s0, s67, 31
	s_ashr_i32 s19, s18, 31
	s_lshl_b32 s60, s0, 19
	s_lshl_b64 s[26:27], s[18:19], 18
	s_add_u32 s28, s2, s26
	s_addc_u32 s29, s3, s27
	s_lshl_b32 s0, s73, 19
	s_add_u32 s34, s5, s0
	s_addc_u32 s35, s33, 0
	s_cmp_lt_u32 s73, 16
	s_cselect_b64 s[16:17], -1, 0
	s_add_i32 s0, s73, -16
	s_lshr_b32 s0, s0, 2
	s_add_i32 s0, s0, 1
	s_cmp_gt_u32 s73, 15
	s_cselect_b32 s0, s0, 0
	s_lshl_b32 s19, s18, 7
	s_add_i32 s41, s0, s81
	s_or_b32 s40, s19, s37
	s_mul_hi_i32 s42, s41, 0x3000
	s_mulk_i32 s41, 0x3000
	s_add_u32 s43, s88, s41
	s_addc_u32 s44, s89, s42
	s_ashr_i32 s41, s40, 31
	s_lshl_b64 s[40:41], s[40:41], 2
	s_add_u32 s42, s43, s40
	s_addc_u32 s43, s44, s41
	v_mov_b32_e32 v139, v81
	v_lshl_add_u64 v[0:1], s[42:43], 0, v[138:139]
	s_mov_b64 s[42:43], 0x42000
	v_lshl_add_u64 v[2:3], v[0:1], 0, s[42:43]
	s_add_i32 s42, s36, s0
	s_ashr_i32 s43, s42, 31
	s_lshl_b64 s[42:43], s[42:43], 12
	s_add_u32 s0, s48, s42
	s_addc_u32 s42, s49, s43
	s_add_u32 s40, s0, s40
	s_mov_b32 s0, 0x42000
	s_addc_u32 s41, s42, s41
	v_add_co_u32_e32 v0, vcc, s0, v0
	v_lshl_add_u64 v[16:17], s[40:41], 0, v[138:139]
	s_nop 0
	v_addc_co_u32_e32 v1, vcc, 0, v1, vcc
	s_mov_b32 m0, s52
	s_waitcnt lgkmcnt(0)
	s_barrier
	global_load_dwordx4 v[8:11], v[2:3], off offset:16
	global_load_dwordx4 v[4:7], v[16:17], off
	global_load_dwordx4 v[12:15], v[0:1], off
	s_nop 0
	global_load_dwordx4 v[0:3], v[16:17], off offset:16
	v_lshl_add_u64 v[16:17], v[114:115], 1, s[28:29]
	global_load_lds_dwordx4 v[16:17], off
	v_lshl_add_u64 v[16:17], v[116:117], 1, s[28:29]
	s_mov_b32 m0, s63
	v_mov_b32_e32 v28, 0
	global_load_lds_dwordx4 v[16:17], off
	v_lshl_add_u64 v[16:17], v[118:119], 1, s[34:35]
	s_add_i32 m0, s50, 0x4000
	v_lshl_add_u64 v[82:83], v[128:129], 0, s[60:61]
	global_load_lds_dwordx4 v[16:17], off
	v_lshl_add_u64 v[16:17], v[120:121], 1, s[34:35]
	s_mov_b32 m0, s64
	v_lshl_add_u64 v[84:85], v[130:131], 0, s[60:61]
	global_load_lds_dwordx4 v[16:17], off
	v_lshl_add_u64 v[16:17], v[122:123], 1, s[34:35]
	s_mov_b32 m0, s65
	v_lshl_add_u64 v[86:87], v[132:133], 0, s[60:61]
	global_load_lds_dwordx4 v[16:17], off
	v_lshl_add_u64 v[16:17], v[124:125], 1, s[34:35]
	s_mov_b32 m0, s66
	v_lshl_add_u64 v[88:89], v[134:135], 0, s[60:61]
	global_load_lds_dwordx4 v[16:17], off
	s_waitcnt vmcnt(0)
	s_mov_b32 s28, 0
	v_lshl_add_u64 v[90:91], v[126:127], 0, s[26:27]
	v_lshl_add_u64 v[92:93], v[136:137], 0, s[26:27]
	s_mov_b64 s[26:27], 0
	v_mov_b32_e32 v29, v28
	v_mov_b32_e32 v30, v28
	v_mov_b32_e32 v31, v28
	v_mov_b32_e32 v36, v28
	v_mov_b32_e32 v37, v28
	v_mov_b32_e32 v38, v28
	v_mov_b32_e32 v39, v28
	v_mov_b32_e32 v16, v28
	v_mov_b32_e32 v17, v28
	v_mov_b32_e32 v18, v28
	v_mov_b32_e32 v19, v28
	v_mov_b32_e32 v20, v28
	v_mov_b32_e32 v21, v28
	v_mov_b32_e32 v22, v28
	v_mov_b32_e32 v23, v28
	v_mov_b32_e32 v24, v28
	v_mov_b32_e32 v25, v28
	v_mov_b32_e32 v26, v28
	v_mov_b32_e32 v27, v28
	v_mov_b32_e32 v32, v28
	v_mov_b32_e32 v33, v28
	v_mov_b32_e32 v34, v28
	v_mov_b32_e32 v35, v28
	v_mov_b32_e32 v40, v28
	v_mov_b32_e32 v41, v28
	v_mov_b32_e32 v42, v28
	v_mov_b32_e32 v43, v28
	v_mov_b32_e32 v44, v28
	v_mov_b32_e32 v45, v28
	v_mov_b32_e32 v46, v28
	v_mov_b32_e32 v47, v28
	v_mov_b32_e32 v48, v28
	v_mov_b32_e32 v49, v28
	v_mov_b32_e32 v50, v28
	v_mov_b32_e32 v51, v28
	v_mov_b32_e32 v52, v28
	v_mov_b32_e32 v53, v28
	v_mov_b32_e32 v54, v28
	v_mov_b32_e32 v55, v28
	v_mov_b32_e32 v56, v28
	v_mov_b32_e32 v57, v28
	v_mov_b32_e32 v58, v28
	v_mov_b32_e32 v59, v28
	v_mov_b32_e32 v60, v28
	v_mov_b32_e32 v61, v28
	v_mov_b32_e32 v62, v28
	v_mov_b32_e32 v63, v28
	v_mov_b32_e32 v64, v28
	v_mov_b32_e32 v65, v28
	v_mov_b32_e32 v66, v28
	v_mov_b32_e32 v67, v28
	v_mov_b32_e32 v68, v28
	v_mov_b32_e32 v69, v28
	v_mov_b32_e32 v70, v28
	v_mov_b32_e32 v71, v28
	v_mov_b32_e32 v72, v28
	v_mov_b32_e32 v73, v28
	v_mov_b32_e32 v74, v28
	v_mov_b32_e32 v75, v28
	v_mov_b32_e32 v76, v28
	v_mov_b32_e32 v77, v28
	v_mov_b32_e32 v78, v28
	v_mov_b32_e32 v79, v28
	s_waitcnt vmcnt(0) lgkmcnt(0)
	s_barrier
.LBB0_393:
	s_and_b32 s0, s28, 1
	s_xor_b32 s29, s0, 1
	s_mul_i32 s29, s29, 0xc000
	s_add_i32 s34, s52, s29
	v_lshl_add_u64 v[94:95], v[92:93], 0, s[26:27]
	s_mul_i32 s0, s0, 0xc000
	s_add_i32 s29, s50, s29
	s_mov_b32 m0, s34
	v_lshl_add_u64 v[96:97], v[88:89], 0, s[26:27]
	s_add_i32 s0, s0, 0
	global_load_lds_dwordx4 v[94:95], off
	s_add_i32 m0, s29, 0x4000
	v_lshl_add_u64 v[98:99], v[86:87], 0, s[26:27]
	v_add_u32_e32 v80, s0, v153
	v_add_u32_e32 v139, s0, v154
	global_load_lds_dwordx4 v[96:97], off
	s_add_i32 m0, s29, 0x4400
	v_add_u32_e32 v146, v80, v151
	v_add_u32_e32 v110, v139, v151
	global_load_lds_dwordx4 v[98:99], off
	ds_read_b128 v[94:97], v146
	ds_read_b128 v[98:101], v110 offset:16384
	ds_read_b128 v[102:105], v110 offset:18432
	ds_read_b128 v[106:109], v110 offset:20480
	ds_read_b128 v[110:113], v110 offset:22528
	s_waitcnt lgkmcnt(0)
	v_mfma_f32_16x16x32_bf16 v[76:79], v[94:97], v[98:101], v[76:79]
	v_lshl_add_u64 v[140:141], v[90:91], 0, s[26:27]
	s_add_i32 s0, s29, 0x4800
	s_add_i32 m0, s34, 0x400
	v_mfma_f32_16x16x32_bf16 v[72:75], v[94:97], v[102:105], v[72:75]
	v_lshl_add_u64 v[142:143], v[82:83], 0, s[26:27]
	s_addk_i32 s29, 0x4c00
	v_lshl_add_u64 v[144:145], v[84:85], 0, s[26:27]
	v_mfma_f32_16x16x32_bf16 v[68:71], v[94:97], v[106:109], v[68:71]
	v_add_u32_e32 v80, v80, v152
	v_add_u32_e32 v139, v139, v152
	s_add_i32 s28, s28, 1
	v_mfma_f32_16x16x32_bf16 v[64:67], v[94:97], v[110:113], v[64:67]
	ds_read_b128 v[94:97], v146 offset:2048
	s_add_u32 s26, s26, 0x80
	s_addc_u32 s27, s27, 0
	s_waitcnt lgkmcnt(0)
	v_mfma_f32_16x16x32_bf16 v[60:63], v[94:97], v[98:101], v[60:63]
	s_cmpk_eq_i32 s26, 0x780
	v_mfma_f32_16x16x32_bf16 v[56:59], v[94:97], v[102:105], v[56:59]
	v_mfma_f32_16x16x32_bf16 v[52:55], v[94:97], v[106:109], v[52:55]
	v_mfma_f32_16x16x32_bf16 v[48:51], v[94:97], v[110:113], v[48:51]
	ds_read_b128 v[94:97], v146 offset:4096
	s_waitcnt lgkmcnt(0)
	v_mfma_f32_16x16x32_bf16 v[44:47], v[94:97], v[98:101], v[44:47]
	v_mfma_f32_16x16x32_bf16 v[40:43], v[94:97], v[102:105], v[40:43]
	v_mfma_f32_16x16x32_bf16 v[32:35], v[94:97], v[106:109], v[32:35]
	v_mfma_f32_16x16x32_bf16 v[24:27], v[94:97], v[110:113], v[24:27]
	ds_read_b128 v[94:97], v146 offset:6144
	global_load_lds_dwordx4 v[140:141], off
	s_mov_b32 m0, s0
	s_waitcnt lgkmcnt(0)
	v_mfma_f32_16x16x32_bf16 v[20:23], v[94:97], v[98:101], v[20:23]
	global_load_lds_dwordx4 v[142:143], off
	s_mov_b32 m0, s29
	v_mfma_f32_16x16x32_bf16 v[16:19], v[94:97], v[102:105], v[16:19]
	global_load_lds_dwordx4 v[144:145], off
	ds_read_b128 v[98:101], v80
	v_mfma_f32_16x16x32_bf16 v[36:39], v[94:97], v[106:109], v[36:39]
	ds_read_b128 v[102:105], v139 offset:18432
	ds_read_b128 v[106:109], v139 offset:20480
	v_mfma_f32_16x16x32_bf16 v[28:31], v[94:97], v[110:113], v[28:31]
	ds_read_b128 v[94:97], v139 offset:16384
	ds_read_b128 v[110:113], v139 offset:22528
	s_waitcnt lgkmcnt(0)
	v_mfma_f32_16x16x32_bf16 v[76:79], v[98:101], v[94:97], v[76:79]
	v_mfma_f32_16x16x32_bf16 v[72:75], v[98:101], v[102:105], v[72:75]
	v_mfma_f32_16x16x32_bf16 v[68:71], v[98:101], v[106:109], v[68:71]
	v_mfma_f32_16x16x32_bf16 v[64:67], v[98:101], v[110:113], v[64:67]
	ds_read_b128 v[98:101], v80 offset:2048
	s_waitcnt lgkmcnt(0)
	v_mfma_f32_16x16x32_bf16 v[60:63], v[98:101], v[94:97], v[60:63]
	v_mfma_f32_16x16x32_bf16 v[56:59], v[98:101], v[102:105], v[56:59]
	v_mfma_f32_16x16x32_bf16 v[52:55], v[98:101], v[106:109], v[52:55]
	v_mfma_f32_16x16x32_bf16 v[48:51], v[98:101], v[110:113], v[48:51]
	ds_read_b128 v[98:101], v80 offset:4096
	s_waitcnt lgkmcnt(0)
	v_mfma_f32_16x16x32_bf16 v[44:47], v[98:101], v[94:97], v[44:47]
	v_mfma_f32_16x16x32_bf16 v[40:43], v[98:101], v[102:105], v[40:43]
	v_mfma_f32_16x16x32_bf16 v[32:35], v[98:101], v[106:109], v[32:35]
	v_mfma_f32_16x16x32_bf16 v[24:27], v[98:101], v[110:113], v[24:27]
	ds_read_b128 v[98:101], v80 offset:6144
	s_waitcnt vmcnt(0)
	s_waitcnt vmcnt(0) lgkmcnt(0)
	v_mfma_f32_16x16x32_bf16 v[20:23], v[98:101], v[94:97], v[20:23]
	s_barrier
	v_mfma_f32_16x16x32_bf16 v[16:19], v[98:101], v[102:105], v[16:19]
	v_mfma_f32_16x16x32_bf16 v[36:39], v[98:101], v[106:109], v[36:39]
	v_mfma_f32_16x16x32_bf16 v[28:31], v[98:101], v[110:113], v[28:31]
	s_cbranch_scc0 .LBB0_393
	v_add_u32_e32 v80, v155, v151
	ds_read_b128 v[82:85], v80 offset:49152
	v_add_u32_e32 v110, v156, v151
	ds_read_b128 v[86:89], v110 offset:16384
	ds_read_b128 v[90:93], v80 offset:51200
	ds_read_b128 v[94:97], v110 offset:18432
	ds_read_b128 v[98:101], v80 offset:53248
	ds_read_b128 v[102:105], v110 offset:20480
	ds_read_b128 v[106:109], v80 offset:55296
	ds_read_b128 v[110:113], v110 offset:22528
	s_waitcnt lgkmcnt(5)
	v_mfma_f32_16x16x32_bf16 v[60:63], v[90:93], v[86:89], v[60:63]
	s_or_b32 s26, s19, s54
	s_lshl_b32 s0, s73, 8
	s_ashr_i32 s27, s26, 31
	s_waitcnt lgkmcnt(3)
	v_mfma_f32_16x16x32_bf16 v[44:47], v[98:101], v[86:89], v[44:47]
	v_mov_b32_e32 v139, v188
	s_add_i32 s28, s0, s51
	s_lshl_b64 s[34:35], s[26:27], 1
	v_mfma_f32_16x16x32_bf16 v[76:79], v[82:85], v[86:89], v[76:79]
	s_add_u32 s40, s55, s34
	s_addc_u32 s41, s56, s35
	s_ashr_i32 s29, s28, 31
	s_waitcnt lgkmcnt(1)
	v_mfma_f32_16x16x32_bf16 v[86:89], v[106:109], v[86:89], v[20:23]
	s_and_b64 vcc, exec, s[8:9]
	s_nop 1
	v_add_u32_e32 v20, v155, v152
	v_mfma_f32_16x16x32_bf16 v[144:147], v[106:109], v[94:97], v[16:19]
	v_add_u32_e32 v21, v156, v152
	s_nop 1
	ds_read_b128 v[16:19], v20 offset:49152
	v_mfma_f32_16x16x32_bf16 v[72:75], v[82:85], v[94:97], v[72:75]
	v_mfma_f32_16x16x32_bf16 v[140:143], v[82:85], v[102:105], v[68:71]
	s_waitcnt lgkmcnt(1)
	v_mfma_f32_16x16x32_bf16 v[82:85], v[82:85], v[110:113], v[64:67]
	v_mfma_f32_16x16x32_bf16 v[56:59], v[90:93], v[94:97], v[56:59]
	v_mfma_f32_16x16x32_bf16 v[52:55], v[90:93], v[102:105], v[52:55]
	v_mfma_f32_16x16x32_bf16 v[48:51], v[90:93], v[110:113], v[48:51]
	v_mfma_f32_16x16x32_bf16 v[40:43], v[98:101], v[94:97], v[40:43]
	v_mfma_f32_16x16x32_bf16 v[32:35], v[98:101], v[102:105], v[32:35]
	v_mfma_f32_16x16x32_bf16 v[98:101], v[98:101], v[110:113], v[24:27]
	v_mfma_f32_16x16x32_bf16 v[36:39], v[106:109], v[102:105], v[36:39]
	v_mfma_f32_16x16x32_bf16 v[102:105], v[106:109], v[110:113], v[28:31]
	ds_read_b128 v[94:97], v21 offset:16384
	ds_read_b128 v[24:27], v20 offset:51200
	ds_read_b128 v[106:109], v21 offset:18432
	ds_read_b128 v[110:113], v20 offset:53248
	ds_read_b128 v[158:161], v21 offset:20480
	ds_read_b128 v[162:165], v20 offset:55296
	ds_read_b128 v[166:169], v21 offset:22528
	s_waitcnt vmcnt(0)
	s_waitcnt lgkmcnt(0)
	v_mfma_f32_16x16x32_bf16 v[68:71], v[16:19], v[94:97], v[76:79]
	s_barrier
	v_mfma_f32_16x16x32_bf16 v[64:67], v[16:19], v[106:109], v[72:75]
	v_mfma_f32_16x16x32_bf16 v[20:23], v[16:19], v[158:161], v[140:143]
	v_mfma_f32_16x16x32_bf16 v[16:19], v[16:19], v[166:169], v[82:85]
	s_nop 1
	v_ashrrev_i32_e32 v140, 3, v139
	v_ashrrev_i32_e32 v141, 31, v140
	v_mfma_f32_16x16x32_bf16 v[76:79], v[24:27], v[94:97], v[60:63]
	v_mfma_f32_16x16x32_bf16 v[72:75], v[24:27], v[106:109], v[56:59]
	v_mfma_f32_16x16x32_bf16 v[28:31], v[24:27], v[158:161], v[52:55]
	v_mfma_f32_16x16x32_bf16 v[24:27], v[24:27], v[166:169], v[48:51]
	v_mfma_f32_16x16x32_bf16 v[90:93], v[110:113], v[94:97], v[44:47]
	v_mfma_f32_16x16x32_bf16 v[82:85], v[110:113], v[106:109], v[40:43]
	v_mfma_f32_16x16x32_bf16 v[40:43], v[110:113], v[158:161], v[32:35]
	v_mfma_f32_16x16x32_bf16 v[32:35], v[110:113], v[166:169], v[98:101]
	v_mfma_f32_16x16x32_bf16 v[94:97], v[162:165], v[94:97], v[86:89]
	v_mfma_f32_16x16x32_bf16 v[86:89], v[162:165], v[106:109], v[144:147]
	v_mfma_f32_16x16x32_bf16 v[44:47], v[162:165], v[158:161], v[36:39]
	v_and_b32_e32 v159, 7, v139
	v_lshlrev_b32_e32 v80, 4, v159
	v_lshl_add_u64 v[142:143], s[40:41], 0, v[80:81]
	v_mfma_f32_16x16x32_bf16 v[36:39], v[162:165], v[166:169], v[102:105]
	s_lshl_b64 s[40:41], s[28:29], 11
	v_lshl_add_u64 v[144:145], v[142:143], 0, s[40:41]
	s_mov_b64 s[40:41], -1
	s_mov_b32 s100, 0
	s_cbranch_vccz .LBB0_396
	v_lshlrev_b64 v[146:147], 11, v[140:141]
	v_lshl_add_u64 v[60:61], v[144:145], 0, v[146:147]
	s_movk_i32 s0, 0x4000
	v_add_co_u32_e32 v52, vcc, s0, v60
	s_mov_b32 s0, 0x8000
	s_nop 0
	v_addc_co_u32_e32 v53, vcc, 0, v61, vcc
	v_add_co_u32_e32 v56, vcc, s0, v60
	s_mov_b32 s0, 0xc000
	s_nop 0
	v_addc_co_u32_e32 v57, vcc, 0, v61, vcc
	global_load_dwordx4 v[48:51], v[60:61], off
	v_add_co_u32_e32 v60, vcc, s0, v60
	global_load_dwordx4 v[52:55], v[52:53], off
	s_nop 0
	v_addc_co_u32_e32 v61, vcc, 0, v61, vcc
	global_load_dwordx4 v[56:59], v[56:57], off
	s_mov_b64 s[40:41], 0
	s_mov_b32 s100, 1
	global_load_dwordx4 v[170:173], v[60:61], off

.LBB0_402:
	v_and_b32_e32 v80, 15, v139
	v_mov_b32_e32 v158, s53
	v_mad_u32_u24 v80, v80, s77, v158
	v_and_b32_e32 v139, -16, v139
	v_add_u32_e32 v158, v80, v139
	s_waitcnt lgkmcnt(0)
	ds_write_b128 v158, v[68:71]
	ds_write_b128 v158, v[76:79] offset:64
	ds_write_b128 v158, v[90:93] offset:128
	ds_write_b128 v158, v[94:97] offset:192
	v_lshl_add_u32 v160, v157, 2, s53
	s_waitcnt lgkmcnt(0)
	s_waitcnt lgkmcnt(0)
	ds_write_b128 v158, v[64:67] offset:4352
	ds_write_b128 v158, v[72:75] offset:4416
	ds_write_b128 v158, v[82:85] offset:4480
	ds_write_b128 v158, v[86:89] offset:4544
	v_mul_lo_u32 v64, v140, s77
	v_add_u32_e32 v139, v160, v64
	s_waitcnt lgkmcnt(0)
	ds_read_b128 v[64:67], v139
	ds_read_b128 v[74:77], v139 offset:16
	s_cmp_eq_u32 s100, 0
	s_cbranch_scc1 .Lg2_res0
	s_waitcnt vmcnt(0)
	v_lshlrev_b32_e32 v110, 16, v48
	v_and_b32_e32 v111, 0xffff0000, v48
	v_lshlrev_b32_e32 v112, 16, v49
	v_and_b32_e32 v113, 0xffff0000, v49
	v_lshlrev_b32_e32 v106, 16, v50
	v_and_b32_e32 v107, 0xffff0000, v50
	v_lshlrev_b32_e32 v108, 16, v51
	v_and_b32_e32 v109, 0xffff0000, v51
	v_lshlrev_b32_e32 v102, 16, v52
	v_and_b32_e32 v103, 0xffff0000, v52
	v_lshlrev_b32_e32 v104, 16, v53
	v_and_b32_e32 v105, 0xffff0000, v53
	v_lshlrev_b32_e32 v98, 16, v54
	v_and_b32_e32 v99, 0xffff0000, v54
	v_lshlrev_b32_e32 v100, 16, v55
	v_and_b32_e32 v101, 0xffff0000, v55
	v_lshlrev_b32_e32 v60, 16, v56
	v_and_b32_e32 v61, 0xffff0000, v56
	v_lshlrev_b32_e32 v62, 16, v57
	v_and_b32_e32 v63, 0xffff0000, v57
	v_lshlrev_b32_e32 v56, 16, v58
	v_and_b32_e32 v57, 0xffff0000, v58
	v_lshlrev_b32_e32 v58, 16, v59
	v_and_b32_e32 v59, 0xffff0000, v59
	v_lshlrev_b32_e32 v52, 16, v170
	v_and_b32_e32 v53, 0xffff0000, v170
	v_lshlrev_b32_e32 v54, 16, v171
	v_and_b32_e32 v55, 0xffff0000, v171
	v_lshlrev_b32_e32 v48, 16, v172
	v_and_b32_e32 v49, 0xffff0000, v172
	v_lshlrev_b32_e32 v50, 16, v173
	v_and_b32_e32 v51, 0xffff0000, v173
.Lg2_res0:
	s_mov_b64 s[40:41], -1
	s_and_b64 vcc, exec, s[12:13]
	s_waitcnt vmcnt(7) lgkmcnt(1)
	v_pk_fma_f32 v[68:69], v[14:15], v[66:67], v[112:113]
	v_pk_fma_f32 v[72:73], v[12:13], v[64:65], v[110:111]
	s_waitcnt vmcnt(6) lgkmcnt(0)
	v_pk_fma_f32 v[70:71], v[10:11], v[76:77], v[108:109]
	v_pk_fma_f32 v[74:75], v[8:9], v[74:75], v[106:107]
	v_cvt_pk_bf16_f32 v64, v72, v73
	v_cvt_pk_bf16_f32 v65, v68, v69
	v_cvt_pk_bf16_f32 v66, v74, v75
	v_cvt_pk_bf16_f32 v67, v70, v71
	v_lshl_add_u64 v[76:77], v[144:145], 0, v[146:147]
	s_cbranch_vccz .LBB0_404
	global_store_dwordx4 v[76:77], v[64:67], off
	s_mov_b64 s[40:41], 0

.LBB0_410:
	s_waitcnt lgkmcnt(0)
	ds_read_b128 v[64:67], v139 offset:2176
	ds_read_b128 v[76:79], v139 offset:2192
	v_add_u32_e32 v84, 8, v140
	v_ashrrev_i32_e32 v85, 31, v84
	v_lshlrev_b64 v[68:69], 11, v[84:85]
	s_waitcnt vmcnt(0) lgkmcnt(0)
	v_pk_fma_f32 v[70:71], v[12:13], v[64:65], v[102:103]
	v_pk_fma_f32 v[74:75], v[14:15], v[66:67], v[104:105]
	v_pk_fma_f32 v[72:73], v[8:9], v[76:77], v[98:99]
	v_pk_fma_f32 v[76:77], v[10:11], v[78:79], v[100:101]
	v_cndmask_b32_e64 v80, 0, 1, s[12:13]
	v_cvt_pk_bf16_f32 v64, v70, v71
	v_cvt_pk_bf16_f32 v65, v74, v75
	v_cvt_pk_bf16_f32 v66, v72, v73
	v_cvt_pk_bf16_f32 v67, v76, v77
	v_lshl_add_u64 v[78:79], v[144:145], 0, v[68:69]
	v_cmp_ne_u32_e64 s[44:45], 1, v80
	s_andn2_b64 vcc, exec, s[12:13]
	s_mov_b64 s[34:35], -1
	s_cbranch_vccnz .LBB0_412
	s_mov_b64 s[34:35], 0
	global_store_dwordx4 v[78:79], v[64:67], off

.LBB0_418:
	s_waitcnt lgkmcnt(0)
	ds_read_b128 v[64:67], v139 offset:4352
	ds_read_b128 v[70:73], v139 offset:4368
	v_add_u32_e32 v86, 16, v140
	v_ashrrev_i32_e32 v87, 31, v86
	s_and_b64 vcc, exec, s[44:45]
	s_waitcnt lgkmcnt(0)
	v_pk_fma_f32 v[64:65], v[12:13], v[64:65], v[60:61]
	v_pk_fma_f32 v[66:67], v[14:15], v[66:67], v[62:63]
	v_pk_fma_f32 v[62:63], v[8:9], v[70:71], v[56:57]
	v_pk_fma_f32 v[70:71], v[10:11], v[72:73], v[58:59]
	v_lshlrev_b64 v[60:61], 11, v[86:87]
	v_cvt_pk_bf16_f32 v56, v64, v65
	v_cvt_pk_bf16_f32 v57, v66, v67
	v_cvt_pk_bf16_f32 v58, v62, v63
	v_cvt_pk_bf16_f32 v59, v70, v71
	v_lshl_add_u64 v[72:73], v[144:145], 0, v[60:61]
	s_mov_b64 s[34:35], -1
	s_cbranch_vccnz .LBB0_420
	s_mov_b64 s[34:35], 0
	global_store_dwordx4 v[72:73], v[56:59], off

.LBB0_426:
	s_waitcnt lgkmcnt(0)
	ds_read_b128 v[56:59], v139 offset:6528
	ds_read_b128 v[62:65], v139 offset:6544
	v_add_u32_e32 v88, 24, v140
	v_ashrrev_i32_e32 v89, 31, v88
	s_and_b64 vcc, exec, s[44:45]
	s_waitcnt lgkmcnt(0)
	v_pk_fma_f32 v[56:57], v[12:13], v[56:57], v[52:53]
	v_pk_fma_f32 v[58:59], v[14:15], v[58:59], v[54:55]
	v_pk_fma_f32 v[54:55], v[8:9], v[62:63], v[48:49]
	v_pk_fma_f32 v[62:63], v[10:11], v[64:65], v[50:51]
	v_lshlrev_b64 v[52:53], 11, v[88:89]
	v_cvt_pk_bf16_f32 v48, v56, v57
	v_cvt_pk_bf16_f32 v49, v58, v59
	v_cvt_pk_bf16_f32 v50, v54, v55
	v_cvt_pk_bf16_f32 v51, v62, v63
	v_lshl_add_u64 v[64:65], v[144:145], 0, v[52:53]
	s_mov_b64 s[34:35], -1
	s_cbranch_vccnz .LBB0_428
	s_mov_b64 s[34:35], 0
	global_store_dwordx4 v[64:65], v[48:51], off

.LBB0_434:
	s_or_b32 s34, s28, 32
	s_ashr_i32 s35, s34, 31
	s_lshl_b64 s[46:47], s[34:35], 11
	v_lshl_add_u64 v[48:49], v[142:143], 0, s[46:47]
	s_mov_b64 s[46:47], -1
	s_andn2_b64 vcc, exec, s[8:9]
	v_lshl_add_u64 v[96:97], v[48:49], 0, v[146:147]
	v_lshl_add_u64 v[94:95], v[48:49], 0, v[68:69]
	v_lshl_add_u64 v[92:93], v[48:49], 0, v[60:61]
	v_lshl_add_u64 v[90:91], v[48:49], 0, v[52:53]
	s_mov_b32 s101, 0
	s_cbranch_vccnz .LBB0_436
	s_waitcnt lgkmcnt(0)
	global_load_dwordx4 v[48:51], v[96:97], off
	global_load_dwordx4 v[52:55], v[94:95], off
	global_load_dwordx4 v[56:59], v[92:93], off
	global_load_dwordx4 v[98:101], v[90:91], off
	s_mov_b64 s[46:47], 0
	s_mov_b32 s101, 1

.LBB0_442:
	s_waitcnt lgkmcnt(0)
	ds_write_b128 v158, v[20:23]
	ds_write_b128 v158, v[28:31] offset:64
	ds_write_b128 v158, v[40:43] offset:128
	ds_write_b128 v158, v[44:47] offset:192
	s_waitcnt lgkmcnt(0)
	s_waitcnt lgkmcnt(0)
	ds_write_b128 v158, v[16:19] offset:4352
	ds_write_b128 v158, v[24:27] offset:4416
	ds_write_b128 v158, v[32:35] offset:4480
	ds_write_b128 v158, v[36:39] offset:4544
	s_waitcnt lgkmcnt(0)
	ds_read_b128 v[16:19], v139
	ds_read_b128 v[26:29], v139 offset:16
	s_cmp_eq_u32 s101, 0
	s_cbranch_scc1 .Lg2_res1
	s_waitcnt vmcnt(0)
	v_lshlrev_b32_e32 v76, 16, v48
	v_and_b32_e32 v77, 0xffff0000, v48
	v_lshlrev_b32_e32 v78, 16, v49
	v_and_b32_e32 v79, 0xffff0000, v49
	v_lshlrev_b32_e32 v72, 16, v50
	v_and_b32_e32 v73, 0xffff0000, v50
	v_lshlrev_b32_e32 v74, 16, v51
	v_and_b32_e32 v75, 0xffff0000, v51
	v_lshlrev_b32_e32 v68, 16, v52
	v_and_b32_e32 v69, 0xffff0000, v52
	v_lshlrev_b32_e32 v70, 16, v53
	v_and_b32_e32 v71, 0xffff0000, v53
	v_lshlrev_b32_e32 v64, 16, v54
	v_and_b32_e32 v65, 0xffff0000, v54
	v_lshlrev_b32_e32 v66, 16, v55
	v_and_b32_e32 v67, 0xffff0000, v55
	v_lshlrev_b32_e32 v60, 16, v56
	v_and_b32_e32 v61, 0xffff0000, v56
	v_lshlrev_b32_e32 v62, 16, v57
	v_and_b32_e32 v63, 0xffff0000, v57
	v_lshlrev_b32_e32 v56, 16, v58
	v_and_b32_e32 v57, 0xffff0000, v58
	v_lshlrev_b32_e32 v58, 16, v59
	v_and_b32_e32 v59, 0xffff0000, v59
	v_lshlrev_b32_e32 v52, 16, v98
	v_and_b32_e32 v53, 0xffff0000, v98
	v_lshlrev_b32_e32 v54, 16, v99
	v_and_b32_e32 v55, 0xffff0000, v99
	v_lshlrev_b32_e32 v48, 16, v100
	v_and_b32_e32 v49, 0xffff0000, v100
	v_lshlrev_b32_e32 v50, 16, v101
	v_and_b32_e32 v51, 0xffff0000, v101
.Lg2_res1:
	s_and_b64 vcc, exec, s[44:45]
	s_mov_b64 s[16:17], -1
	s_waitcnt vmcnt(0) lgkmcnt(0)
	v_pk_fma_f32 v[20:21], v[12:13], v[16:17], v[76:77]
	v_pk_fma_f32 v[24:25], v[14:15], v[18:19], v[78:79]
	v_pk_fma_f32 v[22:23], v[8:9], v[26:27], v[72:73]
	v_pk_fma_f32 v[26:27], v[10:11], v[28:29], v[74:75]
	v_cvt_pk_bf16_f32 v16, v20, v21
	v_cvt_pk_bf16_f32 v17, v24, v25
	v_cvt_pk_bf16_f32 v18, v22, v23
	v_cvt_pk_bf16_f32 v19, v26, v27
	s_cbranch_vccnz .LBB0_444
	s_mov_b64 s[16:17], 0
	global_store_dwordx4 v[96:97], v[16:19], off

.LBB0_450:
	s_waitcnt lgkmcnt(0)
	ds_read_b128 v[16:19], v139 offset:2176
	ds_read_b128 v[26:29], v139 offset:2192
	s_and_b64 vcc, exec, s[44:45]
	s_mov_b64 s[16:17], -1
	s_waitcnt lgkmcnt(0)
	v_pk_fma_f32 v[20:21], v[12:13], v[16:17], v[68:69]
	v_pk_fma_f32 v[24:25], v[14:15], v[18:19], v[70:71]
	v_pk_fma_f32 v[22:23], v[8:9], v[26:27], v[64:65]
	v_pk_fma_f32 v[26:27], v[10:11], v[28:29], v[66:67]
	v_cvt_pk_bf16_f32 v16, v20, v21
	v_cvt_pk_bf16_f32 v17, v24, v25
	v_cvt_pk_bf16_f32 v18, v22, v23
	v_cvt_pk_bf16_f32 v19, v26, v27
	s_cbranch_vccnz .LBB0_452
	s_mov_b64 s[16:17], 0
	global_store_dwordx4 v[94:95], v[16:19], off

.LBB0_458:
	s_waitcnt lgkmcnt(0)
	ds_read_b128 v[16:19], v139 offset:4352
	ds_read_b128 v[26:29], v139 offset:4368
	s_and_b64 vcc, exec, s[44:45]
	s_mov_b64 s[16:17], -1
	s_waitcnt lgkmcnt(0)
	v_pk_fma_f32 v[20:21], v[12:13], v[16:17], v[60:61]
	v_pk_fma_f32 v[24:25], v[14:15], v[18:19], v[62:63]
	v_pk_fma_f32 v[22:23], v[8:9], v[26:27], v[56:57]
	v_pk_fma_f32 v[26:27], v[10:11], v[28:29], v[58:59]
	v_cvt_pk_bf16_f32 v16, v20, v21
	v_cvt_pk_bf16_f32 v17, v24, v25
	v_cvt_pk_bf16_f32 v18, v22, v23
	v_cvt_pk_bf16_f32 v19, v26, v27
	s_cbranch_vccnz .LBB0_460
	s_mov_b64 s[16:17], 0
	global_store_dwordx4 v[92:93], v[16:19], off

.LBB0_466:
	s_waitcnt lgkmcnt(0)
	ds_read_b128 v[16:19], v139 offset:6528
	ds_read_b128 v[20:23], v139 offset:6544
	s_and_b64 vcc, exec, s[44:45]
	s_mov_b64 s[16:17], -1
	s_waitcnt lgkmcnt(0)
	v_pk_fma_f32 v[12:13], v[12:13], v[16:17], v[52:53]
	v_pk_fma_f32 v[16:17], v[14:15], v[18:19], v[54:55]
	v_pk_fma_f32 v[14:15], v[8:9], v[20:21], v[48:49]
	v_pk_fma_f32 v[18:19], v[10:11], v[22:23], v[50:51]
	v_cvt_pk_bf16_f32 v8, v12, v13
	v_cvt_pk_bf16_f32 v9, v16, v17
	v_cvt_pk_bf16_f32 v10, v14, v15
	v_cvt_pk_bf16_f32 v11, v18, v19
	s_cbranch_vccnz .LBB0_468
	s_mov_b64 s[16:17], 0
	global_store_dwordx4 v[90:91], v[8:11], off

.LBB0_538:
	s_and_b32 s0, s80, 31
	s_xor_b64 s[62:63], s[12:13], -1
	s_lshl_b32 s64, s0, 8
	s_lshl_b32 s65, s0, 19
	s_ashr_i32 s16, s79, 5
	s_add_i32 s79, s79, s76
	s_cmpk_lt_i32 s79, 0x180
	s_cselect_b64 s[18:19], -1, 0
	s_cmpk_gt_i32 s79, 0x17f
	s_cselect_b64 s[14:15], -1, 0
	s_cmp_eq_u32 s16, 11
	s_cselect_b64 s[12:13], -1, 0
	s_cmp_lg_u32 s16, 11
	s_mov_b64 s[8:9], -1
	s_cbranch_scc0 .LBB0_1136
	s_lshl_b32 s2, s51, 8
	v_add_u32_e32 v0, s2, v221
	v_ashrrev_i32_e32 v1, 31, v0
	v_lshlrev_b64 v[2:3], 6, v[0:1]
	v_add_u32_e32 v0, 64, v0
	v_ashrrev_i32_e32 v1, 31, v0
	v_lshlrev_b64 v[0:1], 6, v[0:1]
	v_lshl_add_u64 v[2:3], s[4:5], 0, v[2:3]
	v_lshl_add_u64 v[0:1], s[4:5], 0, v[0:1]
	global_load_dwordx4 v[160:163], v[2:3], off
	global_load_dwordx4 v[156:159], v[2:3], off offset:16
	global_load_dwordx4 v[152:155], v[2:3], off offset:32
	global_load_dwordx4 v[82:85], v[2:3], off offset:48
	global_load_dwordx4 v[12:15], v[0:1], off
	global_load_dwordx4 v[8:11], v[0:1], off offset:16
	global_load_dwordx4 v[4:7], v[0:1], off offset:32
	s_nop 0
	global_load_dwordx4 v[0:3], v[0:1], off offset:48
	s_lshl_b32 s3, s16, 1
	v_readlane_b32 s0, v254, 23
	s_or_b32 s58, s3, s0
	s_lshl_b32 s0, s58, 7
	s_or_b32 s8, s0, s78
	s_cmp_lt_i32 s58, 23
	s_cselect_b64 s[26:27], -1, 0
	s_cmp_gt_i32 s58, 22
	v_mov_b32_e32 v80, 0
	s_cbranch_scc1 .LBB0_541
	s_add_i32 s0, s51, -16
	s_lshr_b32 s0, s0, 2
	s_add_i32 s0, s0, 1
	s_cmp_gt_u32 s51, 15
	s_cselect_b32 s0, s0, 0
	s_add_i32 s0, s0, s81
	s_ashr_i32 s9, s8, 31
	s_mul_hi_i32 s17, s0, 0x2e00
	s_mulk_i32 s0, 0x2e00
	v_readlane_b32 s28, v255, 15
	s_add_u32 s0, s28, s0
	v_readlane_b32 s28, v255, 16
	s_addc_u32 s17, s28, s17
	s_lshl_b64 s[28:29], s[8:9], 2
	s_add_u32 s28, s0, s28
	s_addc_u32 s29, s17, s29
	v_lshl_add_u64 v[16:17], v[188:189], 2, s[28:29]
	global_load_dword v80, v[16:17], off

.LBB0_1139:
	v_lshl_add_u32 v16, s51, 8, v222
	v_ashrrev_i32_e32 v17, 31, v16
	v_lshlrev_b64 v[0:1], 6, v[16:17]
	v_add_u32_e32 v16, 64, v16
	v_ashrrev_i32_e32 v17, 31, v16
	v_lshlrev_b64 v[16:17], 6, v[16:17]
	v_lshl_add_u64 v[12:13], s[4:5], 0, v[0:1]
	v_lshl_add_u64 v[28:29], s[4:5], 0, v[16:17]
	global_load_dwordx4 v[0:3], v[12:13], off
	global_load_dwordx4 v[4:7], v[12:13], off offset:16
	global_load_dwordx4 v[8:11], v[12:13], off offset:32
	s_nop 0
	global_load_dwordx4 v[12:15], v[12:13], off offset:48
	s_nop 0
	global_load_dwordx4 v[16:19], v[28:29], off
	global_load_dwordx4 v[20:23], v[28:29], off offset:16
	global_load_dwordx4 v[24:27], v[28:29], off offset:32
	s_nop 0
	global_load_dwordx4 v[28:31], v[28:29], off offset:48
	s_mov_b32 s0, 0x3a800000
	s_waitcnt vmcnt(0) lgkmcnt(0)
	v_mov_b32_e32 v32, v0
	v_mov_b32_e32 v33, v16
	v_mov_b32_e32 v16, v1
	v_pk_add_f32 v[0:1], v[32:33], v[16:17]
	v_mov_b32_e32 v16, v2
	v_mov_b32_e32 v17, v18
	v_mov_b32_e32 v18, v3
	v_pk_add_f32 v[2:3], v[16:17], v[18:19]
	s_nop 0
	v_pk_add_f32 v[0:1], v[0:1], v[2:3]
	v_mov_b32_e32 v2, v4
	v_mov_b32_e32 v3, v20
	v_mov_b32_e32 v20, v5
	v_mov_b32_e32 v4, v6
	v_mov_b32_e32 v5, v22
	v_mov_b32_e32 v22, v7
	v_pk_add_f32 v[2:3], v[2:3], v[20:21]
	v_pk_add_f32 v[4:5], v[4:5], v[22:23]
	v_pk_add_f32 v[0:1], v[0:1], 0 op_sel_hi:[1,0]
	v_pk_add_f32 v[2:3], v[2:3], v[4:5]
	v_mov_b32_e32 v4, v10
	v_pk_add_f32 v[0:1], v[0:1], v[2:3]
	v_mov_b32_e32 v2, v8
	v_mov_b32_e32 v3, v24
	v_mov_b32_e32 v24, v9
	v_mov_b32_e32 v5, v26
	v_mov_b32_e32 v26, v11
	v_pk_add_f32 v[2:3], v[2:3], v[24:25]
	v_pk_add_f32 v[4:5], v[4:5], v[26:27]
	s_nop 0
	v_pk_add_f32 v[2:3], v[2:3], v[4:5]
	v_mov_b32_e32 v4, v14
	v_pk_add_f32 v[0:1], v[0:1], v[2:3]
	v_mov_b32_e32 v2, v12
	v_mov_b32_e32 v3, v28
	v_mov_b32_e32 v28, v13
	v_mov_b32_e32 v5, v30
	v_mov_b32_e32 v30, v15
	v_pk_add_f32 v[2:3], v[2:3], v[28:29]
	v_pk_add_f32 v[4:5], v[4:5], v[30:31]
	s_nop 0
	v_pk_add_f32 v[2:3], v[2:3], v[4:5]
	s_nop 0
	v_pk_add_f32 v[0:1], v[0:1], v[2:3]
	s_nop 0
	v_pk_fma_f32 v[0:1], v[0:1], s[0:1], v[180:181] op_sel_hi:[1,0,0]
	s_mov_b32 s0, 0x45800000
	v_mul_f32_e32 v2, 0x4b800000, v0
	v_cmp_gt_f32_e64 s[42:43], s66, v0
	v_cmp_gt_f32_e32 vcc, s66, v1
	s_nop 0
	v_cndmask_b32_e64 v0, v0, v2, s[42:43]
	v_mul_f32_e32 v2, 0x4b800000, v1
	v_cndmask_b32_e32 v1, v1, v2, vcc
	v_rsq_f32_e32 v0, v0
	v_rsq_f32_e32 v1, v1
	s_nop 0
	v_pk_mul_f32 v[2:3], v[0:1], s[0:1] op_sel_hi:[1,0]
	s_add_i32 s0, s51, -16
	s_lshr_b32 s0, s0, 2
	s_add_i32 s0, s0, 1
	s_cmp_gt_u32 s51, 15
	s_cselect_b32 s0, s0, 0
	s_add_i32 s0, s0, s81
	s_mul_hi_i32 s3, s0, 0x2e00
	s_mulk_i32 s0, 0x2e00
	s_add_u32 s2, s88, s0
	s_addc_u32 s3, s89, s3
	v_cndmask_b32_e64 v85, v0, v2, s[42:43]
	v_cndmask_b32_e32 v84, v1, v3, vcc
	v_lshl_add_u64 v[0:1], v[188:189], 2, s[2:3]
	v_add_co_u32_e32 v0, vcc, 0x102000, v0
	s_nop 1
	v_addc_co_u32_e32 v1, vcc, 0, v1, vcc
	global_load_dword v86, v[0:1], off offset:3072

.LBB0_1360:
	global_load_dwordx4 v[0:3], v[78:79], off
	s_waitcnt vmcnt(0) lgkmcnt(0)
	v_mov_b32_e32 v4, v1
	v_mov_b32_e32 v5, v2
	v_mov_b32_e32 v1, v3
	v_pk_add_f32 v[0:1], v[4:5], v[0:1]
	s_nop 0
	v_add_f32_e32 v0, v0, v1
	v_fmamk_f32 v0, v0, 0x3b800000, v180
	v_mul_f32_e32 v1, 0x4b800000, v0
	v_cmp_gt_f32_e32 vcc, s1, v0
	s_nop 1
	v_cndmask_b32_e32 v0, v0, v1, vcc
	v_rsq_f32_e32 v0, v0
	s_nop 0
	v_mul_f32_e32 v1, 0x45800000, v0
	v_cndmask_b32_e32 v106, v0, v1, vcc

.LBB0_1504:
	v_mad_u64_u32 v[4:5], s[8:9], s8, 5, v[60:61]
	v_mov_b64_e32 v[6:7], s[6:7]
	v_mad_i64_i32 v[4:5], s[8:9], v4, s1, v[6:7]
	v_lshl_add_u64 v[4:5], v[66:67], 2, v[4:5]
	global_atomic_add_f32 v[4:5], v2, off
	global_atomic_add_f32 v[4:5], v3, off offset:4
	global_atomic_add_f32 v[4:5], v0, off offset:8
	global_atomic_add_f32 v[4:5], v1, off offset:12
